# speedup vs baseline: 1.1077x; 1.1077x over previous
; #define PG8_STAGE(bufoff, gbase, voff) do { _Pragma("unroll") for (int _i = 0; _i < 2; ++_i) \
;         __builtin_amdgcn_global_load_lds((const unsigned*)((const char*)(gbase) + (voff)[_i]), (PG8_LAS unsigned*)(lds + (bufoff) + ldsw + _i * 8192), 16, 0, 0); } while (0)
; #define PG8_LDA(dst, b, h) do { _Pragma("unroll") for (int m = 0; m < 4; ++m) _Pragma("unroll") for (int k = 0; k < 2; ++k) dst[m][k] = *(const PG8_LAS bf16x8*)(lds + PG8_SA(b, h) + aoff + m * 2048 + k * 1024); } while (0)
; #define PG8_LDB(dst, b, h) do { _Pragma("unroll") for (int n = 0; n < 2; ++n) _Pragma("unroll") for (int k = 0; k < 2; ++k) dst[n][k] = *(const PG8_LAS bf16x8*)(lds + PG8_SB(b, h) + boff + n * 2048 + k * 1024); } while (0)
; #define PG8_WAIT_V(n) asm volatile("s_waitcnt vmcnt(" #n ")" ::: "memory")
; #define PG8_WAIT_L(n) asm volatile("s_waitcnt lgkmcnt(" #n ")" ::: "memory")
; #define PG8_BAR __builtin_amdgcn_s_barrier()
; #define PG8_SCHED __builtin_amdgcn_sched_barrier(0)
; template <class Epi, class Sched, bool ALIGN_EPI = false, bool SP2 = false>
; __device__ __forceinline__ void gemm_phase(PG8_LAS unsigned char* lds, const Gemm g, const Sched& S, const Epi& E) {
;     ...
;         const char* nA = has_next ? (const char*)g.A + (size_t)nxt.pm * tstep : cA; const char* nB = has_next ? (const char*)g.Bt + (size_t)nxt.pn * tstep : cB;
;         for (int t = 0; t < nt; t += 2) {
;             if constexpr (Epi::MID_HOOK) { if (t == Epi::MID_T) E.mid(acc, cur, wr, wc, fr, fq); }
;             const bool last = (t == nt - 2);
;             const char* a1 = cA + (size_t)(t + 1) * kstep;
;             const char* a2 = last ? nA : cA + (size_t)(t + 2) * kstep; const char* b2 = last ? nB : cB + (size_t)(t + 2) * kstep;
;             const char* a3 = a2 + kstep; const char* b3 = b2 + kstep;
;             if (last && has_next) S.a_ready(nxt);
;             if constexpr (SP2) {
;             PG8_LDB(B0, 0, 0); PG8_LDB(B1, 0, 1); PG8_SCHED; PG8_LDA(At, 0, 0); PG8_STAGE(PG8_SA(1, 1), a1 + hstep, voffA);
;             PG8_WAIT_V(8); PG8_WAIT_L(0); PG8_BAR; PG8_MMA(0, 0, At, B0); PG8_MMA(0, 1, At, B1); PG8_BAR; PG8_SCHED;
;             PG8_LDA(At, 0, 1); PG8_STAGE(PG8_SB(0, 0), b2, voffB); PG8_STAGE(PG8_SB(0, 1), b2 + hstep, voffB); PG8_STAGE(PG8_SA(0, 0), a2, voffA);
;             PG8_WAIT_V(8); PG8_WAIT_L(0); PG8_BAR; PG8_MMA(1, 0, At, B0); PG8_MMA(1, 1, At, B1); PG8_BAR; PG8_SCHED;
.LBB0_128:
	s_ashr_i32 s67, s66, 31
	s_lshl_b64 s[14:15], s[66:67], 20
	s_add_u32 s70, s37, s14
	s_addc_u32 s71, s38, s15
	s_and_b64 s[14:15], s[68:69], exec
	s_cselect_b32 s2, s71, s1
	s_cselect_b32 s11, s70, s0
	s_ashr_i32 s65, s64, 31
	s_lshl_b64 s[14:15], s[64:65], 20
	s_add_u32 s72, s31, s14
	s_addc_u32 s73, s36, s15
	s_and_b64 s[14:15], s[68:69], exec
	s_cselect_b32 s18, s73, s13
	s_cselect_b32 s19, s72, s12
	s_add_u32 s0, s0, 0x80080
	s_addc_u32 s1, s1, 0
	s_add_u32 s34, s12, 0x100
	s_addc_u32 s41, s13, 0
	s_mov_b32 s42, -2
	v_lshl_add_u64 v[194:195], s[0:1], 0, v[144:145]
	s_add_i32 m0, s74, 0xc000
	global_load_lds_dwordx4 v[194:195], off
	s_add_i32 m0, s74, 0xe000
	v_lshl_add_u64 v[194:195], s[0:1], 0, v[146:147]
	global_load_lds_dwordx4 v[194:195], off
	s_add_u32 s12, s0, 0xfff80080
	s_addc_u32 s13, s1, -1
	s_add_i32 s43, 0, 0x10000
	s_cmp_eq_u32 s42, 28
	s_cselect_b32 s15, s2, s13
	s_cselect_b32 s14, s11, s12
	s_cselect_b32 s13, s18, s41
	s_cselect_b32 s12, s19, s34
	s_add_i32 s65, 0, 0x14000
	s_waitcnt vmcnt(8)
	s_waitcnt lgkmcnt(0)
	s_barrier
	s_setprio 1
	s_waitcnt lgkmcnt(0)
	v_mfma_f32_16x16x32_bf16 v[124:127], v[128:131], v[172:175], 0
	v_mfma_f32_16x16x32_bf16 v[120:123], v[148:151], v[172:175], 0
	v_mfma_f32_16x16x32_bf16 v[108:111], v[128:131], v[184:187], 0
	v_mfma_f32_16x16x32_bf16 v[104:107], v[148:151], v[184:187], 0
	v_mfma_f32_16x16x32_bf16 v[92:95], v[128:131], v[206:209], 0
	v_mfma_f32_16x16x32_bf16 v[88:91], v[148:151], v[206:209], 0
	v_mfma_f32_16x16x32_bf16 v[76:79], v[128:131], v[214:217], 0
	v_mfma_f32_16x16x32_bf16 v[72:75], v[148:151], v[214:217], 0
	v_mfma_f32_16x16x32_bf16 v[124:127], v[132:135], v[180:183], v[124:127]
	v_mfma_f32_16x16x32_bf16 v[120:123], v[152:155], v[180:183], v[120:123]
	v_mfma_f32_16x16x32_bf16 v[108:111], v[132:135], v[188:191], v[108:111]
	v_mfma_f32_16x16x32_bf16 v[104:107], v[152:155], v[188:191], v[104:107]
	v_mfma_f32_16x16x32_bf16 v[92:95], v[132:135], v[210:213], v[92:95]
	v_mfma_f32_16x16x32_bf16 v[88:91], v[152:155], v[210:213], v[88:91]
	v_mfma_f32_16x16x32_bf16 v[76:79], v[132:135], v[218:221], v[76:79]
	v_mfma_f32_16x16x32_bf16 v[72:75], v[152:155], v[218:221], v[72:75]
	s_setprio 0
	s_setprio 1
	v_mfma_f32_16x16x32_bf16 v[116:119], v[156:159], v[172:175], 0
	v_mfma_f32_16x16x32_bf16 v[112:115], v[164:167], v[172:175], 0
	v_mfma_f32_16x16x32_bf16 v[100:103], v[156:159], v[184:187], 0
	v_mfma_f32_16x16x32_bf16 v[96:99], v[164:167], v[184:187], 0
	v_mfma_f32_16x16x32_bf16 v[84:87], v[156:159], v[206:209], 0
	v_mfma_f32_16x16x32_bf16 v[80:83], v[164:167], v[206:209], 0
	v_mfma_f32_16x16x32_bf16 v[68:71], v[156:159], v[214:217], 0
	v_mfma_f32_16x16x32_bf16 v[64:67], v[164:167], v[214:217], 0
	v_mfma_f32_16x16x32_bf16 v[116:119], v[160:163], v[180:183], v[116:119]
	v_mfma_f32_16x16x32_bf16 v[112:115], v[168:171], v[180:183], v[112:115]
	v_mfma_f32_16x16x32_bf16 v[100:103], v[160:163], v[188:191], v[100:103]
	v_mfma_f32_16x16x32_bf16 v[96:99], v[168:171], v[188:191], v[96:99]
	v_mfma_f32_16x16x32_bf16 v[84:87], v[160:163], v[210:213], v[84:87]
	v_mfma_f32_16x16x32_bf16 v[80:83], v[168:171], v[210:213], v[80:83]
	v_mfma_f32_16x16x32_bf16 v[68:71], v[160:163], v[218:221], v[68:71]
	v_mfma_f32_16x16x32_bf16 v[64:67], v[168:171], v[218:221], v[64:67]
	s_setprio 0
	s_barrier
	s_add_i32 s43, s43, s39
	v_lshl_add_u64 v[194:195], s[12:13], 0, v[138:139]
	s_mov_b32 m0, s43
	s_nop 0
	global_load_lds_dwordx4 v[194:195], off
	s_add_i32 m0, s43, 0x2000
	s_add_u32 s86, s12, 0x80000
	v_lshl_add_u64 v[196:197], s[12:13], 0, v[142:143]
	s_addc_u32 s87, s13, 0
	s_add_i32 s43, s65, s39
	global_load_lds_dwordx4 v[196:197], off
	v_lshl_add_u64 v[202:203], s[86:87], 0, v[138:139]
	s_mov_b32 m0, s43
	v_lshl_add_u64 v[204:205], s[14:15], 0, v[140:141]
	global_load_lds_dwordx4 v[202:203], off
	s_add_i32 m0, s43, 0x2000
	v_lshl_add_u64 v[202:203], s[86:87], 0, v[142:143]
	global_load_lds_dwordx4 v[202:203], off
	s_mov_b32 m0, s74
	v_lshl_add_u64 v[202:203], s[14:15], 0, v[136:137]
	global_load_lds_dwordx4 v[202:203], off
	s_mov_b32 m0, s75
	s_nop 0
	global_load_lds_dwordx4 v[204:205], off
	ds_read_b128 v[172:175], v179 offset:16384
	ds_read_b128 v[180:183], v179 offset:17408
	ds_read_b128 v[184:187], v179 offset:18432
	ds_read_b128 v[188:191], v179 offset:19456
	ds_read_b128 v[206:209], v179 offset:20480
	ds_read_b128 v[210:213], v179 offset:21504
	ds_read_b128 v[214:217], v179 offset:22528
	ds_read_b128 v[218:221], v179 offset:23552
	s_waitcnt vmcnt(8)
	s_waitcnt lgkmcnt(0)
	s_barrier
	s_setprio 1
	s_waitcnt lgkmcnt(0)
	v_mfma_f32_16x16x32_bf16 v[60:63], v[128:131], v[172:175], 0
	v_mfma_f32_16x16x32_bf16 v[56:59], v[148:151], v[172:175], 0
	v_mfma_f32_16x16x32_bf16 v[44:47], v[128:131], v[184:187], 0
	v_mfma_f32_16x16x32_bf16 v[40:43], v[148:151], v[184:187], 0
	v_mfma_f32_16x16x32_bf16 v[28:31], v[128:131], v[206:209], 0
	v_mfma_f32_16x16x32_bf16 v[24:27], v[148:151], v[206:209], 0
	v_mfma_f32_16x16x32_bf16 v[12:15], v[128:131], v[214:217], 0
	v_mfma_f32_16x16x32_bf16 v[8:11], v[148:151], v[214:217], 0
	v_mfma_f32_16x16x32_bf16 v[60:63], v[132:135], v[180:183], v[60:63]
	v_mfma_f32_16x16x32_bf16 v[56:59], v[152:155], v[180:183], v[56:59]
	v_mfma_f32_16x16x32_bf16 v[44:47], v[132:135], v[188:191], v[44:47]
	v_mfma_f32_16x16x32_bf16 v[40:43], v[152:155], v[188:191], v[40:43]
	v_mfma_f32_16x16x32_bf16 v[28:31], v[132:135], v[210:213], v[28:31]
	v_mfma_f32_16x16x32_bf16 v[24:27], v[152:155], v[210:213], v[24:27]
	v_mfma_f32_16x16x32_bf16 v[12:15], v[132:135], v[218:221], v[12:15]
	v_mfma_f32_16x16x32_bf16 v[8:11], v[152:155], v[218:221], v[8:11]
	s_setprio 0
	s_setprio 1
	v_mfma_f32_16x16x32_bf16 v[52:55], v[156:159], v[172:175], 0
	v_mfma_f32_16x16x32_bf16 v[48:51], v[164:167], v[172:175], 0
	v_mfma_f32_16x16x32_bf16 v[36:39], v[156:159], v[184:187], 0
	v_mfma_f32_16x16x32_bf16 v[32:35], v[164:167], v[184:187], 0
	v_mfma_f32_16x16x32_bf16 v[20:23], v[156:159], v[206:209], 0
	v_mfma_f32_16x16x32_bf16 v[16:19], v[164:167], v[206:209], 0
	v_mfma_f32_16x16x32_bf16 v[4:7], v[156:159], v[214:217], 0
	v_mfma_f32_16x16x32_bf16 v[0:3], v[164:167], v[214:217], 0
	v_mfma_f32_16x16x32_bf16 v[52:55], v[160:163], v[180:183], v[52:55]
	v_mfma_f32_16x16x32_bf16 v[48:51], v[168:171], v[180:183], v[48:51]
	v_mfma_f32_16x16x32_bf16 v[36:39], v[160:163], v[188:191], v[36:39]
	v_mfma_f32_16x16x32_bf16 v[32:35], v[168:171], v[188:191], v[32:35]
	v_mfma_f32_16x16x32_bf16 v[20:23], v[160:163], v[210:213], v[20:23]
	v_mfma_f32_16x16x32_bf16 v[16:19], v[168:171], v[210:213], v[16:19]
	v_mfma_f32_16x16x32_bf16 v[4:7], v[160:163], v[218:221], v[4:7]
	v_mfma_f32_16x16x32_bf16 v[0:3], v[168:171], v[218:221], v[0:3]
	s_setprio 0
	s_barrier
; #define PG8_STAGE(bufoff, gbase, voff) do { _Pragma("unroll") for (int _i = 0; _i < 2; ++_i) \
;         __builtin_amdgcn_global_load_lds((const unsigned*)((const char*)(gbase) + (voff)[_i]), (PG8_LAS unsigned*)(lds + (bufoff) + ldsw + _i * 8192), 16, 0, 0); } while (0)
; #define PG8_LDA(dst, b, h) do { _Pragma("unroll") for (int m = 0; m < 4; ++m) _Pragma("unroll") for (int k = 0; k < 2; ++k) dst[m][k] = *(const PG8_LAS bf16x8*)(lds + PG8_SA(b, h) + aoff + m * 2048 + k * 1024); } while (0)
; #define PG8_LDB(dst, b, h) do { _Pragma("unroll") for (int n = 0; n < 2; ++n) _Pragma("unroll") for (int k = 0; k < 2; ++k) dst[n][k] = *(const PG8_LAS bf16x8*)(lds + PG8_SB(b, h) + boff + n * 2048 + k * 1024); } while (0)
; #define PG8_MMA(ai, bj, At, Bt) do { __builtin_amdgcn_s_setprio(1); _Pragma("unroll") for (int m = 0; m < 4; ++m) _Pragma("unroll") for (int n = 0; n < 2; ++n) _Pragma("unroll") for (int k = 0; k < 2; ++k) \
;         acc[ai][bj][m][n] = __builtin_amdgcn_mfma_f32_16x16x32_bf16(Bt[n][k], At[m][k], acc[ai][bj][m][n], 0, 0, 0); __builtin_amdgcn_s_setprio(0); } while (0)
; #define PG8_WAIT_V(n) asm volatile("s_waitcnt vmcnt(" #n ")" ::: "memory")
; #define PG8_WAIT_L(n) asm volatile("s_waitcnt lgkmcnt(" #n ")" ::: "memory")
; #define PG8_BAR __builtin_amdgcn_s_barrier()
; #define PG8_SCHED __builtin_amdgcn_sched_barrier(0)
; template <class Epi, class Sched, bool ALIGN_EPI = false, bool SP2 = false>
; __device__ __forceinline__ void gemm_phase(PG8_LAS unsigned char* lds, const Gemm g, const Sched& S, const Epi& E) {
;     ...
;             PG8_LDB(B0, 1, 0); PG8_LDB(B1, 1, 1); PG8_SCHED; PG8_LDA(At, 1, 0); PG8_STAGE(PG8_SA(0, 1), a2 + hstep, voffA);
;             PG8_WAIT_V(8); PG8_WAIT_L(0); PG8_BAR; PG8_MMA(0, 0, At, B0); PG8_MMA(0, 1, At, B1); PG8_BAR; PG8_SCHED;
;             PG8_LDA(At, 1, 1); PG8_STAGE(PG8_SB(1, 0), b3, voffB); PG8_STAGE(PG8_SB(1, 1), b3 + hstep, voffB); PG8_STAGE(PG8_SA(1, 0), a3, voffA);
;             PG8_WAIT_V(8); PG8_WAIT_L(0); PG8_BAR; PG8_MMA(1, 0, At, B0); PG8_MMA(1, 1, At, B1); PG8_BAR; PG8_SCHED;
	s_add_i32 s43, 0, 0x18000
	s_add_i32 s65, 0, 0x1c000
	s_add_u32 s14, s14, 0x80000
	s_addc_u32 s15, s15, 0
	s_mov_b32 m0, s76
	v_lshl_add_u64 v[232:233], s[14:15], 0, v[136:137]
	global_load_lds_dwordx4 v[232:233], off
	s_mov_b32 m0, s77
	v_lshl_add_u64 v[232:233], s[14:15], 0, v[140:141]
	global_load_lds_dwordx4 v[232:233], off
	v_add_u32_e32 v152, 0x18000, v178
	v_add_u32_e32 v168, 0x1c000, v178
	ds_read_b128 v[128:131], v152
	ds_read_b128 v[132:135], v152 offset:1024
	ds_read_b128 v[148:151], v152 offset:2048
	ds_read_b128 v[152:155], v152 offset:3072
	ds_read_b128 v[156:159], v168
	ds_read_b128 v[160:163], v168 offset:1024
	ds_read_b128 v[164:167], v168 offset:2048
	ds_read_b128 v[168:171], v168 offset:3072
	ds_read_b128 v[172:175], v179 offset:32768
	ds_read_b128 v[180:183], v179 offset:33792
	ds_read_b128 v[184:187], v179 offset:34816
	ds_read_b128 v[188:191], v179 offset:35840
	ds_read_b128 v[206:209], v179 offset:36864
	ds_read_b128 v[210:213], v179 offset:37888
	ds_read_b128 v[214:217], v179 offset:38912
	ds_read_b128 v[218:221], v179 offset:39936
	s_waitcnt vmcnt(8)
	s_waitcnt lgkmcnt(0)
	s_barrier
	s_setprio 1
	s_waitcnt lgkmcnt(0)
	v_mfma_f32_16x16x32_bf16 v[124:127], v[128:131], v[172:175], v[124:127]
	v_mfma_f32_16x16x32_bf16 v[120:123], v[148:151], v[172:175], v[120:123]
	v_mfma_f32_16x16x32_bf16 v[108:111], v[128:131], v[184:187], v[108:111]
	v_mfma_f32_16x16x32_bf16 v[104:107], v[148:151], v[184:187], v[104:107]
	v_mfma_f32_16x16x32_bf16 v[92:95], v[128:131], v[206:209], v[92:95]
	v_mfma_f32_16x16x32_bf16 v[88:91], v[148:151], v[206:209], v[88:91]
	v_mfma_f32_16x16x32_bf16 v[76:79], v[128:131], v[214:217], v[76:79]
	v_mfma_f32_16x16x32_bf16 v[72:75], v[148:151], v[214:217], v[72:75]
	v_mfma_f32_16x16x32_bf16 v[124:127], v[132:135], v[180:183], v[124:127]
	v_mfma_f32_16x16x32_bf16 v[120:123], v[152:155], v[180:183], v[120:123]
	v_mfma_f32_16x16x32_bf16 v[108:111], v[132:135], v[188:191], v[108:111]
	v_mfma_f32_16x16x32_bf16 v[104:107], v[152:155], v[188:191], v[104:107]
	v_mfma_f32_16x16x32_bf16 v[92:95], v[132:135], v[210:213], v[92:95]
	v_mfma_f32_16x16x32_bf16 v[88:91], v[152:155], v[210:213], v[88:91]
	v_mfma_f32_16x16x32_bf16 v[76:79], v[132:135], v[218:221], v[76:79]
	v_mfma_f32_16x16x32_bf16 v[72:75], v[152:155], v[218:221], v[72:75]
	s_setprio 0
	s_setprio 1
	v_mfma_f32_16x16x32_bf16 v[116:119], v[156:159], v[172:175], v[116:119]
	v_mfma_f32_16x16x32_bf16 v[112:115], v[164:167], v[172:175], v[112:115]
	v_mfma_f32_16x16x32_bf16 v[100:103], v[156:159], v[184:187], v[100:103]
	v_mfma_f32_16x16x32_bf16 v[96:99], v[164:167], v[184:187], v[96:99]
	v_mfma_f32_16x16x32_bf16 v[84:87], v[156:159], v[206:209], v[84:87]
	v_mfma_f32_16x16x32_bf16 v[80:83], v[164:167], v[206:209], v[80:83]
	v_mfma_f32_16x16x32_bf16 v[68:71], v[156:159], v[214:217], v[68:71]
	v_mfma_f32_16x16x32_bf16 v[64:67], v[164:167], v[214:217], v[64:67]
	v_mfma_f32_16x16x32_bf16 v[116:119], v[160:163], v[180:183], v[116:119]
	v_mfma_f32_16x16x32_bf16 v[112:115], v[168:171], v[180:183], v[112:115]
	v_mfma_f32_16x16x32_bf16 v[100:103], v[160:163], v[188:191], v[100:103]
	v_mfma_f32_16x16x32_bf16 v[96:99], v[168:171], v[188:191], v[96:99]
	v_mfma_f32_16x16x32_bf16 v[84:87], v[160:163], v[210:213], v[84:87]
	v_mfma_f32_16x16x32_bf16 v[80:83], v[168:171], v[210:213], v[80:83]
	v_mfma_f32_16x16x32_bf16 v[68:71], v[160:163], v[218:221], v[68:71]
	v_mfma_f32_16x16x32_bf16 v[64:67], v[168:171], v[218:221], v[64:67]
	s_setprio 0
	s_barrier
	s_add_i32 s14, s43, s39
	v_lshl_add_u64 v[194:195], v[194:195], 0, s[16:17]
	s_mov_b32 m0, s14
	s_nop 0
	global_load_lds_dwordx4 v[194:195], off
	s_add_i32 m0, s14, 0x2000
	s_add_u32 s12, s12, 0x80080
	v_lshl_add_u64 v[194:195], v[196:197], 0, s[16:17]
	s_addc_u32 s13, s13, 0
	s_add_i32 s14, s65, s39
	global_load_lds_dwordx4 v[194:195], off
	s_mov_b32 m0, s14
	v_lshl_add_u64 v[194:195], s[12:13], 0, v[138:139]
	global_load_lds_dwordx4 v[194:195], off
	s_add_i32 m0, s14, 0x2000
	v_lshl_add_u64 v[194:195], s[12:13], 0, v[142:143]
	global_load_lds_dwordx4 v[194:195], off
	s_mov_b32 m0, s80
	v_lshl_add_u64 v[194:195], v[202:203], 0, s[16:17]
	global_load_lds_dwordx4 v[194:195], off
	s_mov_b32 m0, s81
	v_lshl_add_u64 v[194:195], v[204:205], 0, s[16:17]
	global_load_lds_dwordx4 v[194:195], off
	ds_read_b128 v[172:175], v179 offset:49152
	ds_read_b128 v[180:183], v179 offset:50176
	ds_read_b128 v[184:187], v179 offset:51200
	ds_read_b128 v[188:191], v179 offset:52224
	ds_read_b128 v[206:209], v179 offset:53248
	ds_read_b128 v[210:213], v179 offset:54272
	ds_read_b128 v[214:217], v179 offset:55296
	ds_read_b128 v[218:221], v179 offset:56320
	s_waitcnt vmcnt(8)
	s_waitcnt lgkmcnt(0)
	s_barrier
; #define PG8_STAGE(bufoff, gbase, voff) do { _Pragma("unroll") for (int _i = 0; _i < 2; ++_i) \
;         __builtin_amdgcn_global_load_lds((const unsigned*)((const char*)(gbase) + (voff)[_i]), (PG8_LAS unsigned*)(lds + (bufoff) + ldsw + _i * 8192), 16, 0, 0); } while (0)
; #define PG8_LDA(dst, b, h) do { _Pragma("unroll") for (int m = 0; m < 4; ++m) _Pragma("unroll") for (int k = 0; k < 2; ++k) dst[m][k] = *(const PG8_LAS bf16x8*)(lds + PG8_SA(b, h) + aoff + m * 2048 + k * 1024); } while (0)
; #define PG8_LDB(dst, b, h) do { _Pragma("unroll") for (int n = 0; n < 2; ++n) _Pragma("unroll") for (int k = 0; k < 2; ++k) dst[n][k] = *(const PG8_LAS bf16x8*)(lds + PG8_SB(b, h) + boff + n * 2048 + k * 1024); } while (0)
; #define PG8_MMA(ai, bj, At, Bt) do { __builtin_amdgcn_s_setprio(1); _Pragma("unroll") for (int m = 0; m < 4; ++m) _Pragma("unroll") for (int n = 0; n < 2; ++n) _Pragma("unroll") for (int k = 0; k < 2; ++k) \
;         acc[ai][bj][m][n] = __builtin_amdgcn_mfma_f32_16x16x32_bf16(Bt[n][k], At[m][k], acc[ai][bj][m][n], 0, 0, 0); __builtin_amdgcn_s_setprio(0); } while (0)
; #define PG8_WAIT_V(n) asm volatile("s_waitcnt vmcnt(" #n ")" ::: "memory")
; template <class Epi, class Sched, bool ALIGN_EPI = false, bool SP2 = false>
; __device__ __forceinline__ void gemm_phase(PG8_LAS unsigned char* lds, const Gemm g, const Sched& S, const Epi& E) {
;     ...
;             PG8_LDB(B0, 0, 0); PG8_LDB(B1, 0, 1); PG8_SCHED; PG8_LDA(At, 0, 0); PG8_STAGE(PG8_SA(1, 1), a1 + hstep, voffA);
;             PG8_WAIT_V(8); PG8_WAIT_L(0); PG8_BAR; PG8_MMA(0, 0, At, B0); PG8_MMA(0, 1, At, B1); PG8_BAR; PG8_SCHED;
;             PG8_LDA(At, 0, 1); PG8_STAGE(PG8_SB(0, 0), b2, voffB); PG8_STAGE(PG8_SB(0, 1), b2 + hstep, voffB); PG8_STAGE(PG8_SA(0, 0), a2, voffA);
;             PG8_WAIT_V(8); PG8_WAIT_L(0); PG8_BAR; PG8_MMA(1, 0, At, B0); PG8_MMA(1, 1, At, B1); PG8_BAR; PG8_SCHED;
;             PG8_LDB(B0, 1, 0); PG8_LDB(B1, 1, 1); PG8_SCHED; PG8_LDA(At, 1, 0); PG8_STAGE(PG8_SA(0, 1), a2 + hstep, voffA);
;             PG8_WAIT_V(8); PG8_WAIT_L(0); PG8_BAR; PG8_MMA(0, 0, At, B0); PG8_MMA(0, 1, At, B1); PG8_BAR; PG8_SCHED;
;             PG8_LDA(At, 1, 1); PG8_STAGE(PG8_SB(1, 0), b3, voffB); PG8_STAGE(PG8_SB(1, 1), b3 + hstep, voffB); PG8_STAGE(PG8_SA(1, 0), a3, voffA);
;             PG8_WAIT_V(8); PG8_WAIT_L(0); PG8_BAR; PG8_MMA(1, 0, At, B0); PG8_MMA(1, 1, At, B1); PG8_BAR; PG8_SCHED;
	s_setprio 1
	s_waitcnt lgkmcnt(0)
	v_mfma_f32_16x16x32_bf16 v[60:63], v[128:131], v[172:175], v[60:63]
	v_mfma_f32_16x16x32_bf16 v[56:59], v[148:151], v[172:175], v[56:59]
	v_mfma_f32_16x16x32_bf16 v[44:47], v[128:131], v[184:187], v[44:47]
	v_mfma_f32_16x16x32_bf16 v[40:43], v[148:151], v[184:187], v[40:43]
	v_mfma_f32_16x16x32_bf16 v[28:31], v[128:131], v[206:209], v[28:31]
	v_mfma_f32_16x16x32_bf16 v[24:27], v[148:151], v[206:209], v[24:27]
	v_mfma_f32_16x16x32_bf16 v[12:15], v[128:131], v[214:217], v[12:15]
	v_mfma_f32_16x16x32_bf16 v[8:11], v[148:151], v[214:217], v[8:11]
	v_mfma_f32_16x16x32_bf16 v[60:63], v[132:135], v[180:183], v[60:63]
	v_mfma_f32_16x16x32_bf16 v[56:59], v[152:155], v[180:183], v[56:59]
	v_mfma_f32_16x16x32_bf16 v[44:47], v[132:135], v[188:191], v[44:47]
	v_mfma_f32_16x16x32_bf16 v[40:43], v[152:155], v[188:191], v[40:43]
	v_mfma_f32_16x16x32_bf16 v[28:31], v[132:135], v[210:213], v[28:31]
	v_mfma_f32_16x16x32_bf16 v[24:27], v[152:155], v[210:213], v[24:27]
	v_mfma_f32_16x16x32_bf16 v[12:15], v[132:135], v[218:221], v[12:15]
	v_mfma_f32_16x16x32_bf16 v[8:11], v[152:155], v[218:221], v[8:11]
	s_setprio 0
	s_setprio 1
	v_mfma_f32_16x16x32_bf16 v[52:55], v[156:159], v[172:175], v[52:55]
	v_mfma_f32_16x16x32_bf16 v[48:51], v[164:167], v[172:175], v[48:51]
	v_mfma_f32_16x16x32_bf16 v[36:39], v[156:159], v[184:187], v[36:39]
	v_mfma_f32_16x16x32_bf16 v[32:35], v[164:167], v[184:187], v[32:35]
	v_mfma_f32_16x16x32_bf16 v[20:23], v[156:159], v[206:209], v[20:23]
	v_mfma_f32_16x16x32_bf16 v[16:19], v[164:167], v[206:209], v[16:19]
	v_mfma_f32_16x16x32_bf16 v[4:7], v[156:159], v[214:217], v[4:7]
	v_mfma_f32_16x16x32_bf16 v[0:3], v[164:167], v[214:217], v[0:3]
	v_mfma_f32_16x16x32_bf16 v[52:55], v[160:163], v[180:183], v[52:55]
	v_mfma_f32_16x16x32_bf16 v[48:51], v[168:171], v[180:183], v[48:51]
	v_mfma_f32_16x16x32_bf16 v[36:39], v[160:163], v[188:191], v[36:39]
	v_mfma_f32_16x16x32_bf16 v[32:35], v[168:171], v[188:191], v[32:35]
	v_mfma_f32_16x16x32_bf16 v[20:23], v[160:163], v[210:213], v[20:23]
	v_mfma_f32_16x16x32_bf16 v[16:19], v[168:171], v[210:213], v[16:19]
	v_mfma_f32_16x16x32_bf16 v[4:7], v[160:163], v[218:221], v[4:7]
	v_mfma_f32_16x16x32_bf16 v[0:3], v[168:171], v[218:221], v[0:3]
	s_setprio 0
	s_barrier
	s_add_i32 s42, s42, 2
	s_add_u32 s0, s0, 0x100
	s_addc_u32 s1, s1, 0
	s_add_u32 s34, s34, 0x100
	s_addc_u32 s41, s41, 0
	s_cmp_gt_u32 s42, 29
	s_branch .LBB0_129
.LBB0_129:
	v_lshl_add_u64 v[194:195], s[0:1], 0, v[144:145]
	s_add_i32 m0, s74, 0xc000
	s_nop 0
	global_load_lds_dwordx4 v[194:195], off
	s_add_i32 m0, s74, 0xe000
	v_lshl_add_u64 v[194:195], s[0:1], 0, v[146:147]
	global_load_lds_dwordx4 v[194:195], off
	s_add_u32 s12, s0, 0xfff80080
	s_addc_u32 s13, s1, -1
	s_add_i32 s43, 0, 0x10000
	s_cmp_eq_u32 s42, 28
	s_cselect_b32 s15, s2, s13
	s_cselect_b32 s14, s11, s12
	s_cselect_b32 s13, s18, s41
	s_cselect_b32 s12, s19, s34
	s_add_i32 s65, 0, 0x14000
	v_add_u32_e32 v152, 0x10000, v178
	v_add_u32_e32 v168, 0x14000, v178
	ds_read_b128 v[128:131], v152
	ds_read_b128 v[132:135], v152 offset:1024
	ds_read_b128 v[148:151], v152 offset:2048
	ds_read_b128 v[152:155], v152 offset:3072
	ds_read_b128 v[156:159], v168
	ds_read_b128 v[160:163], v168 offset:1024
	ds_read_b128 v[164:167], v168 offset:2048
	ds_read_b128 v[168:171], v168 offset:3072
	ds_read_b128 v[172:175], v179
	ds_read_b128 v[180:183], v179 offset:1024
	ds_read_b128 v[184:187], v179 offset:2048
	ds_read_b128 v[188:191], v179 offset:3072
	ds_read_b128 v[206:209], v179 offset:4096
	ds_read_b128 v[210:213], v179 offset:5120
	ds_read_b128 v[214:217], v179 offset:6144
	ds_read_b128 v[218:221], v179 offset:7168
	s_waitcnt vmcnt(8)
	s_waitcnt lgkmcnt(0)
	s_barrier
	s_setprio 1
	s_waitcnt lgkmcnt(0)
	v_mfma_f32_16x16x32_bf16 v[124:127], v[128:131], v[172:175], v[124:127]
	v_mfma_f32_16x16x32_bf16 v[120:123], v[148:151], v[172:175], v[120:123]
	v_mfma_f32_16x16x32_bf16 v[108:111], v[128:131], v[184:187], v[108:111]
	v_mfma_f32_16x16x32_bf16 v[104:107], v[148:151], v[184:187], v[104:107]
	v_mfma_f32_16x16x32_bf16 v[92:95], v[128:131], v[206:209], v[92:95]
	v_mfma_f32_16x16x32_bf16 v[88:91], v[148:151], v[206:209], v[88:91]
	v_mfma_f32_16x16x32_bf16 v[76:79], v[128:131], v[214:217], v[76:79]
	v_mfma_f32_16x16x32_bf16 v[72:75], v[148:151], v[214:217], v[72:75]
	v_mfma_f32_16x16x32_bf16 v[124:127], v[132:135], v[180:183], v[124:127]
	v_mfma_f32_16x16x32_bf16 v[120:123], v[152:155], v[180:183], v[120:123]
	v_mfma_f32_16x16x32_bf16 v[108:111], v[132:135], v[188:191], v[108:111]
	v_mfma_f32_16x16x32_bf16 v[104:107], v[152:155], v[188:191], v[104:107]
	v_mfma_f32_16x16x32_bf16 v[92:95], v[132:135], v[210:213], v[92:95]
	v_mfma_f32_16x16x32_bf16 v[88:91], v[152:155], v[210:213], v[88:91]
	v_mfma_f32_16x16x32_bf16 v[76:79], v[132:135], v[218:221], v[76:79]
	v_mfma_f32_16x16x32_bf16 v[72:75], v[152:155], v[218:221], v[72:75]
	s_setprio 0
	s_setprio 1
	v_mfma_f32_16x16x32_bf16 v[116:119], v[156:159], v[172:175], v[116:119]
	v_mfma_f32_16x16x32_bf16 v[112:115], v[164:167], v[172:175], v[112:115]
	v_mfma_f32_16x16x32_bf16 v[100:103], v[156:159], v[184:187], v[100:103]
	v_mfma_f32_16x16x32_bf16 v[96:99], v[164:167], v[184:187], v[96:99]
	v_mfma_f32_16x16x32_bf16 v[84:87], v[156:159], v[206:209], v[84:87]
	v_mfma_f32_16x16x32_bf16 v[80:83], v[164:167], v[206:209], v[80:83]
	v_mfma_f32_16x16x32_bf16 v[68:71], v[156:159], v[214:217], v[68:71]
	v_mfma_f32_16x16x32_bf16 v[64:67], v[164:167], v[214:217], v[64:67]
	v_mfma_f32_16x16x32_bf16 v[116:119], v[160:163], v[180:183], v[116:119]
	v_mfma_f32_16x16x32_bf16 v[112:115], v[168:171], v[180:183], v[112:115]
	v_mfma_f32_16x16x32_bf16 v[100:103], v[160:163], v[188:191], v[100:103]
	v_mfma_f32_16x16x32_bf16 v[96:99], v[168:171], v[188:191], v[96:99]
	v_mfma_f32_16x16x32_bf16 v[84:87], v[160:163], v[210:213], v[84:87]
	v_mfma_f32_16x16x32_bf16 v[80:83], v[168:171], v[210:213], v[80:83]
	v_mfma_f32_16x16x32_bf16 v[68:71], v[160:163], v[218:221], v[68:71]
	v_mfma_f32_16x16x32_bf16 v[64:67], v[168:171], v[218:221], v[64:67]
	s_setprio 0
	s_barrier
; #define PG8_STAGE(bufoff, gbase, voff) do { _Pragma("unroll") for (int _i = 0; _i < 2; ++_i) \
;         __builtin_amdgcn_global_load_lds((const unsigned*)((const char*)(gbase) + (voff)[_i]), (PG8_LAS unsigned*)(lds + (bufoff) + ldsw + _i * 8192), 16, 0, 0); } while (0)
; #define PG8_LDA(dst, b, h) do { _Pragma("unroll") for (int m = 0; m < 4; ++m) _Pragma("unroll") for (int k = 0; k < 2; ++k) dst[m][k] = *(const PG8_LAS bf16x8*)(lds + PG8_SA(b, h) + aoff + m * 2048 + k * 1024); } while (0)
; #define PG8_LDB(dst, b, h) do { _Pragma("unroll") for (int n = 0; n < 2; ++n) _Pragma("unroll") for (int k = 0; k < 2; ++k) dst[n][k] = *(const PG8_LAS bf16x8*)(lds + PG8_SB(b, h) + boff + n * 2048 + k * 1024); } while (0)
; #define PG8_MMA(ai, bj, At, Bt) do { __builtin_amdgcn_s_setprio(1); _Pragma("unroll") for (int m = 0; m < 4; ++m) _Pragma("unroll") for (int n = 0; n < 2; ++n) _Pragma("unroll") for (int k = 0; k < 2; ++k) \
;         acc[ai][bj][m][n] = __builtin_amdgcn_mfma_f32_16x16x32_bf16(Bt[n][k], At[m][k], acc[ai][bj][m][n], 0, 0, 0); __builtin_amdgcn_s_setprio(0); } while (0)
; #define PG8_WAIT_V(n) asm volatile("s_waitcnt vmcnt(" #n ")" ::: "memory")
; #define PG8_WAIT_L(n) asm volatile("s_waitcnt lgkmcnt(" #n ")" ::: "memory")
; #define PG8_BAR __builtin_amdgcn_s_barrier()
; #define PG8_SCHED __builtin_amdgcn_sched_barrier(0)
; template <class Epi, class Sched, bool ALIGN_EPI = false, bool SP2 = false>
; __device__ __forceinline__ void gemm_phase(PG8_LAS unsigned char* lds, const Gemm g, const Sched& S, const Epi& E) {
;     ...
;             PG8_LDA(At, 0, 1); PG8_STAGE(PG8_SB(0, 0), b2, voffB); PG8_STAGE(PG8_SB(0, 1), b2 + hstep, voffB); PG8_STAGE(PG8_SA(0, 0), a2, voffA);
;             PG8_WAIT_V(8); PG8_WAIT_L(0); PG8_BAR; PG8_MMA(1, 0, At, B0); PG8_MMA(1, 1, At, B1); PG8_BAR; PG8_SCHED;
;             PG8_LDB(B0, 1, 0); PG8_LDB(B1, 1, 1); PG8_SCHED; PG8_LDA(At, 1, 0); PG8_STAGE(PG8_SA(0, 1), a2 + hstep, voffA);
;             PG8_WAIT_V(8); PG8_WAIT_L(0); PG8_BAR; PG8_MMA(0, 0, At, B0); PG8_MMA(0, 1, At, B1); PG8_BAR; PG8_SCHED;
	s_add_i32 s43, s43, s39
	v_lshl_add_u64 v[194:195], s[12:13], 0, v[138:139]
	s_mov_b32 m0, s43
	s_nop 0
	global_load_lds_dwordx4 v[194:195], off
	s_add_i32 m0, s43, 0x2000
	s_add_u32 s86, s12, 0x80000
	v_lshl_add_u64 v[196:197], s[12:13], 0, v[142:143]
	s_addc_u32 s87, s13, 0
	s_add_i32 s43, s65, s39
	global_load_lds_dwordx4 v[196:197], off
	v_lshl_add_u64 v[202:203], s[86:87], 0, v[138:139]
	s_mov_b32 m0, s43
	v_lshl_add_u64 v[204:205], s[14:15], 0, v[140:141]
	global_load_lds_dwordx4 v[202:203], off
	s_add_i32 m0, s43, 0x2000
	v_lshl_add_u64 v[202:203], s[86:87], 0, v[142:143]
	global_load_lds_dwordx4 v[202:203], off
	s_mov_b32 m0, s74
	v_lshl_add_u64 v[202:203], s[14:15], 0, v[136:137]
	global_load_lds_dwordx4 v[202:203], off
	s_mov_b32 m0, s75
	s_nop 0
	global_load_lds_dwordx4 v[204:205], off
	ds_read_b128 v[172:175], v179 offset:16384
	ds_read_b128 v[180:183], v179 offset:17408
	ds_read_b128 v[184:187], v179 offset:18432
	ds_read_b128 v[188:191], v179 offset:19456
	ds_read_b128 v[206:209], v179 offset:20480
	ds_read_b128 v[210:213], v179 offset:21504
	ds_read_b128 v[214:217], v179 offset:22528
	ds_read_b128 v[218:221], v179 offset:23552
	s_waitcnt vmcnt(8)
	s_waitcnt lgkmcnt(0)
	s_barrier
	s_setprio 1
	s_waitcnt lgkmcnt(0)
	v_mfma_f32_16x16x32_bf16 v[60:63], v[128:131], v[172:175], v[60:63]
	v_mfma_f32_16x16x32_bf16 v[56:59], v[148:151], v[172:175], v[56:59]
	v_mfma_f32_16x16x32_bf16 v[44:47], v[128:131], v[184:187], v[44:47]
	v_mfma_f32_16x16x32_bf16 v[40:43], v[148:151], v[184:187], v[40:43]
	v_mfma_f32_16x16x32_bf16 v[28:31], v[128:131], v[206:209], v[28:31]
	v_mfma_f32_16x16x32_bf16 v[24:27], v[148:151], v[206:209], v[24:27]
	v_mfma_f32_16x16x32_bf16 v[12:15], v[128:131], v[214:217], v[12:15]
	v_mfma_f32_16x16x32_bf16 v[8:11], v[148:151], v[214:217], v[8:11]
	v_mfma_f32_16x16x32_bf16 v[60:63], v[132:135], v[180:183], v[60:63]
	v_mfma_f32_16x16x32_bf16 v[56:59], v[152:155], v[180:183], v[56:59]
	v_mfma_f32_16x16x32_bf16 v[44:47], v[132:135], v[188:191], v[44:47]
	v_mfma_f32_16x16x32_bf16 v[40:43], v[152:155], v[188:191], v[40:43]
	v_mfma_f32_16x16x32_bf16 v[28:31], v[132:135], v[210:213], v[28:31]
	v_mfma_f32_16x16x32_bf16 v[24:27], v[152:155], v[210:213], v[24:27]
	v_mfma_f32_16x16x32_bf16 v[12:15], v[132:135], v[218:221], v[12:15]
	v_mfma_f32_16x16x32_bf16 v[8:11], v[152:155], v[218:221], v[8:11]
	s_setprio 0
	s_setprio 1
	v_mfma_f32_16x16x32_bf16 v[52:55], v[156:159], v[172:175], v[52:55]
	v_mfma_f32_16x16x32_bf16 v[48:51], v[164:167], v[172:175], v[48:51]
	v_mfma_f32_16x16x32_bf16 v[36:39], v[156:159], v[184:187], v[36:39]
	v_mfma_f32_16x16x32_bf16 v[32:35], v[164:167], v[184:187], v[32:35]
	v_mfma_f32_16x16x32_bf16 v[20:23], v[156:159], v[206:209], v[20:23]
	v_mfma_f32_16x16x32_bf16 v[16:19], v[164:167], v[206:209], v[16:19]
	v_mfma_f32_16x16x32_bf16 v[4:7], v[156:159], v[214:217], v[4:7]
	v_mfma_f32_16x16x32_bf16 v[0:3], v[164:167], v[214:217], v[0:3]
	v_mfma_f32_16x16x32_bf16 v[52:55], v[160:163], v[180:183], v[52:55]
	v_mfma_f32_16x16x32_bf16 v[48:51], v[168:171], v[180:183], v[48:51]
	v_mfma_f32_16x16x32_bf16 v[36:39], v[160:163], v[188:191], v[36:39]
	v_mfma_f32_16x16x32_bf16 v[32:35], v[168:171], v[188:191], v[32:35]
	v_mfma_f32_16x16x32_bf16 v[20:23], v[160:163], v[210:213], v[20:23]
	v_mfma_f32_16x16x32_bf16 v[16:19], v[168:171], v[210:213], v[16:19]
	v_mfma_f32_16x16x32_bf16 v[4:7], v[160:163], v[218:221], v[4:7]
	v_mfma_f32_16x16x32_bf16 v[0:3], v[168:171], v[218:221], v[0:3]
	s_setprio 0
	s_barrier
	s_add_i32 s43, 0, 0x18000
	s_add_i32 s65, 0, 0x1c000
	s_add_u32 s14, s14, 0x80000
	s_addc_u32 s15, s15, 0
	s_mov_b32 m0, s76
	v_lshl_add_u64 v[232:233], s[14:15], 0, v[136:137]
	global_load_lds_dwordx4 v[232:233], off
	s_mov_b32 m0, s77
	v_lshl_add_u64 v[232:233], s[14:15], 0, v[140:141]
	global_load_lds_dwordx4 v[232:233], off
	v_add_u32_e32 v152, 0x18000, v178
	v_add_u32_e32 v168, 0x1c000, v178
	ds_read_b128 v[128:131], v152
	ds_read_b128 v[132:135], v152 offset:1024
	ds_read_b128 v[148:151], v152 offset:2048
	ds_read_b128 v[152:155], v152 offset:3072
	ds_read_b128 v[156:159], v168
	ds_read_b128 v[160:163], v168 offset:1024
	ds_read_b128 v[164:167], v168 offset:2048
	ds_read_b128 v[168:171], v168 offset:3072
	ds_read_b128 v[172:175], v179 offset:32768
	ds_read_b128 v[180:183], v179 offset:33792
	ds_read_b128 v[184:187], v179 offset:34816
	ds_read_b128 v[188:191], v179 offset:35840
	ds_read_b128 v[206:209], v179 offset:36864
	ds_read_b128 v[210:213], v179 offset:37888
	ds_read_b128 v[214:217], v179 offset:38912
	ds_read_b128 v[218:221], v179 offset:39936
	s_waitcnt vmcnt(8)
	s_waitcnt lgkmcnt(0)
	s_barrier
; #define PG8_STAGE(bufoff, gbase, voff) do { _Pragma("unroll") for (int _i = 0; _i < 2; ++_i) \
;         __builtin_amdgcn_global_load_lds((const unsigned*)((const char*)(gbase) + (voff)[_i]), (PG8_LAS unsigned*)(lds + (bufoff) + ldsw + _i * 8192), 16, 0, 0); } while (0)
; #define PG8_LDA(dst, b, h) do { _Pragma("unroll") for (int m = 0; m < 4; ++m) _Pragma("unroll") for (int k = 0; k < 2; ++k) dst[m][k] = *(const PG8_LAS bf16x8*)(lds + PG8_SA(b, h) + aoff + m * 2048 + k * 1024); } while (0)
; #define PG8_LDB(dst, b, h) do { _Pragma("unroll") for (int n = 0; n < 2; ++n) _Pragma("unroll") for (int k = 0; k < 2; ++k) dst[n][k] = *(const PG8_LAS bf16x8*)(lds + PG8_SB(b, h) + boff + n * 2048 + k * 1024); } while (0)
; #define PG8_MMA(ai, bj, At, Bt) do { __builtin_amdgcn_s_setprio(1); _Pragma("unroll") for (int m = 0; m < 4; ++m) _Pragma("unroll") for (int n = 0; n < 2; ++n) _Pragma("unroll") for (int k = 0; k < 2; ++k) \
;         acc[ai][bj][m][n] = __builtin_amdgcn_mfma_f32_16x16x32_bf16(Bt[n][k], At[m][k], acc[ai][bj][m][n], 0, 0, 0); __builtin_amdgcn_s_setprio(0); } while (0)
; #define PG8_WAIT_V(n) asm volatile("s_waitcnt vmcnt(" #n ")" ::: "memory")
; #define PG8_WAIT_L(n) asm volatile("s_waitcnt lgkmcnt(" #n ")" ::: "memory")
; #define PG8_BAR __builtin_amdgcn_s_barrier()
; #define PG8_SCHED __builtin_amdgcn_sched_barrier(0)
; template <class Epi, class Sched, bool ALIGN_EPI = false, bool SP2 = false>
; __device__ __forceinline__ void gemm_phase(PG8_LAS unsigned char* lds, const Gemm g, const Sched& S, const Epi& E) {
;     ...
;             PG8_LDB(B0, 1, 0); PG8_LDB(B1, 1, 1); PG8_SCHED; PG8_LDA(At, 1, 0); PG8_STAGE(PG8_SA(0, 1), a2 + hstep, voffA);
;             PG8_WAIT_V(8); PG8_WAIT_L(0); PG8_BAR; PG8_MMA(0, 0, At, B0); PG8_MMA(0, 1, At, B1); PG8_BAR; PG8_SCHED;
;             PG8_LDA(At, 1, 1); PG8_STAGE(PG8_SB(1, 0), b3, voffB); PG8_STAGE(PG8_SB(1, 1), b3 + hstep, voffB); PG8_STAGE(PG8_SA(1, 0), a3, voffA);
;             PG8_WAIT_V(8); PG8_WAIT_L(0); PG8_BAR; PG8_MMA(1, 0, At, B0); PG8_MMA(1, 1, At, B1); PG8_BAR; PG8_SCHED;
;     ...
;         if constexpr (ALIGN_EPI) { if (wr == 0) PG8_BAR; }
	s_setprio 1
	s_waitcnt lgkmcnt(0)
	v_mfma_f32_16x16x32_bf16 v[124:127], v[128:131], v[172:175], v[124:127]
	v_mfma_f32_16x16x32_bf16 v[120:123], v[148:151], v[172:175], v[120:123]
	v_mfma_f32_16x16x32_bf16 v[108:111], v[128:131], v[184:187], v[108:111]
	v_mfma_f32_16x16x32_bf16 v[104:107], v[148:151], v[184:187], v[104:107]
	v_mfma_f32_16x16x32_bf16 v[92:95], v[128:131], v[206:209], v[92:95]
	v_mfma_f32_16x16x32_bf16 v[88:91], v[148:151], v[206:209], v[88:91]
	v_mfma_f32_16x16x32_bf16 v[76:79], v[128:131], v[214:217], v[76:79]
	v_mfma_f32_16x16x32_bf16 v[72:75], v[148:151], v[214:217], v[72:75]
	v_mfma_f32_16x16x32_bf16 v[124:127], v[132:135], v[180:183], v[124:127]
	v_mfma_f32_16x16x32_bf16 v[120:123], v[152:155], v[180:183], v[120:123]
	v_mfma_f32_16x16x32_bf16 v[108:111], v[132:135], v[188:191], v[108:111]
	v_mfma_f32_16x16x32_bf16 v[104:107], v[152:155], v[188:191], v[104:107]
	v_mfma_f32_16x16x32_bf16 v[92:95], v[132:135], v[210:213], v[92:95]
	v_mfma_f32_16x16x32_bf16 v[88:91], v[152:155], v[210:213], v[88:91]
	v_mfma_f32_16x16x32_bf16 v[76:79], v[132:135], v[218:221], v[76:79]
	v_mfma_f32_16x16x32_bf16 v[72:75], v[152:155], v[218:221], v[72:75]
	s_setprio 0
	s_setprio 1
	v_mfma_f32_16x16x32_bf16 v[116:119], v[156:159], v[172:175], v[116:119]
	v_mfma_f32_16x16x32_bf16 v[112:115], v[164:167], v[172:175], v[112:115]
	v_mfma_f32_16x16x32_bf16 v[100:103], v[156:159], v[184:187], v[100:103]
	v_mfma_f32_16x16x32_bf16 v[96:99], v[164:167], v[184:187], v[96:99]
	v_mfma_f32_16x16x32_bf16 v[84:87], v[156:159], v[206:209], v[84:87]
	v_mfma_f32_16x16x32_bf16 v[80:83], v[164:167], v[206:209], v[80:83]
	v_mfma_f32_16x16x32_bf16 v[68:71], v[156:159], v[214:217], v[68:71]
	v_mfma_f32_16x16x32_bf16 v[64:67], v[164:167], v[214:217], v[64:67]
	v_mfma_f32_16x16x32_bf16 v[116:119], v[160:163], v[180:183], v[116:119]
	v_mfma_f32_16x16x32_bf16 v[112:115], v[168:171], v[180:183], v[112:115]
	v_mfma_f32_16x16x32_bf16 v[100:103], v[160:163], v[188:191], v[100:103]
	v_mfma_f32_16x16x32_bf16 v[96:99], v[168:171], v[188:191], v[96:99]
	v_mfma_f32_16x16x32_bf16 v[84:87], v[160:163], v[210:213], v[84:87]
	v_mfma_f32_16x16x32_bf16 v[80:83], v[168:171], v[210:213], v[80:83]
	v_mfma_f32_16x16x32_bf16 v[68:71], v[160:163], v[218:221], v[68:71]
	v_mfma_f32_16x16x32_bf16 v[64:67], v[168:171], v[218:221], v[64:67]
	s_setprio 0
	s_barrier
	s_add_i32 s14, s43, s39
	v_lshl_add_u64 v[194:195], v[194:195], 0, s[16:17]
	s_mov_b32 m0, s14
	s_nop 0
	global_load_lds_dwordx4 v[194:195], off
	s_add_i32 m0, s14, 0x2000
	s_add_u32 s12, s12, 0x80080
	v_lshl_add_u64 v[194:195], v[196:197], 0, s[16:17]
	s_addc_u32 s13, s13, 0
	s_add_i32 s14, s65, s39
	global_load_lds_dwordx4 v[194:195], off
	s_mov_b32 m0, s14
	v_lshl_add_u64 v[194:195], s[12:13], 0, v[138:139]
	global_load_lds_dwordx4 v[194:195], off
	s_add_i32 m0, s14, 0x2000
	v_lshl_add_u64 v[194:195], s[12:13], 0, v[142:143]
	global_load_lds_dwordx4 v[194:195], off
	s_mov_b32 m0, s80
	v_lshl_add_u64 v[194:195], v[202:203], 0, s[16:17]
	global_load_lds_dwordx4 v[194:195], off
	s_mov_b32 m0, s81
	v_lshl_add_u64 v[194:195], v[204:205], 0, s[16:17]
	global_load_lds_dwordx4 v[194:195], off
	ds_read_b128 v[172:175], v179 offset:49152
	ds_read_b128 v[180:183], v179 offset:50176
	ds_read_b128 v[184:187], v179 offset:51200
	ds_read_b128 v[188:191], v179 offset:52224
	ds_read_b128 v[206:209], v179 offset:53248
	ds_read_b128 v[210:213], v179 offset:54272
	ds_read_b128 v[214:217], v179 offset:55296
	ds_read_b128 v[218:221], v179 offset:56320
	s_waitcnt vmcnt(8)
	s_waitcnt lgkmcnt(0)
	s_barrier
	s_setprio 1
	s_waitcnt lgkmcnt(0)
	v_mfma_f32_16x16x32_bf16 v[60:63], v[128:131], v[172:175], v[60:63]
	v_mfma_f32_16x16x32_bf16 v[56:59], v[148:151], v[172:175], v[56:59]
	v_mfma_f32_16x16x32_bf16 v[44:47], v[128:131], v[184:187], v[44:47]
	v_mfma_f32_16x16x32_bf16 v[40:43], v[148:151], v[184:187], v[40:43]
	v_mfma_f32_16x16x32_bf16 v[28:31], v[128:131], v[206:209], v[28:31]
	v_mfma_f32_16x16x32_bf16 v[24:27], v[148:151], v[206:209], v[24:27]
	v_mfma_f32_16x16x32_bf16 v[12:15], v[128:131], v[214:217], v[12:15]
	v_mfma_f32_16x16x32_bf16 v[8:11], v[148:151], v[214:217], v[8:11]
	v_mfma_f32_16x16x32_bf16 v[60:63], v[132:135], v[180:183], v[60:63]
	v_mfma_f32_16x16x32_bf16 v[56:59], v[152:155], v[180:183], v[56:59]
	v_mfma_f32_16x16x32_bf16 v[44:47], v[132:135], v[188:191], v[44:47]
	v_mfma_f32_16x16x32_bf16 v[40:43], v[152:155], v[188:191], v[40:43]
	v_mfma_f32_16x16x32_bf16 v[28:31], v[132:135], v[210:213], v[28:31]
	v_mfma_f32_16x16x32_bf16 v[24:27], v[152:155], v[210:213], v[24:27]
	v_mfma_f32_16x16x32_bf16 v[12:15], v[132:135], v[218:221], v[12:15]
	v_mfma_f32_16x16x32_bf16 v[8:11], v[152:155], v[218:221], v[8:11]
	s_setprio 0
	s_setprio 1
	v_mfma_f32_16x16x32_bf16 v[52:55], v[156:159], v[172:175], v[52:55]
	v_mfma_f32_16x16x32_bf16 v[48:51], v[164:167], v[172:175], v[48:51]
	v_mfma_f32_16x16x32_bf16 v[36:39], v[156:159], v[184:187], v[36:39]
	v_mfma_f32_16x16x32_bf16 v[32:35], v[164:167], v[184:187], v[32:35]
	v_mfma_f32_16x16x32_bf16 v[20:23], v[156:159], v[206:209], v[20:23]
	v_mfma_f32_16x16x32_bf16 v[16:19], v[164:167], v[206:209], v[16:19]
	v_mfma_f32_16x16x32_bf16 v[4:7], v[156:159], v[214:217], v[4:7]
	v_mfma_f32_16x16x32_bf16 v[0:3], v[164:167], v[214:217], v[0:3]
	v_mfma_f32_16x16x32_bf16 v[52:55], v[160:163], v[180:183], v[52:55]
	v_mfma_f32_16x16x32_bf16 v[48:51], v[168:171], v[180:183], v[48:51]
	v_mfma_f32_16x16x32_bf16 v[36:39], v[160:163], v[188:191], v[36:39]
	v_mfma_f32_16x16x32_bf16 v[32:35], v[168:171], v[188:191], v[32:35]
	v_mfma_f32_16x16x32_bf16 v[20:23], v[160:163], v[210:213], v[20:23]
	v_mfma_f32_16x16x32_bf16 v[16:19], v[168:171], v[210:213], v[16:19]
	v_mfma_f32_16x16x32_bf16 v[4:7], v[160:163], v[218:221], v[4:7]
	v_mfma_f32_16x16x32_bf16 v[0:3], v[168:171], v[218:221], v[0:3]
	s_setprio 0
	s_barrier
	s_add_i32 s42, s42, 2
	s_add_u32 s0, s0, 0x100
	s_addc_u32 s1, s1, 0
	s_add_u32 s34, s34, 0x100
	s_addc_u32 s41, s41, 0
	s_cmp_gt_u32 s42, 29
	s_cbranch_scc0 .LBB0_129
	s_and_b64 vcc, exec, s[62:63]
	s_cbranch_vccz .LBB0_132
	s_barrier

; #define PG8_STAGE(bufoff, gbase, voff) do { _Pragma("unroll") for (int _i = 0; _i < 2; ++_i) \
;         __builtin_amdgcn_global_load_lds((const unsigned*)((const char*)(gbase) + (voff)[_i]), (PG8_LAS unsigned*)(lds + (bufoff) + ldsw + _i * 8192), 16, 0, 0); } while (0)
; #define PG8_LDA(dst, b, h) do { _Pragma("unroll") for (int m = 0; m < 4; ++m) _Pragma("unroll") for (int k = 0; k < 2; ++k) dst[m][k] = *(const PG8_LAS bf16x8*)(lds + PG8_SA(b, h) + aoff + m * 2048 + k * 1024); } while (0)
; #define PG8_LDB(dst, b, h) do { _Pragma("unroll") for (int n = 0; n < 2; ++n) _Pragma("unroll") for (int k = 0; k < 2; ++k) dst[n][k] = *(const PG8_LAS bf16x8*)(lds + PG8_SB(b, h) + boff + n * 2048 + k * 1024); } while (0)
; #define PG8_WAIT_V(n) asm volatile("s_waitcnt vmcnt(" #n ")" ::: "memory")
; #define PG8_WAIT_L(n) asm volatile("s_waitcnt lgkmcnt(" #n ")" ::: "memory")
; #define PG8_BAR __builtin_amdgcn_s_barrier()
; #define PG8_SCHED __builtin_amdgcn_sched_barrier(0)
; template <class Epi, class Sched, bool ALIGN_EPI = false, bool SP2 = false>
; __device__ __forceinline__ void gemm_phase(PG8_LAS unsigned char* lds, const Gemm g, const Sched& S, const Epi& E) {
;     ...
;         const char* nA = has_next ? (const char*)g.A + (size_t)nxt.pm * tstep : cA; const char* nB = has_next ? (const char*)g.Bt + (size_t)nxt.pn * tstep : cB;
;         for (int t = 0; t < nt; t += 2) {
;             if constexpr (Epi::MID_HOOK) { if (t == Epi::MID_T) E.mid(acc, cur, wr, wc, fr, fq); }
;             const bool last = (t == nt - 2);
;             const char* a1 = cA + (size_t)(t + 1) * kstep;
;             const char* a2 = last ? nA : cA + (size_t)(t + 2) * kstep; const char* b2 = last ? nB : cB + (size_t)(t + 2) * kstep;
;             const char* a3 = a2 + kstep; const char* b3 = b2 + kstep;
;             if (last && has_next) S.a_ready(nxt);
;             if constexpr (SP2) {
;             PG8_LDB(B0, 0, 0); PG8_LDB(B1, 0, 1); PG8_SCHED; PG8_LDA(At, 0, 0); PG8_STAGE(PG8_SA(1, 1), a1 + hstep, voffA);
;             PG8_WAIT_V(8); PG8_WAIT_L(0); PG8_BAR; PG8_MMA(0, 0, At, B0); PG8_MMA(0, 1, At, B1); PG8_BAR; PG8_SCHED;
;             PG8_LDA(At, 0, 1); PG8_STAGE(PG8_SB(0, 0), b2, voffB); PG8_STAGE(PG8_SB(0, 1), b2 + hstep, voffB); PG8_STAGE(PG8_SA(0, 0), a2, voffA);
;             PG8_WAIT_V(8); PG8_WAIT_L(0); PG8_BAR; PG8_MMA(1, 0, At, B0); PG8_MMA(1, 1, At, B1); PG8_BAR; PG8_SCHED;
.LBB0_634:
	s_ashr_i32 s15, s14, 31
	s_lshl_b64 s[18:19], s[14:15], 20
	s_add_u32 s18, s45, s18
	s_addc_u32 s19, s46, s19
	s_and_b64 s[30:31], s[0:1], exec
	s_cselect_b32 s15, s19, s37
	s_cselect_b32 s61, s18, s36
	s_ashr_i32 s13, s12, 31
	s_lshl_b64 s[30:31], s[12:13], 20
	s_add_u32 s30, s34, s30
	s_addc_u32 s31, s44, s31
	s_and_b64 s[42:43], s[0:1], exec
	s_cselect_b32 s13, s31, s39
	s_cselect_b32 s62, s30, s38
	s_add_u32 s36, s36, 0x80080
	s_addc_u32 s37, s37, 0
	s_add_u32 s63, s38, 0x100
	s_addc_u32 s64, s39, 0
	s_mov_b32 s65, -2
	s_waitcnt lgkmcnt(0)
	v_lshl_add_u64 v[168:169], s[36:37], 0, v[160:161]
	s_add_i32 m0, s2, 0xc000
	global_load_lds_dwordx4 v[168:169], off
	s_add_i32 m0, s2, 0xe000
	v_lshl_add_u64 v[168:169], s[36:37], 0, v[162:163]
	global_load_lds_dwordx4 v[168:169], off
	s_add_u32 s24, s36, 0xfff80080
	s_addc_u32 s25, s37, -1
	s_add_i32 s33, 0, 0x10000
	s_cmp_eq_u32 s65, 28
	s_cselect_b32 s43, s15, s25
	s_cselect_b32 s42, s61, s24
	s_cselect_b32 s39, s13, s64
	s_cselect_b32 s38, s62, s63
	s_add_i32 s24, 0, 0x14000
	s_waitcnt vmcnt(8)
	s_waitcnt lgkmcnt(0)
	s_barrier
	s_setprio 1
	s_waitcnt lgkmcnt(0)
	v_mfma_f32_16x16x32_bf16 v[124:127], v[128:131], v[178:181], 0
	v_mfma_f32_16x16x32_bf16 v[120:123], v[136:139], v[178:181], 0
	v_mfma_f32_16x16x32_bf16 v[108:111], v[128:131], v[186:189], 0
	v_mfma_f32_16x16x32_bf16 v[104:107], v[136:139], v[186:189], 0
	v_mfma_f32_16x16x32_bf16 v[92:95], v[128:131], v[202:205], 0
	v_mfma_f32_16x16x32_bf16 v[88:91], v[136:139], v[202:205], 0
	v_mfma_f32_16x16x32_bf16 v[76:79], v[128:131], v[210:213], 0
	v_mfma_f32_16x16x32_bf16 v[72:75], v[136:139], v[210:213], 0
	v_mfma_f32_16x16x32_bf16 v[124:127], v[132:135], v[182:185], v[124:127]
	v_mfma_f32_16x16x32_bf16 v[120:123], v[140:143], v[182:185], v[120:123]
	v_mfma_f32_16x16x32_bf16 v[108:111], v[132:135], v[194:197], v[108:111]
	v_mfma_f32_16x16x32_bf16 v[104:107], v[140:143], v[194:197], v[104:107]
	v_mfma_f32_16x16x32_bf16 v[92:95], v[132:135], v[206:209], v[92:95]
	v_mfma_f32_16x16x32_bf16 v[88:91], v[140:143], v[206:209], v[88:91]
	v_mfma_f32_16x16x32_bf16 v[76:79], v[132:135], v[214:217], v[76:79]
	v_mfma_f32_16x16x32_bf16 v[72:75], v[140:143], v[214:217], v[72:75]
	s_setprio 0
	s_setprio 1
	v_mfma_f32_16x16x32_bf16 v[116:119], v[144:147], v[178:181], 0
	v_mfma_f32_16x16x32_bf16 v[112:115], v[164:167], v[178:181], 0
	v_mfma_f32_16x16x32_bf16 v[100:103], v[144:147], v[186:189], 0
	v_mfma_f32_16x16x32_bf16 v[96:99], v[164:167], v[186:189], 0
	v_mfma_f32_16x16x32_bf16 v[84:87], v[144:147], v[202:205], 0
	v_mfma_f32_16x16x32_bf16 v[80:83], v[164:167], v[202:205], 0
	v_mfma_f32_16x16x32_bf16 v[68:71], v[144:147], v[210:213], 0
	v_mfma_f32_16x16x32_bf16 v[64:67], v[164:167], v[210:213], 0
	v_mfma_f32_16x16x32_bf16 v[116:119], v[148:151], v[182:185], v[116:119]
	v_mfma_f32_16x16x32_bf16 v[112:115], v[174:177], v[182:185], v[112:115]
	v_mfma_f32_16x16x32_bf16 v[100:103], v[148:151], v[194:197], v[100:103]
	v_mfma_f32_16x16x32_bf16 v[96:99], v[174:177], v[194:197], v[96:99]
	v_mfma_f32_16x16x32_bf16 v[84:87], v[148:151], v[206:209], v[84:87]
	v_mfma_f32_16x16x32_bf16 v[80:83], v[174:177], v[206:209], v[80:83]
	v_mfma_f32_16x16x32_bf16 v[68:71], v[148:151], v[214:217], v[68:71]
	v_mfma_f32_16x16x32_bf16 v[64:67], v[174:177], v[214:217], v[64:67]
	s_setprio 0
	s_barrier
	s_add_i32 s25, s33, s47
	v_lshl_add_u64 v[168:169], s[38:39], 0, v[156:157]
	s_mov_b32 m0, s25
	s_nop 0
	global_load_lds_dwordx4 v[168:169], off
	s_add_i32 m0, s25, 0x2000
	s_add_u32 s66, s38, 0x80000
	v_lshl_add_u64 v[190:191], s[38:39], 0, v[152:153]
	s_addc_u32 s67, s39, 0
	s_add_i32 s24, s24, s47
	global_load_lds_dwordx4 v[190:191], off
	v_lshl_add_u64 v[218:219], s[66:67], 0, v[156:157]
	s_mov_b32 m0, s24
	v_lshl_add_u64 v[220:221], s[42:43], 0, v[154:155]
	global_load_lds_dwordx4 v[218:219], off
	s_add_i32 m0, s24, 0x2000
	v_lshl_add_u64 v[218:219], s[66:67], 0, v[152:153]
	global_load_lds_dwordx4 v[218:219], off
	s_mov_b32 m0, s2
	v_lshl_add_u64 v[218:219], s[42:43], 0, v[158:159]
	global_load_lds_dwordx4 v[218:219], off
	s_mov_b32 m0, s48
	s_nop 0
	global_load_lds_dwordx4 v[220:221], off
	ds_read_b128 v[178:181], v173 offset:16384
	ds_read_b128 v[182:185], v173 offset:17408
	ds_read_b128 v[186:189], v173 offset:18432
	ds_read_b128 v[194:197], v173 offset:19456
	ds_read_b128 v[202:205], v173 offset:20480
	ds_read_b128 v[206:209], v173 offset:21504
	ds_read_b128 v[210:213], v173 offset:22528
	ds_read_b128 v[214:217], v173 offset:23552
	s_waitcnt vmcnt(8)
	s_waitcnt lgkmcnt(0)
	s_barrier
	s_setprio 1
	s_waitcnt lgkmcnt(0)
	v_mfma_f32_16x16x32_bf16 v[60:63], v[128:131], v[178:181], 0
	v_mfma_f32_16x16x32_bf16 v[56:59], v[136:139], v[178:181], 0
	v_mfma_f32_16x16x32_bf16 v[44:47], v[128:131], v[186:189], 0
	v_mfma_f32_16x16x32_bf16 v[40:43], v[136:139], v[186:189], 0
	v_mfma_f32_16x16x32_bf16 v[28:31], v[128:131], v[202:205], 0
	v_mfma_f32_16x16x32_bf16 v[24:27], v[136:139], v[202:205], 0
	v_mfma_f32_16x16x32_bf16 v[12:15], v[128:131], v[210:213], 0
	v_mfma_f32_16x16x32_bf16 v[8:11], v[136:139], v[210:213], 0
	v_mfma_f32_16x16x32_bf16 v[60:63], v[132:135], v[182:185], v[60:63]
	v_mfma_f32_16x16x32_bf16 v[56:59], v[140:143], v[182:185], v[56:59]
	v_mfma_f32_16x16x32_bf16 v[44:47], v[132:135], v[194:197], v[44:47]
	v_mfma_f32_16x16x32_bf16 v[40:43], v[140:143], v[194:197], v[40:43]
	v_mfma_f32_16x16x32_bf16 v[28:31], v[132:135], v[206:209], v[28:31]
	v_mfma_f32_16x16x32_bf16 v[24:27], v[140:143], v[206:209], v[24:27]
	v_mfma_f32_16x16x32_bf16 v[12:15], v[132:135], v[214:217], v[12:15]
	v_mfma_f32_16x16x32_bf16 v[8:11], v[140:143], v[214:217], v[8:11]
	s_setprio 0
	s_setprio 1
	v_mfma_f32_16x16x32_bf16 v[52:55], v[144:147], v[178:181], 0
	v_mfma_f32_16x16x32_bf16 v[48:51], v[164:167], v[178:181], 0
	v_mfma_f32_16x16x32_bf16 v[36:39], v[144:147], v[186:189], 0
	v_mfma_f32_16x16x32_bf16 v[32:35], v[164:167], v[186:189], 0
	v_mfma_f32_16x16x32_bf16 v[20:23], v[144:147], v[202:205], 0
	v_mfma_f32_16x16x32_bf16 v[16:19], v[164:167], v[202:205], 0
	v_mfma_f32_16x16x32_bf16 v[4:7], v[144:147], v[210:213], 0
	v_mfma_f32_16x16x32_bf16 v[0:3], v[164:167], v[210:213], 0
	v_mfma_f32_16x16x32_bf16 v[52:55], v[148:151], v[182:185], v[52:55]
	v_mfma_f32_16x16x32_bf16 v[48:51], v[174:177], v[182:185], v[48:51]
	v_mfma_f32_16x16x32_bf16 v[36:39], v[148:151], v[194:197], v[36:39]
	v_mfma_f32_16x16x32_bf16 v[32:35], v[174:177], v[194:197], v[32:35]
	v_mfma_f32_16x16x32_bf16 v[20:23], v[148:151], v[206:209], v[20:23]
	v_mfma_f32_16x16x32_bf16 v[16:19], v[174:177], v[206:209], v[16:19]
	v_mfma_f32_16x16x32_bf16 v[4:7], v[148:151], v[214:217], v[4:7]
	v_mfma_f32_16x16x32_bf16 v[0:3], v[174:177], v[214:217], v[0:3]
	s_setprio 0
	s_barrier
; #define PG8_STAGE(bufoff, gbase, voff) do { _Pragma("unroll") for (int _i = 0; _i < 2; ++_i) \
;         __builtin_amdgcn_global_load_lds((const unsigned*)((const char*)(gbase) + (voff)[_i]), (PG8_LAS unsigned*)(lds + (bufoff) + ldsw + _i * 8192), 16, 0, 0); } while (0)
; #define PG8_LDA(dst, b, h) do { _Pragma("unroll") for (int m = 0; m < 4; ++m) _Pragma("unroll") for (int k = 0; k < 2; ++k) dst[m][k] = *(const PG8_LAS bf16x8*)(lds + PG8_SA(b, h) + aoff + m * 2048 + k * 1024); } while (0)
; #define PG8_LDB(dst, b, h) do { _Pragma("unroll") for (int n = 0; n < 2; ++n) _Pragma("unroll") for (int k = 0; k < 2; ++k) dst[n][k] = *(const PG8_LAS bf16x8*)(lds + PG8_SB(b, h) + boff + n * 2048 + k * 1024); } while (0)
; #define PG8_MMA(ai, bj, At, Bt) do { __builtin_amdgcn_s_setprio(1); _Pragma("unroll") for (int m = 0; m < 4; ++m) _Pragma("unroll") for (int n = 0; n < 2; ++n) _Pragma("unroll") for (int k = 0; k < 2; ++k) \
;         acc[ai][bj][m][n] = __builtin_amdgcn_mfma_f32_16x16x32_bf16(Bt[n][k], At[m][k], acc[ai][bj][m][n], 0, 0, 0); __builtin_amdgcn_s_setprio(0); } while (0)
; #define PG8_WAIT_V(n) asm volatile("s_waitcnt vmcnt(" #n ")" ::: "memory")
; #define PG8_WAIT_L(n) asm volatile("s_waitcnt lgkmcnt(" #n ")" ::: "memory")
; #define PG8_BAR __builtin_amdgcn_s_barrier()
; #define PG8_SCHED __builtin_amdgcn_sched_barrier(0)
; template <class Epi, class Sched, bool ALIGN_EPI = false, bool SP2 = false>
; __device__ __forceinline__ void gemm_phase(PG8_LAS unsigned char* lds, const Gemm g, const Sched& S, const Epi& E) {
;     ...
;             PG8_LDB(B0, 1, 0); PG8_LDB(B1, 1, 1); PG8_SCHED; PG8_LDA(At, 1, 0); PG8_STAGE(PG8_SA(0, 1), a2 + hstep, voffA);
;             PG8_WAIT_V(8); PG8_WAIT_L(0); PG8_BAR; PG8_MMA(0, 0, At, B0); PG8_MMA(0, 1, At, B1); PG8_BAR; PG8_SCHED;
;             PG8_LDA(At, 1, 1); PG8_STAGE(PG8_SB(1, 0), b3, voffB); PG8_STAGE(PG8_SB(1, 1), b3 + hstep, voffB); PG8_STAGE(PG8_SA(1, 0), a3, voffA);
;             PG8_WAIT_V(8); PG8_WAIT_L(0); PG8_BAR; PG8_MMA(1, 0, At, B0); PG8_MMA(1, 1, At, B1); PG8_BAR; PG8_SCHED;
	s_add_i32 s24, 0, 0x18000
	s_add_i32 s25, 0, 0x1c000
	s_add_u32 s42, s42, 0x80000
	s_addc_u32 s43, s43, 0
	s_mov_b32 m0, s49
	v_lshl_add_u64 v[230:231], s[42:43], 0, v[158:159]
	global_load_lds_dwordx4 v[230:231], off
	s_mov_b32 m0, s50
	v_lshl_add_u64 v[230:231], s[42:43], 0, v[154:155]
	global_load_lds_dwordx4 v[230:231], off
	v_add_u32_e32 v140, 0x18000, v172
	v_add_u32_e32 v174, 0x1c000, v172
	ds_read_b128 v[128:131], v140
	ds_read_b128 v[132:135], v140 offset:1024
	ds_read_b128 v[136:139], v140 offset:2048
	ds_read_b128 v[140:143], v140 offset:3072
	ds_read_b128 v[144:147], v174
	ds_read_b128 v[148:151], v174 offset:1024
	ds_read_b128 v[164:167], v174 offset:2048
	ds_read_b128 v[174:177], v174 offset:3072
	ds_read_b128 v[178:181], v173 offset:32768
	ds_read_b128 v[182:185], v173 offset:33792
	ds_read_b128 v[186:189], v173 offset:34816
	ds_read_b128 v[194:197], v173 offset:35840
	ds_read_b128 v[202:205], v173 offset:36864
	ds_read_b128 v[206:209], v173 offset:37888
	ds_read_b128 v[210:213], v173 offset:38912
	ds_read_b128 v[214:217], v173 offset:39936
	s_waitcnt vmcnt(8)
	s_waitcnt lgkmcnt(0)
	s_barrier
	s_setprio 1
	s_waitcnt lgkmcnt(0)
	v_mfma_f32_16x16x32_bf16 v[124:127], v[128:131], v[178:181], v[124:127]
	v_mfma_f32_16x16x32_bf16 v[120:123], v[136:139], v[178:181], v[120:123]
	v_mfma_f32_16x16x32_bf16 v[108:111], v[128:131], v[186:189], v[108:111]
	v_mfma_f32_16x16x32_bf16 v[104:107], v[136:139], v[186:189], v[104:107]
	v_mfma_f32_16x16x32_bf16 v[92:95], v[128:131], v[202:205], v[92:95]
	v_mfma_f32_16x16x32_bf16 v[88:91], v[136:139], v[202:205], v[88:91]
	v_mfma_f32_16x16x32_bf16 v[76:79], v[128:131], v[210:213], v[76:79]
	v_mfma_f32_16x16x32_bf16 v[72:75], v[136:139], v[210:213], v[72:75]
	v_mfma_f32_16x16x32_bf16 v[124:127], v[132:135], v[182:185], v[124:127]
	v_mfma_f32_16x16x32_bf16 v[120:123], v[140:143], v[182:185], v[120:123]
	v_mfma_f32_16x16x32_bf16 v[108:111], v[132:135], v[194:197], v[108:111]
	v_mfma_f32_16x16x32_bf16 v[104:107], v[140:143], v[194:197], v[104:107]
	v_mfma_f32_16x16x32_bf16 v[92:95], v[132:135], v[206:209], v[92:95]
	v_mfma_f32_16x16x32_bf16 v[88:91], v[140:143], v[206:209], v[88:91]
	v_mfma_f32_16x16x32_bf16 v[76:79], v[132:135], v[214:217], v[76:79]
	v_mfma_f32_16x16x32_bf16 v[72:75], v[140:143], v[214:217], v[72:75]
	s_setprio 0
	s_setprio 1
	v_mfma_f32_16x16x32_bf16 v[116:119], v[144:147], v[178:181], v[116:119]
	v_mfma_f32_16x16x32_bf16 v[112:115], v[164:167], v[178:181], v[112:115]
	v_mfma_f32_16x16x32_bf16 v[100:103], v[144:147], v[186:189], v[100:103]
	v_mfma_f32_16x16x32_bf16 v[96:99], v[164:167], v[186:189], v[96:99]
	v_mfma_f32_16x16x32_bf16 v[84:87], v[144:147], v[202:205], v[84:87]
	v_mfma_f32_16x16x32_bf16 v[80:83], v[164:167], v[202:205], v[80:83]
	v_mfma_f32_16x16x32_bf16 v[68:71], v[144:147], v[210:213], v[68:71]
	v_mfma_f32_16x16x32_bf16 v[64:67], v[164:167], v[210:213], v[64:67]
	v_mfma_f32_16x16x32_bf16 v[116:119], v[148:151], v[182:185], v[116:119]
	v_mfma_f32_16x16x32_bf16 v[112:115], v[174:177], v[182:185], v[112:115]
	v_mfma_f32_16x16x32_bf16 v[100:103], v[148:151], v[194:197], v[100:103]
	v_mfma_f32_16x16x32_bf16 v[96:99], v[174:177], v[194:197], v[96:99]
	v_mfma_f32_16x16x32_bf16 v[84:87], v[148:151], v[206:209], v[84:87]
	v_mfma_f32_16x16x32_bf16 v[80:83], v[174:177], v[206:209], v[80:83]
	v_mfma_f32_16x16x32_bf16 v[68:71], v[148:151], v[214:217], v[68:71]
	v_mfma_f32_16x16x32_bf16 v[64:67], v[174:177], v[214:217], v[64:67]
	s_setprio 0
	s_barrier
	s_add_i32 s24, s24, s47
	v_lshl_add_u64 v[168:169], v[168:169], 0, s[16:17]
	s_mov_b32 m0, s24
	s_nop 0
	global_load_lds_dwordx4 v[168:169], off
	s_add_i32 m0, s24, 0x2000
	s_add_u32 s38, s38, 0x80080
	v_lshl_add_u64 v[168:169], v[190:191], 0, s[16:17]
	s_addc_u32 s39, s39, 0
	s_add_i32 s24, s25, s47
	global_load_lds_dwordx4 v[168:169], off
	s_mov_b32 m0, s24
	v_lshl_add_u64 v[168:169], s[38:39], 0, v[156:157]
	global_load_lds_dwordx4 v[168:169], off
	s_add_i32 m0, s24, 0x2000
	v_lshl_add_u64 v[168:169], s[38:39], 0, v[152:153]
	global_load_lds_dwordx4 v[168:169], off
	s_mov_b32 m0, s55
	v_lshl_add_u64 v[168:169], v[218:219], 0, s[16:17]
	global_load_lds_dwordx4 v[168:169], off
	s_mov_b32 m0, s56
	v_lshl_add_u64 v[168:169], v[220:221], 0, s[16:17]
	global_load_lds_dwordx4 v[168:169], off
	ds_read_b128 v[178:181], v173 offset:49152
	ds_read_b128 v[182:185], v173 offset:50176
	ds_read_b128 v[186:189], v173 offset:51200
	ds_read_b128 v[194:197], v173 offset:52224
	ds_read_b128 v[202:205], v173 offset:53248
	ds_read_b128 v[206:209], v173 offset:54272
	ds_read_b128 v[210:213], v173 offset:55296
	ds_read_b128 v[214:217], v173 offset:56320
	s_waitcnt vmcnt(8)
	s_waitcnt lgkmcnt(0)
	s_barrier
; #define PG8_STAGE(bufoff, gbase, voff) do { _Pragma("unroll") for (int _i = 0; _i < 2; ++_i) \
;         __builtin_amdgcn_global_load_lds((const unsigned*)((const char*)(gbase) + (voff)[_i]), (PG8_LAS unsigned*)(lds + (bufoff) + ldsw + _i * 8192), 16, 0, 0); } while (0)
; #define PG8_LDA(dst, b, h) do { _Pragma("unroll") for (int m = 0; m < 4; ++m) _Pragma("unroll") for (int k = 0; k < 2; ++k) dst[m][k] = *(const PG8_LAS bf16x8*)(lds + PG8_SA(b, h) + aoff + m * 2048 + k * 1024); } while (0)
; #define PG8_LDB(dst, b, h) do { _Pragma("unroll") for (int n = 0; n < 2; ++n) _Pragma("unroll") for (int k = 0; k < 2; ++k) dst[n][k] = *(const PG8_LAS bf16x8*)(lds + PG8_SB(b, h) + boff + n * 2048 + k * 1024); } while (0)
; #define PG8_MMA(ai, bj, At, Bt) do { __builtin_amdgcn_s_setprio(1); _Pragma("unroll") for (int m = 0; m < 4; ++m) _Pragma("unroll") for (int n = 0; n < 2; ++n) _Pragma("unroll") for (int k = 0; k < 2; ++k) \
;         acc[ai][bj][m][n] = __builtin_amdgcn_mfma_f32_16x16x32_bf16(Bt[n][k], At[m][k], acc[ai][bj][m][n], 0, 0, 0); __builtin_amdgcn_s_setprio(0); } while (0)
; #define PG8_WAIT_V(n) asm volatile("s_waitcnt vmcnt(" #n ")" ::: "memory")
; template <class Epi, class Sched, bool ALIGN_EPI = false, bool SP2 = false>
; __device__ __forceinline__ void gemm_phase(PG8_LAS unsigned char* lds, const Gemm g, const Sched& S, const Epi& E) {
;     ...
;             PG8_LDB(B0, 0, 0); PG8_LDB(B1, 0, 1); PG8_SCHED; PG8_LDA(At, 0, 0); PG8_STAGE(PG8_SA(1, 1), a1 + hstep, voffA);
;             PG8_WAIT_V(8); PG8_WAIT_L(0); PG8_BAR; PG8_MMA(0, 0, At, B0); PG8_MMA(0, 1, At, B1); PG8_BAR; PG8_SCHED;
;             PG8_LDA(At, 0, 1); PG8_STAGE(PG8_SB(0, 0), b2, voffB); PG8_STAGE(PG8_SB(0, 1), b2 + hstep, voffB); PG8_STAGE(PG8_SA(0, 0), a2, voffA);
;             PG8_WAIT_V(8); PG8_WAIT_L(0); PG8_BAR; PG8_MMA(1, 0, At, B0); PG8_MMA(1, 1, At, B1); PG8_BAR; PG8_SCHED;
;             PG8_LDB(B0, 1, 0); PG8_LDB(B1, 1, 1); PG8_SCHED; PG8_LDA(At, 1, 0); PG8_STAGE(PG8_SA(0, 1), a2 + hstep, voffA);
;             PG8_WAIT_V(8); PG8_WAIT_L(0); PG8_BAR; PG8_MMA(0, 0, At, B0); PG8_MMA(0, 1, At, B1); PG8_BAR; PG8_SCHED;
;             PG8_LDA(At, 1, 1); PG8_STAGE(PG8_SB(1, 0), b3, voffB); PG8_STAGE(PG8_SB(1, 1), b3 + hstep, voffB); PG8_STAGE(PG8_SA(1, 0), a3, voffA);
;             PG8_WAIT_V(8); PG8_WAIT_L(0); PG8_BAR; PG8_MMA(1, 0, At, B0); PG8_MMA(1, 1, At, B1); PG8_BAR; PG8_SCHED;
	s_setprio 1
	s_waitcnt lgkmcnt(0)
	v_mfma_f32_16x16x32_bf16 v[60:63], v[128:131], v[178:181], v[60:63]
	v_mfma_f32_16x16x32_bf16 v[56:59], v[136:139], v[178:181], v[56:59]
	v_mfma_f32_16x16x32_bf16 v[44:47], v[128:131], v[186:189], v[44:47]
	v_mfma_f32_16x16x32_bf16 v[40:43], v[136:139], v[186:189], v[40:43]
	v_mfma_f32_16x16x32_bf16 v[28:31], v[128:131], v[202:205], v[28:31]
	v_mfma_f32_16x16x32_bf16 v[24:27], v[136:139], v[202:205], v[24:27]
	v_mfma_f32_16x16x32_bf16 v[12:15], v[128:131], v[210:213], v[12:15]
	v_mfma_f32_16x16x32_bf16 v[8:11], v[136:139], v[210:213], v[8:11]
	v_mfma_f32_16x16x32_bf16 v[60:63], v[132:135], v[182:185], v[60:63]
	v_mfma_f32_16x16x32_bf16 v[56:59], v[140:143], v[182:185], v[56:59]
	v_mfma_f32_16x16x32_bf16 v[44:47], v[132:135], v[194:197], v[44:47]
	v_mfma_f32_16x16x32_bf16 v[40:43], v[140:143], v[194:197], v[40:43]
	v_mfma_f32_16x16x32_bf16 v[28:31], v[132:135], v[206:209], v[28:31]
	v_mfma_f32_16x16x32_bf16 v[24:27], v[140:143], v[206:209], v[24:27]
	v_mfma_f32_16x16x32_bf16 v[12:15], v[132:135], v[214:217], v[12:15]
	v_mfma_f32_16x16x32_bf16 v[8:11], v[140:143], v[214:217], v[8:11]
	s_setprio 0
	s_setprio 1
	v_mfma_f32_16x16x32_bf16 v[52:55], v[144:147], v[178:181], v[52:55]
	v_mfma_f32_16x16x32_bf16 v[48:51], v[164:167], v[178:181], v[48:51]
	v_mfma_f32_16x16x32_bf16 v[36:39], v[144:147], v[186:189], v[36:39]
	v_mfma_f32_16x16x32_bf16 v[32:35], v[164:167], v[186:189], v[32:35]
	v_mfma_f32_16x16x32_bf16 v[20:23], v[144:147], v[202:205], v[20:23]
	v_mfma_f32_16x16x32_bf16 v[16:19], v[164:167], v[202:205], v[16:19]
	v_mfma_f32_16x16x32_bf16 v[4:7], v[144:147], v[210:213], v[4:7]
	v_mfma_f32_16x16x32_bf16 v[0:3], v[164:167], v[210:213], v[0:3]
	v_mfma_f32_16x16x32_bf16 v[52:55], v[148:151], v[182:185], v[52:55]
	v_mfma_f32_16x16x32_bf16 v[48:51], v[174:177], v[182:185], v[48:51]
	v_mfma_f32_16x16x32_bf16 v[36:39], v[148:151], v[194:197], v[36:39]
	v_mfma_f32_16x16x32_bf16 v[32:35], v[174:177], v[194:197], v[32:35]
	v_mfma_f32_16x16x32_bf16 v[20:23], v[148:151], v[206:209], v[20:23]
	v_mfma_f32_16x16x32_bf16 v[16:19], v[174:177], v[206:209], v[16:19]
	v_mfma_f32_16x16x32_bf16 v[4:7], v[148:151], v[214:217], v[4:7]
	v_mfma_f32_16x16x32_bf16 v[0:3], v[174:177], v[214:217], v[0:3]
	s_setprio 0
	s_barrier
	s_add_i32 s65, s65, 2
	s_add_u32 s36, s36, 0x100
	s_addc_u32 s37, s37, 0
	s_add_u32 s63, s63, 0x100
	s_addc_u32 s64, s64, 0
	s_cmp_gt_u32 s65, 29
	s_branch .LBB0_635
.LBB0_635:
	v_add_u32_e32 v140, 0x10000, v172
	v_add_u32_e32 v168, 0x14000, v172
	ds_read_b128 v[128:131], v140
	ds_read_b128 v[132:135], v140 offset:1024
	ds_read_b128 v[136:139], v140 offset:2048
	ds_read_b128 v[140:143], v140 offset:3072
	ds_read_b128 v[144:147], v168
	ds_read_b128 v[148:151], v168 offset:1024
	ds_read_b128 v[164:167], v168 offset:2048
	ds_read_b128 v[174:177], v168 offset:3072
	v_lshl_add_u64 v[168:169], s[36:37], 0, v[160:161]
	s_add_i32 m0, s2, 0xc000
	ds_read_b128 v[178:181], v173
	ds_read_b128 v[182:185], v173 offset:1024
	ds_read_b128 v[186:189], v173 offset:2048
	ds_read_b128 v[194:197], v173 offset:3072
	ds_read_b128 v[202:205], v173 offset:4096
	ds_read_b128 v[206:209], v173 offset:5120
	ds_read_b128 v[210:213], v173 offset:6144
	ds_read_b128 v[214:217], v173 offset:7168
	global_load_lds_dwordx4 v[168:169], off
	s_add_i32 m0, s2, 0xe000
	v_lshl_add_u64 v[168:169], s[36:37], 0, v[162:163]
	global_load_lds_dwordx4 v[168:169], off
	s_add_u32 s24, s36, 0xfff80080
	s_addc_u32 s25, s37, -1
	s_add_i32 s33, 0, 0x10000
	s_cmp_eq_u32 s65, 28
	s_cselect_b32 s43, s15, s25
	s_cselect_b32 s42, s61, s24
	s_cselect_b32 s39, s13, s64
	s_cselect_b32 s38, s62, s63
	s_add_i32 s24, 0, 0x14000
	s_waitcnt vmcnt(8)
	s_waitcnt lgkmcnt(0)
	s_barrier
	s_setprio 1
	s_waitcnt lgkmcnt(0)
	v_mfma_f32_16x16x32_bf16 v[124:127], v[128:131], v[178:181], v[124:127]
	v_mfma_f32_16x16x32_bf16 v[120:123], v[136:139], v[178:181], v[120:123]
	v_mfma_f32_16x16x32_bf16 v[108:111], v[128:131], v[186:189], v[108:111]
	v_mfma_f32_16x16x32_bf16 v[104:107], v[136:139], v[186:189], v[104:107]
	v_mfma_f32_16x16x32_bf16 v[92:95], v[128:131], v[202:205], v[92:95]
	v_mfma_f32_16x16x32_bf16 v[88:91], v[136:139], v[202:205], v[88:91]
	v_mfma_f32_16x16x32_bf16 v[76:79], v[128:131], v[210:213], v[76:79]
	v_mfma_f32_16x16x32_bf16 v[72:75], v[136:139], v[210:213], v[72:75]
	v_mfma_f32_16x16x32_bf16 v[124:127], v[132:135], v[182:185], v[124:127]
	v_mfma_f32_16x16x32_bf16 v[120:123], v[140:143], v[182:185], v[120:123]
	v_mfma_f32_16x16x32_bf16 v[108:111], v[132:135], v[194:197], v[108:111]
	v_mfma_f32_16x16x32_bf16 v[104:107], v[140:143], v[194:197], v[104:107]
	v_mfma_f32_16x16x32_bf16 v[92:95], v[132:135], v[206:209], v[92:95]
	v_mfma_f32_16x16x32_bf16 v[88:91], v[140:143], v[206:209], v[88:91]
	v_mfma_f32_16x16x32_bf16 v[76:79], v[132:135], v[214:217], v[76:79]
	v_mfma_f32_16x16x32_bf16 v[72:75], v[140:143], v[214:217], v[72:75]
	s_setprio 0
	s_setprio 1
	v_mfma_f32_16x16x32_bf16 v[116:119], v[144:147], v[178:181], v[116:119]
	v_mfma_f32_16x16x32_bf16 v[112:115], v[164:167], v[178:181], v[112:115]
	v_mfma_f32_16x16x32_bf16 v[100:103], v[144:147], v[186:189], v[100:103]
	v_mfma_f32_16x16x32_bf16 v[96:99], v[164:167], v[186:189], v[96:99]
	v_mfma_f32_16x16x32_bf16 v[84:87], v[144:147], v[202:205], v[84:87]
	v_mfma_f32_16x16x32_bf16 v[80:83], v[164:167], v[202:205], v[80:83]
	v_mfma_f32_16x16x32_bf16 v[68:71], v[144:147], v[210:213], v[68:71]
	v_mfma_f32_16x16x32_bf16 v[64:67], v[164:167], v[210:213], v[64:67]
	v_mfma_f32_16x16x32_bf16 v[116:119], v[148:151], v[182:185], v[116:119]
	v_mfma_f32_16x16x32_bf16 v[112:115], v[174:177], v[182:185], v[112:115]
	v_mfma_f32_16x16x32_bf16 v[100:103], v[148:151], v[194:197], v[100:103]
	v_mfma_f32_16x16x32_bf16 v[96:99], v[174:177], v[194:197], v[96:99]
	v_mfma_f32_16x16x32_bf16 v[84:87], v[148:151], v[206:209], v[84:87]
	v_mfma_f32_16x16x32_bf16 v[80:83], v[174:177], v[206:209], v[80:83]
	v_mfma_f32_16x16x32_bf16 v[68:71], v[148:151], v[214:217], v[68:71]
	v_mfma_f32_16x16x32_bf16 v[64:67], v[174:177], v[214:217], v[64:67]
	s_setprio 0
	s_barrier
; #define PG8_STAGE(bufoff, gbase, voff) do { _Pragma("unroll") for (int _i = 0; _i < 2; ++_i) \
;         __builtin_amdgcn_global_load_lds((const unsigned*)((const char*)(gbase) + (voff)[_i]), (PG8_LAS unsigned*)(lds + (bufoff) + ldsw + _i * 8192), 16, 0, 0); } while (0)
; #define PG8_LDA(dst, b, h) do { _Pragma("unroll") for (int m = 0; m < 4; ++m) _Pragma("unroll") for (int k = 0; k < 2; ++k) dst[m][k] = *(const PG8_LAS bf16x8*)(lds + PG8_SA(b, h) + aoff + m * 2048 + k * 1024); } while (0)
; #define PG8_LDB(dst, b, h) do { _Pragma("unroll") for (int n = 0; n < 2; ++n) _Pragma("unroll") for (int k = 0; k < 2; ++k) dst[n][k] = *(const PG8_LAS bf16x8*)(lds + PG8_SB(b, h) + boff + n * 2048 + k * 1024); } while (0)
; #define PG8_MMA(ai, bj, At, Bt) do { __builtin_amdgcn_s_setprio(1); _Pragma("unroll") for (int m = 0; m < 4; ++m) _Pragma("unroll") for (int n = 0; n < 2; ++n) _Pragma("unroll") for (int k = 0; k < 2; ++k) \
;         acc[ai][bj][m][n] = __builtin_amdgcn_mfma_f32_16x16x32_bf16(Bt[n][k], At[m][k], acc[ai][bj][m][n], 0, 0, 0); __builtin_amdgcn_s_setprio(0); } while (0)
; #define PG8_WAIT_V(n) asm volatile("s_waitcnt vmcnt(" #n ")" ::: "memory")
; #define PG8_WAIT_L(n) asm volatile("s_waitcnt lgkmcnt(" #n ")" ::: "memory")
; #define PG8_BAR __builtin_amdgcn_s_barrier()
; #define PG8_SCHED __builtin_amdgcn_sched_barrier(0)
; template <class Epi, class Sched, bool ALIGN_EPI = false, bool SP2 = false>
; __device__ __forceinline__ void gemm_phase(PG8_LAS unsigned char* lds, const Gemm g, const Sched& S, const Epi& E) {
;     ...
;             PG8_LDA(At, 0, 1); PG8_STAGE(PG8_SB(0, 0), b2, voffB); PG8_STAGE(PG8_SB(0, 1), b2 + hstep, voffB); PG8_STAGE(PG8_SA(0, 0), a2, voffA);
;             PG8_WAIT_V(8); PG8_WAIT_L(0); PG8_BAR; PG8_MMA(1, 0, At, B0); PG8_MMA(1, 1, At, B1); PG8_BAR; PG8_SCHED;
;             PG8_LDB(B0, 1, 0); PG8_LDB(B1, 1, 1); PG8_SCHED; PG8_LDA(At, 1, 0); PG8_STAGE(PG8_SA(0, 1), a2 + hstep, voffA);
;             PG8_WAIT_V(8); PG8_WAIT_L(0); PG8_BAR; PG8_MMA(0, 0, At, B0); PG8_MMA(0, 1, At, B1); PG8_BAR; PG8_SCHED;
	s_add_i32 s25, s33, s47
	v_lshl_add_u64 v[168:169], s[38:39], 0, v[156:157]
	s_mov_b32 m0, s25
	s_nop 0
	global_load_lds_dwordx4 v[168:169], off
	s_add_i32 m0, s25, 0x2000
	s_add_u32 s66, s38, 0x80000
	v_lshl_add_u64 v[190:191], s[38:39], 0, v[152:153]
	s_addc_u32 s67, s39, 0
	s_add_i32 s24, s24, s47
	global_load_lds_dwordx4 v[190:191], off
	v_lshl_add_u64 v[218:219], s[66:67], 0, v[156:157]
	s_mov_b32 m0, s24
	v_lshl_add_u64 v[220:221], s[42:43], 0, v[154:155]
	global_load_lds_dwordx4 v[218:219], off
	s_add_i32 m0, s24, 0x2000
	v_lshl_add_u64 v[218:219], s[66:67], 0, v[152:153]
	global_load_lds_dwordx4 v[218:219], off
	s_mov_b32 m0, s2
	v_lshl_add_u64 v[218:219], s[42:43], 0, v[158:159]
	global_load_lds_dwordx4 v[218:219], off
	s_mov_b32 m0, s48
	s_nop 0
	global_load_lds_dwordx4 v[220:221], off
	ds_read_b128 v[178:181], v173 offset:16384
	ds_read_b128 v[182:185], v173 offset:17408
	ds_read_b128 v[186:189], v173 offset:18432
	ds_read_b128 v[194:197], v173 offset:19456
	ds_read_b128 v[202:205], v173 offset:20480
	ds_read_b128 v[206:209], v173 offset:21504
	ds_read_b128 v[210:213], v173 offset:22528
	ds_read_b128 v[214:217], v173 offset:23552
	s_waitcnt vmcnt(8)
	s_waitcnt lgkmcnt(0)
	s_barrier
	s_setprio 1
	s_waitcnt lgkmcnt(0)
	v_mfma_f32_16x16x32_bf16 v[60:63], v[128:131], v[178:181], v[60:63]
	v_mfma_f32_16x16x32_bf16 v[56:59], v[136:139], v[178:181], v[56:59]
	v_mfma_f32_16x16x32_bf16 v[44:47], v[128:131], v[186:189], v[44:47]
	v_mfma_f32_16x16x32_bf16 v[40:43], v[136:139], v[186:189], v[40:43]
	v_mfma_f32_16x16x32_bf16 v[28:31], v[128:131], v[202:205], v[28:31]
	v_mfma_f32_16x16x32_bf16 v[24:27], v[136:139], v[202:205], v[24:27]
	v_mfma_f32_16x16x32_bf16 v[12:15], v[128:131], v[210:213], v[12:15]
	v_mfma_f32_16x16x32_bf16 v[8:11], v[136:139], v[210:213], v[8:11]
	v_mfma_f32_16x16x32_bf16 v[60:63], v[132:135], v[182:185], v[60:63]
	v_mfma_f32_16x16x32_bf16 v[56:59], v[140:143], v[182:185], v[56:59]
	v_mfma_f32_16x16x32_bf16 v[44:47], v[132:135], v[194:197], v[44:47]
	v_mfma_f32_16x16x32_bf16 v[40:43], v[140:143], v[194:197], v[40:43]
	v_mfma_f32_16x16x32_bf16 v[28:31], v[132:135], v[206:209], v[28:31]
	v_mfma_f32_16x16x32_bf16 v[24:27], v[140:143], v[206:209], v[24:27]
	v_mfma_f32_16x16x32_bf16 v[12:15], v[132:135], v[214:217], v[12:15]
	v_mfma_f32_16x16x32_bf16 v[8:11], v[140:143], v[214:217], v[8:11]
	s_setprio 0
	s_setprio 1
	v_mfma_f32_16x16x32_bf16 v[52:55], v[144:147], v[178:181], v[52:55]
	v_mfma_f32_16x16x32_bf16 v[48:51], v[164:167], v[178:181], v[48:51]
	v_mfma_f32_16x16x32_bf16 v[36:39], v[144:147], v[186:189], v[36:39]
	v_mfma_f32_16x16x32_bf16 v[32:35], v[164:167], v[186:189], v[32:35]
	v_mfma_f32_16x16x32_bf16 v[20:23], v[144:147], v[202:205], v[20:23]
	v_mfma_f32_16x16x32_bf16 v[16:19], v[164:167], v[202:205], v[16:19]
	v_mfma_f32_16x16x32_bf16 v[4:7], v[144:147], v[210:213], v[4:7]
	v_mfma_f32_16x16x32_bf16 v[0:3], v[164:167], v[210:213], v[0:3]
	v_mfma_f32_16x16x32_bf16 v[52:55], v[148:151], v[182:185], v[52:55]
	v_mfma_f32_16x16x32_bf16 v[48:51], v[174:177], v[182:185], v[48:51]
	v_mfma_f32_16x16x32_bf16 v[36:39], v[148:151], v[194:197], v[36:39]
	v_mfma_f32_16x16x32_bf16 v[32:35], v[174:177], v[194:197], v[32:35]
	v_mfma_f32_16x16x32_bf16 v[20:23], v[148:151], v[206:209], v[20:23]
	v_mfma_f32_16x16x32_bf16 v[16:19], v[174:177], v[206:209], v[16:19]
	v_mfma_f32_16x16x32_bf16 v[4:7], v[148:151], v[214:217], v[4:7]
	v_mfma_f32_16x16x32_bf16 v[0:3], v[174:177], v[214:217], v[0:3]
	s_setprio 0
	s_barrier
	s_add_i32 s24, 0, 0x18000
	s_add_i32 s25, 0, 0x1c000
	s_add_u32 s42, s42, 0x80000
	s_addc_u32 s43, s43, 0
	s_mov_b32 m0, s49
	v_lshl_add_u64 v[230:231], s[42:43], 0, v[158:159]
	global_load_lds_dwordx4 v[230:231], off
	s_mov_b32 m0, s50
	v_lshl_add_u64 v[230:231], s[42:43], 0, v[154:155]
	global_load_lds_dwordx4 v[230:231], off
	v_add_u32_e32 v140, 0x18000, v172
	v_add_u32_e32 v174, 0x1c000, v172
	ds_read_b128 v[128:131], v140
	ds_read_b128 v[132:135], v140 offset:1024
	ds_read_b128 v[136:139], v140 offset:2048
	ds_read_b128 v[140:143], v140 offset:3072
	ds_read_b128 v[144:147], v174
	ds_read_b128 v[148:151], v174 offset:1024
	ds_read_b128 v[164:167], v174 offset:2048
	ds_read_b128 v[174:177], v174 offset:3072
	ds_read_b128 v[178:181], v173 offset:32768
	ds_read_b128 v[182:185], v173 offset:33792
	ds_read_b128 v[186:189], v173 offset:34816
	ds_read_b128 v[194:197], v173 offset:35840
	ds_read_b128 v[202:205], v173 offset:36864
	ds_read_b128 v[206:209], v173 offset:37888
	ds_read_b128 v[210:213], v173 offset:38912
	ds_read_b128 v[214:217], v173 offset:39936
	s_waitcnt vmcnt(8)
	s_waitcnt lgkmcnt(0)
	s_barrier
; #define PG8_STAGE(bufoff, gbase, voff) do { _Pragma("unroll") for (int _i = 0; _i < 2; ++_i) \
;         __builtin_amdgcn_global_load_lds((const unsigned*)((const char*)(gbase) + (voff)[_i]), (PG8_LAS unsigned*)(lds + (bufoff) + ldsw + _i * 8192), 16, 0, 0); } while (0)
; #define PG8_LDA(dst, b, h) do { _Pragma("unroll") for (int m = 0; m < 4; ++m) _Pragma("unroll") for (int k = 0; k < 2; ++k) dst[m][k] = *(const PG8_LAS bf16x8*)(lds + PG8_SA(b, h) + aoff + m * 2048 + k * 1024); } while (0)
; #define PG8_LDB(dst, b, h) do { _Pragma("unroll") for (int n = 0; n < 2; ++n) _Pragma("unroll") for (int k = 0; k < 2; ++k) dst[n][k] = *(const PG8_LAS bf16x8*)(lds + PG8_SB(b, h) + boff + n * 2048 + k * 1024); } while (0)
; #define PG8_MMA(ai, bj, At, Bt) do { __builtin_amdgcn_s_setprio(1); _Pragma("unroll") for (int m = 0; m < 4; ++m) _Pragma("unroll") for (int n = 0; n < 2; ++n) _Pragma("unroll") for (int k = 0; k < 2; ++k) \
;         acc[ai][bj][m][n] = __builtin_amdgcn_mfma_f32_16x16x32_bf16(Bt[n][k], At[m][k], acc[ai][bj][m][n], 0, 0, 0); __builtin_amdgcn_s_setprio(0); } while (0)
; #define PG8_WAIT_V(n) asm volatile("s_waitcnt vmcnt(" #n ")" ::: "memory")
; #define PG8_WAIT_L(n) asm volatile("s_waitcnt lgkmcnt(" #n ")" ::: "memory")
; #define PG8_BAR __builtin_amdgcn_s_barrier()
; #define PG8_SCHED __builtin_amdgcn_sched_barrier(0)
; template <class Epi, class Sched, bool ALIGN_EPI = false, bool SP2 = false>
; __device__ __forceinline__ void gemm_phase(PG8_LAS unsigned char* lds, const Gemm g, const Sched& S, const Epi& E) {
;     ...
;             PG8_LDB(B0, 1, 0); PG8_LDB(B1, 1, 1); PG8_SCHED; PG8_LDA(At, 1, 0); PG8_STAGE(PG8_SA(0, 1), a2 + hstep, voffA);
;             PG8_WAIT_V(8); PG8_WAIT_L(0); PG8_BAR; PG8_MMA(0, 0, At, B0); PG8_MMA(0, 1, At, B1); PG8_BAR; PG8_SCHED;
;             PG8_LDA(At, 1, 1); PG8_STAGE(PG8_SB(1, 0), b3, voffB); PG8_STAGE(PG8_SB(1, 1), b3 + hstep, voffB); PG8_STAGE(PG8_SA(1, 0), a3, voffA);
;             PG8_WAIT_V(8); PG8_WAIT_L(0); PG8_BAR; PG8_MMA(1, 0, At, B0); PG8_MMA(1, 1, At, B1); PG8_BAR; PG8_SCHED;
;     ...
;         if constexpr (ALIGN_EPI) { if (wr == 0) PG8_BAR; }
	s_setprio 1
	s_waitcnt lgkmcnt(0)
	v_mfma_f32_16x16x32_bf16 v[124:127], v[128:131], v[178:181], v[124:127]
	v_mfma_f32_16x16x32_bf16 v[120:123], v[136:139], v[178:181], v[120:123]
	v_mfma_f32_16x16x32_bf16 v[108:111], v[128:131], v[186:189], v[108:111]
	v_mfma_f32_16x16x32_bf16 v[104:107], v[136:139], v[186:189], v[104:107]
	v_mfma_f32_16x16x32_bf16 v[92:95], v[128:131], v[202:205], v[92:95]
	v_mfma_f32_16x16x32_bf16 v[88:91], v[136:139], v[202:205], v[88:91]
	v_mfma_f32_16x16x32_bf16 v[76:79], v[128:131], v[210:213], v[76:79]
	v_mfma_f32_16x16x32_bf16 v[72:75], v[136:139], v[210:213], v[72:75]
	v_mfma_f32_16x16x32_bf16 v[124:127], v[132:135], v[182:185], v[124:127]
	v_mfma_f32_16x16x32_bf16 v[120:123], v[140:143], v[182:185], v[120:123]
	v_mfma_f32_16x16x32_bf16 v[108:111], v[132:135], v[194:197], v[108:111]
	v_mfma_f32_16x16x32_bf16 v[104:107], v[140:143], v[194:197], v[104:107]
	v_mfma_f32_16x16x32_bf16 v[92:95], v[132:135], v[206:209], v[92:95]
	v_mfma_f32_16x16x32_bf16 v[88:91], v[140:143], v[206:209], v[88:91]
	v_mfma_f32_16x16x32_bf16 v[76:79], v[132:135], v[214:217], v[76:79]
	v_mfma_f32_16x16x32_bf16 v[72:75], v[140:143], v[214:217], v[72:75]
	s_setprio 0
	s_setprio 1
	v_mfma_f32_16x16x32_bf16 v[116:119], v[144:147], v[178:181], v[116:119]
	v_mfma_f32_16x16x32_bf16 v[112:115], v[164:167], v[178:181], v[112:115]
	v_mfma_f32_16x16x32_bf16 v[100:103], v[144:147], v[186:189], v[100:103]
	v_mfma_f32_16x16x32_bf16 v[96:99], v[164:167], v[186:189], v[96:99]
	v_mfma_f32_16x16x32_bf16 v[84:87], v[144:147], v[202:205], v[84:87]
	v_mfma_f32_16x16x32_bf16 v[80:83], v[164:167], v[202:205], v[80:83]
	v_mfma_f32_16x16x32_bf16 v[68:71], v[144:147], v[210:213], v[68:71]
	v_mfma_f32_16x16x32_bf16 v[64:67], v[164:167], v[210:213], v[64:67]
	v_mfma_f32_16x16x32_bf16 v[116:119], v[148:151], v[182:185], v[116:119]
	v_mfma_f32_16x16x32_bf16 v[112:115], v[174:177], v[182:185], v[112:115]
	v_mfma_f32_16x16x32_bf16 v[100:103], v[148:151], v[194:197], v[100:103]
	v_mfma_f32_16x16x32_bf16 v[96:99], v[174:177], v[194:197], v[96:99]
	v_mfma_f32_16x16x32_bf16 v[84:87], v[148:151], v[206:209], v[84:87]
	v_mfma_f32_16x16x32_bf16 v[80:83], v[174:177], v[206:209], v[80:83]
	v_mfma_f32_16x16x32_bf16 v[68:71], v[148:151], v[214:217], v[68:71]
	v_mfma_f32_16x16x32_bf16 v[64:67], v[174:177], v[214:217], v[64:67]
	s_setprio 0
	s_barrier
	s_add_i32 s24, s24, s47
	v_lshl_add_u64 v[168:169], v[168:169], 0, s[16:17]
	s_mov_b32 m0, s24
	s_nop 0
	global_load_lds_dwordx4 v[168:169], off
	s_add_i32 m0, s24, 0x2000
	s_add_u32 s38, s38, 0x80080
	v_lshl_add_u64 v[168:169], v[190:191], 0, s[16:17]
	s_addc_u32 s39, s39, 0
	s_add_i32 s24, s25, s47
	global_load_lds_dwordx4 v[168:169], off
	s_mov_b32 m0, s24
	v_lshl_add_u64 v[168:169], s[38:39], 0, v[156:157]
	global_load_lds_dwordx4 v[168:169], off
	s_add_i32 m0, s24, 0x2000
	v_lshl_add_u64 v[168:169], s[38:39], 0, v[152:153]
	global_load_lds_dwordx4 v[168:169], off
	s_mov_b32 m0, s55
	v_lshl_add_u64 v[168:169], v[218:219], 0, s[16:17]
	global_load_lds_dwordx4 v[168:169], off
	s_mov_b32 m0, s56
	v_lshl_add_u64 v[168:169], v[220:221], 0, s[16:17]
	global_load_lds_dwordx4 v[168:169], off
	ds_read_b128 v[178:181], v173 offset:49152
	ds_read_b128 v[182:185], v173 offset:50176
	ds_read_b128 v[186:189], v173 offset:51200
	ds_read_b128 v[194:197], v173 offset:52224
	ds_read_b128 v[202:205], v173 offset:53248
	ds_read_b128 v[206:209], v173 offset:54272
	ds_read_b128 v[210:213], v173 offset:55296
	ds_read_b128 v[214:217], v173 offset:56320
	s_waitcnt vmcnt(8)
	s_waitcnt lgkmcnt(0)
	s_barrier
	s_setprio 1
	s_waitcnt lgkmcnt(0)
	v_mfma_f32_16x16x32_bf16 v[60:63], v[128:131], v[178:181], v[60:63]
	v_mfma_f32_16x16x32_bf16 v[56:59], v[136:139], v[178:181], v[56:59]
	v_mfma_f32_16x16x32_bf16 v[44:47], v[128:131], v[186:189], v[44:47]
	v_mfma_f32_16x16x32_bf16 v[40:43], v[136:139], v[186:189], v[40:43]
	v_mfma_f32_16x16x32_bf16 v[28:31], v[128:131], v[202:205], v[28:31]
	v_mfma_f32_16x16x32_bf16 v[24:27], v[136:139], v[202:205], v[24:27]
	v_mfma_f32_16x16x32_bf16 v[12:15], v[128:131], v[210:213], v[12:15]
	v_mfma_f32_16x16x32_bf16 v[8:11], v[136:139], v[210:213], v[8:11]
	v_mfma_f32_16x16x32_bf16 v[60:63], v[132:135], v[182:185], v[60:63]
	v_mfma_f32_16x16x32_bf16 v[56:59], v[140:143], v[182:185], v[56:59]
	v_mfma_f32_16x16x32_bf16 v[44:47], v[132:135], v[194:197], v[44:47]
	v_mfma_f32_16x16x32_bf16 v[40:43], v[140:143], v[194:197], v[40:43]
	v_mfma_f32_16x16x32_bf16 v[28:31], v[132:135], v[206:209], v[28:31]
	v_mfma_f32_16x16x32_bf16 v[24:27], v[140:143], v[206:209], v[24:27]
	v_mfma_f32_16x16x32_bf16 v[12:15], v[132:135], v[214:217], v[12:15]
	v_mfma_f32_16x16x32_bf16 v[8:11], v[140:143], v[214:217], v[8:11]
	s_setprio 0
	s_setprio 1
	v_mfma_f32_16x16x32_bf16 v[52:55], v[144:147], v[178:181], v[52:55]
	v_mfma_f32_16x16x32_bf16 v[48:51], v[164:167], v[178:181], v[48:51]
	v_mfma_f32_16x16x32_bf16 v[36:39], v[144:147], v[186:189], v[36:39]
	v_mfma_f32_16x16x32_bf16 v[32:35], v[164:167], v[186:189], v[32:35]
	v_mfma_f32_16x16x32_bf16 v[20:23], v[144:147], v[202:205], v[20:23]
	v_mfma_f32_16x16x32_bf16 v[16:19], v[164:167], v[202:205], v[16:19]
	v_mfma_f32_16x16x32_bf16 v[4:7], v[144:147], v[210:213], v[4:7]
	v_mfma_f32_16x16x32_bf16 v[0:3], v[164:167], v[210:213], v[0:3]
	v_mfma_f32_16x16x32_bf16 v[52:55], v[148:151], v[182:185], v[52:55]
	v_mfma_f32_16x16x32_bf16 v[48:51], v[174:177], v[182:185], v[48:51]
	v_mfma_f32_16x16x32_bf16 v[36:39], v[148:151], v[194:197], v[36:39]
	v_mfma_f32_16x16x32_bf16 v[32:35], v[174:177], v[194:197], v[32:35]
	v_mfma_f32_16x16x32_bf16 v[20:23], v[148:151], v[206:209], v[20:23]
	v_mfma_f32_16x16x32_bf16 v[16:19], v[174:177], v[206:209], v[16:19]
	v_mfma_f32_16x16x32_bf16 v[4:7], v[148:151], v[214:217], v[4:7]
	v_mfma_f32_16x16x32_bf16 v[0:3], v[174:177], v[214:217], v[0:3]
	s_setprio 0
	s_barrier
	s_add_i32 s65, s65, 2
	s_add_u32 s36, s36, 0x100
	s_addc_u32 s37, s37, 0
	s_add_u32 s63, s63, 0x100
	s_addc_u32 s64, s64, 0
	s_cmp_gt_u32 s65, 29
	s_cbranch_scc0 .LBB0_635
	s_and_b64 vcc, exec, s[10:11]
	s_cbranch_vccz .LBB0_638
	s_barrier

; #define PG8_STAGE(bufoff, gbase, voff) do { _Pragma("unroll") for (int _i = 0; _i < 2; ++_i) \
;         __builtin_amdgcn_global_load_lds((const unsigned*)((const char*)(gbase) + (voff)[_i]), (PG8_LAS unsigned*)(lds + (bufoff) + ldsw + _i * 8192), 16, 0, 0); } while (0)
; #define PG8_LDA(dst, b, h) do { _Pragma("unroll") for (int m = 0; m < 4; ++m) _Pragma("unroll") for (int k = 0; k < 2; ++k) dst[m][k] = *(const PG8_LAS bf16x8*)(lds + PG8_SA(b, h) + aoff + m * 2048 + k * 1024); } while (0)
; #define PG8_LDB(dst, b, h) do { _Pragma("unroll") for (int n = 0; n < 2; ++n) _Pragma("unroll") for (int k = 0; k < 2; ++k) dst[n][k] = *(const PG8_LAS bf16x8*)(lds + PG8_SB(b, h) + boff + n * 2048 + k * 1024); } while (0)
; #define PG8_WAIT_V(n) asm volatile("s_waitcnt vmcnt(" #n ")" ::: "memory")
; #define PG8_WAIT_L(n) asm volatile("s_waitcnt lgkmcnt(" #n ")" ::: "memory")
; #define PG8_BAR __builtin_amdgcn_s_barrier()
; #define PG8_SCHED __builtin_amdgcn_sched_barrier(0)
; template <class Epi, class Sched, bool ALIGN_EPI = false, bool SP2 = false>
; __device__ __forceinline__ void gemm_phase(PG8_LAS unsigned char* lds, const Gemm g, const Sched& S, const Epi& E) {
;     ...
;         const char* nA = has_next ? (const char*)g.A + (size_t)nxt.pm * tstep : cA; const char* nB = has_next ? (const char*)g.Bt + (size_t)nxt.pn * tstep : cB;
;         for (int t = 0; t < nt; t += 2) {
;             if constexpr (Epi::MID_HOOK) { if (t == Epi::MID_T) E.mid(acc, cur, wr, wc, fr, fq); }
;             const bool last = (t == nt - 2);
;             const char* a1 = cA + (size_t)(t + 1) * kstep;
;             const char* a2 = last ? nA : cA + (size_t)(t + 2) * kstep; const char* b2 = last ? nB : cB + (size_t)(t + 2) * kstep;
;             const char* a3 = a2 + kstep; const char* b3 = b2 + kstep;
;             if (last && has_next) S.a_ready(nxt);
;             if constexpr (SP2) {
;             PG8_LDB(B0, 0, 0); PG8_LDB(B1, 0, 1); PG8_SCHED; PG8_LDA(At, 0, 0); PG8_STAGE(PG8_SA(1, 1), a1 + hstep, voffA);
;             PG8_WAIT_V(8); PG8_WAIT_L(0); PG8_BAR; PG8_MMA(0, 0, At, B0); PG8_MMA(0, 1, At, B1); PG8_BAR; PG8_SCHED;
;             PG8_LDA(At, 0, 1); PG8_STAGE(PG8_SB(0, 0), b2, voffB); PG8_STAGE(PG8_SB(0, 1), b2 + hstep, voffB); PG8_STAGE(PG8_SA(0, 0), a2, voffA);
;             PG8_WAIT_V(8); PG8_WAIT_L(0); PG8_BAR; PG8_MMA(1, 0, At, B0); PG8_MMA(1, 1, At, B1); PG8_BAR; PG8_SCHED;
.LBB0_729:
	s_ashr_i32 s49, s48, 31
	s_lshl_b64 s[12:13], s[48:49], 20
	s_add_u32 s50, s18, s12
	s_addc_u32 s51, s19, s13
	s_and_b64 s[12:13], s[42:43], exec
	s_cselect_b32 s49, s51, s1
	s_cselect_b32 s60, s50, s0
	s_ashr_i32 s47, s46, 31
	s_lshl_b64 s[12:13], s[46:47], 20
	s_add_u32 s52, s14, s12
	s_addc_u32 s53, s15, s13
	s_and_b64 s[12:13], s[42:43], exec
	s_cselect_b32 s47, s53, s11
	s_cselect_b32 s61, s52, s10
	s_add_u32 s0, s0, 0x80080
	s_addc_u32 s1, s1, 0
	s_add_u32 s62, s10, 0x100
	s_addc_u32 s63, s11, 0
	s_mov_b32 s64, -2
	v_lshl_add_u64 v[190:191], s[0:1], 0, v[136:137]
	s_add_i32 m0, s31, 0xc000
	global_load_lds_dwordx4 v[190:191], off
	s_add_i32 m0, s31, 0xe000
	v_lshl_add_u64 v[190:191], s[0:1], 0, v[138:139]
	global_load_lds_dwordx4 v[190:191], off
	s_add_u32 s10, s0, 0xfff80080
	s_addc_u32 s11, s1, -1
	s_add_i32 s24, 0, 0x10000
	s_cmp_eq_u32 s64, 28
	s_cselect_b32 s13, s49, s11
	s_cselect_b32 s12, s60, s10
	s_cselect_b32 s11, s47, s63
	s_cselect_b32 s10, s61, s62
	s_add_i32 s25, 0, 0x14000
	s_waitcnt vmcnt(8)
	s_waitcnt lgkmcnt(0)
	s_barrier
	s_setprio 1
	s_waitcnt lgkmcnt(0)
	v_mfma_f32_16x16x32_bf16 v[124:127], v[140:143], v[178:181], 0
	v_mfma_f32_16x16x32_bf16 v[112:115], v[154:157], v[178:181], 0
	v_mfma_f32_16x16x32_bf16 v[108:111], v[140:143], v[186:189], 0
	v_mfma_f32_16x16x32_bf16 v[100:103], v[154:157], v[186:189], 0
	v_mfma_f32_16x16x32_bf16 v[92:95], v[140:143], v[202:205], 0
	v_mfma_f32_16x16x32_bf16 v[84:87], v[154:157], v[202:205], 0
	v_mfma_f32_16x16x32_bf16 v[76:79], v[140:143], v[210:213], 0
	v_mfma_f32_16x16x32_bf16 v[68:71], v[154:157], v[210:213], 0
	v_mfma_f32_16x16x32_bf16 v[124:127], v[144:147], v[182:185], v[124:127]
	v_mfma_f32_16x16x32_bf16 v[112:115], v[158:161], v[182:185], v[112:115]
	v_mfma_f32_16x16x32_bf16 v[108:111], v[144:147], v[194:197], v[108:111]
	v_mfma_f32_16x16x32_bf16 v[100:103], v[158:161], v[194:197], v[100:103]
	v_mfma_f32_16x16x32_bf16 v[92:95], v[144:147], v[206:209], v[92:95]
	v_mfma_f32_16x16x32_bf16 v[84:87], v[158:161], v[206:209], v[84:87]
	v_mfma_f32_16x16x32_bf16 v[76:79], v[144:147], v[214:217], v[76:79]
	v_mfma_f32_16x16x32_bf16 v[68:71], v[158:161], v[214:217], v[68:71]
	s_setprio 0
	s_setprio 1
	v_mfma_f32_16x16x32_bf16 v[120:123], v[162:165], v[178:181], 0
	v_mfma_f32_16x16x32_bf16 v[116:119], v[170:173], v[178:181], 0
	v_mfma_f32_16x16x32_bf16 v[104:107], v[162:165], v[186:189], 0
	v_mfma_f32_16x16x32_bf16 v[96:99], v[170:173], v[186:189], 0
	v_mfma_f32_16x16x32_bf16 v[88:91], v[162:165], v[202:205], 0
	v_mfma_f32_16x16x32_bf16 v[80:83], v[170:173], v[202:205], 0
	v_mfma_f32_16x16x32_bf16 v[72:75], v[162:165], v[210:213], 0
	v_mfma_f32_16x16x32_bf16 v[64:67], v[170:173], v[210:213], 0
	v_mfma_f32_16x16x32_bf16 v[120:123], v[166:169], v[182:185], v[120:123]
	v_mfma_f32_16x16x32_bf16 v[116:119], v[174:177], v[182:185], v[116:119]
	v_mfma_f32_16x16x32_bf16 v[104:107], v[166:169], v[194:197], v[104:107]
	v_mfma_f32_16x16x32_bf16 v[96:99], v[174:177], v[194:197], v[96:99]
	v_mfma_f32_16x16x32_bf16 v[88:91], v[166:169], v[206:209], v[88:91]
	v_mfma_f32_16x16x32_bf16 v[80:83], v[174:177], v[206:209], v[80:83]
	v_mfma_f32_16x16x32_bf16 v[72:75], v[166:169], v[214:217], v[72:75]
	v_mfma_f32_16x16x32_bf16 v[64:67], v[174:177], v[214:217], v[64:67]
	s_setprio 0
	s_barrier
	s_add_i32 s24, s24, s30
	v_lshl_add_u64 v[190:191], s[10:11], 0, v[132:133]
	s_mov_b32 m0, s24
	s_nop 0
	global_load_lds_dwordx4 v[190:191], off
	s_add_i32 m0, s24, 0x2000
	s_add_u32 s66, s10, 0x80000
	v_lshl_add_u64 v[218:219], s[10:11], 0, v[128:129]
	s_addc_u32 s67, s11, 0
	s_add_i32 s24, s25, s30
	global_load_lds_dwordx4 v[218:219], off
	v_lshl_add_u64 v[220:221], s[66:67], 0, v[132:133]
	s_mov_b32 m0, s24
	v_lshl_add_u64 v[230:231], s[12:13], 0, v[130:131]
	global_load_lds_dwordx4 v[220:221], off
	s_add_i32 m0, s24, 0x2000
	v_lshl_add_u64 v[220:221], s[66:67], 0, v[128:129]
	global_load_lds_dwordx4 v[220:221], off
	s_mov_b32 m0, s31
	v_lshl_add_u64 v[220:221], s[12:13], 0, v[134:135]
	global_load_lds_dwordx4 v[220:221], off
	s_mov_b32 m0, s34
	s_nop 0
	global_load_lds_dwordx4 v[230:231], off
	ds_read_b128 v[178:181], v152 offset:16384
	ds_read_b128 v[182:185], v152 offset:17408
	ds_read_b128 v[186:189], v152 offset:18432
	ds_read_b128 v[194:197], v152 offset:19456
	ds_read_b128 v[202:205], v152 offset:20480
	ds_read_b128 v[206:209], v152 offset:21504
	ds_read_b128 v[210:213], v152 offset:22528
	ds_read_b128 v[214:217], v152 offset:23552
	s_waitcnt vmcnt(8)
	s_waitcnt lgkmcnt(0)
	s_barrier
	s_setprio 1
	s_waitcnt lgkmcnt(0)
	v_mfma_f32_16x16x32_bf16 v[60:63], v[140:143], v[178:181], 0
	v_mfma_f32_16x16x32_bf16 v[52:55], v[154:157], v[178:181], 0
	v_mfma_f32_16x16x32_bf16 v[44:47], v[140:143], v[186:189], 0
	v_mfma_f32_16x16x32_bf16 v[36:39], v[154:157], v[186:189], 0
	v_mfma_f32_16x16x32_bf16 v[28:31], v[140:143], v[202:205], 0
	v_mfma_f32_16x16x32_bf16 v[20:23], v[154:157], v[202:205], 0
	v_mfma_f32_16x16x32_bf16 v[12:15], v[140:143], v[210:213], 0
	v_mfma_f32_16x16x32_bf16 v[4:7], v[154:157], v[210:213], 0
	v_mfma_f32_16x16x32_bf16 v[60:63], v[144:147], v[182:185], v[60:63]
	v_mfma_f32_16x16x32_bf16 v[52:55], v[158:161], v[182:185], v[52:55]
	v_mfma_f32_16x16x32_bf16 v[44:47], v[144:147], v[194:197], v[44:47]
	v_mfma_f32_16x16x32_bf16 v[36:39], v[158:161], v[194:197], v[36:39]
	v_mfma_f32_16x16x32_bf16 v[28:31], v[144:147], v[206:209], v[28:31]
	v_mfma_f32_16x16x32_bf16 v[20:23], v[158:161], v[206:209], v[20:23]
	v_mfma_f32_16x16x32_bf16 v[12:15], v[144:147], v[214:217], v[12:15]
	v_mfma_f32_16x16x32_bf16 v[4:7], v[158:161], v[214:217], v[4:7]
	s_setprio 0
	s_setprio 1
	v_mfma_f32_16x16x32_bf16 v[56:59], v[162:165], v[178:181], 0
	v_mfma_f32_16x16x32_bf16 v[48:51], v[170:173], v[178:181], 0
	v_mfma_f32_16x16x32_bf16 v[40:43], v[162:165], v[186:189], 0
	v_mfma_f32_16x16x32_bf16 v[32:35], v[170:173], v[186:189], 0
	v_mfma_f32_16x16x32_bf16 v[24:27], v[162:165], v[202:205], 0
	v_mfma_f32_16x16x32_bf16 v[16:19], v[170:173], v[202:205], 0
	v_mfma_f32_16x16x32_bf16 v[8:11], v[162:165], v[210:213], 0
	v_mfma_f32_16x16x32_bf16 v[0:3], v[170:173], v[210:213], 0
	v_mfma_f32_16x16x32_bf16 v[56:59], v[166:169], v[182:185], v[56:59]
	v_mfma_f32_16x16x32_bf16 v[48:51], v[174:177], v[182:185], v[48:51]
	v_mfma_f32_16x16x32_bf16 v[40:43], v[166:169], v[194:197], v[40:43]
	v_mfma_f32_16x16x32_bf16 v[32:35], v[174:177], v[194:197], v[32:35]
	v_mfma_f32_16x16x32_bf16 v[24:27], v[166:169], v[206:209], v[24:27]
	v_mfma_f32_16x16x32_bf16 v[16:19], v[174:177], v[206:209], v[16:19]
	v_mfma_f32_16x16x32_bf16 v[8:11], v[166:169], v[214:217], v[8:11]
	v_mfma_f32_16x16x32_bf16 v[0:3], v[174:177], v[214:217], v[0:3]
	s_setprio 0
	s_barrier
; #define PG8_STAGE(bufoff, gbase, voff) do { _Pragma("unroll") for (int _i = 0; _i < 2; ++_i) \
;         __builtin_amdgcn_global_load_lds((const unsigned*)((const char*)(gbase) + (voff)[_i]), (PG8_LAS unsigned*)(lds + (bufoff) + ldsw + _i * 8192), 16, 0, 0); } while (0)
; #define PG8_LDA(dst, b, h) do { _Pragma("unroll") for (int m = 0; m < 4; ++m) _Pragma("unroll") for (int k = 0; k < 2; ++k) dst[m][k] = *(const PG8_LAS bf16x8*)(lds + PG8_SA(b, h) + aoff + m * 2048 + k * 1024); } while (0)
; #define PG8_LDB(dst, b, h) do { _Pragma("unroll") for (int n = 0; n < 2; ++n) _Pragma("unroll") for (int k = 0; k < 2; ++k) dst[n][k] = *(const PG8_LAS bf16x8*)(lds + PG8_SB(b, h) + boff + n * 2048 + k * 1024); } while (0)
; #define PG8_MMA(ai, bj, At, Bt) do { __builtin_amdgcn_s_setprio(1); _Pragma("unroll") for (int m = 0; m < 4; ++m) _Pragma("unroll") for (int n = 0; n < 2; ++n) _Pragma("unroll") for (int k = 0; k < 2; ++k) \
;         acc[ai][bj][m][n] = __builtin_amdgcn_mfma_f32_16x16x32_bf16(Bt[n][k], At[m][k], acc[ai][bj][m][n], 0, 0, 0); __builtin_amdgcn_s_setprio(0); } while (0)
; #define PG8_WAIT_V(n) asm volatile("s_waitcnt vmcnt(" #n ")" ::: "memory")
; #define PG8_WAIT_L(n) asm volatile("s_waitcnt lgkmcnt(" #n ")" ::: "memory")
; #define PG8_BAR __builtin_amdgcn_s_barrier()
; #define PG8_SCHED __builtin_amdgcn_sched_barrier(0)
; template <class Epi, class Sched, bool ALIGN_EPI = false, bool SP2 = false>
; __device__ __forceinline__ void gemm_phase(PG8_LAS unsigned char* lds, const Gemm g, const Sched& S, const Epi& E) {
;     ...
;             PG8_LDB(B0, 1, 0); PG8_LDB(B1, 1, 1); PG8_SCHED; PG8_LDA(At, 1, 0); PG8_STAGE(PG8_SA(0, 1), a2 + hstep, voffA);
;             PG8_WAIT_V(8); PG8_WAIT_L(0); PG8_BAR; PG8_MMA(0, 0, At, B0); PG8_MMA(0, 1, At, B1); PG8_BAR; PG8_SCHED;
;             PG8_LDA(At, 1, 1); PG8_STAGE(PG8_SB(1, 0), b3, voffB); PG8_STAGE(PG8_SB(1, 1), b3 + hstep, voffB); PG8_STAGE(PG8_SA(1, 0), a3, voffA);
;             PG8_WAIT_V(8); PG8_WAIT_L(0); PG8_BAR; PG8_MMA(1, 0, At, B0); PG8_MMA(1, 1, At, B1); PG8_BAR; PG8_SCHED;
	s_add_i32 s24, 0, 0x18000
	s_add_i32 s25, 0, 0x1c000
	s_add_u32 s12, s12, 0x80000
	s_addc_u32 s13, s13, 0
	s_mov_b32 m0, s36
	v_lshl_add_u64 v[232:233], s[12:13], 0, v[134:135]
	global_load_lds_dwordx4 v[232:233], off
	s_mov_b32 m0, s37
	v_lshl_add_u64 v[232:233], s[12:13], 0, v[130:131]
	global_load_lds_dwordx4 v[232:233], off
	v_add_u32_e32 v148, 0x18000, v151
	ds_read_b128 v[140:143], v148
	ds_read_b128 v[144:147], v148 offset:1024
	ds_read_b128 v[154:157], v148 offset:2048
	ds_read_b128 v[158:161], v148 offset:3072
	v_add_u32_e32 v148, 0x1c000, v151
	ds_read_b128 v[162:165], v148
	ds_read_b128 v[166:169], v148 offset:1024
	ds_read_b128 v[170:173], v148 offset:2048
	ds_read_b128 v[174:177], v148 offset:3072
	ds_read_b128 v[178:181], v152 offset:32768
	ds_read_b128 v[182:185], v152 offset:33792
	ds_read_b128 v[186:189], v152 offset:34816
	ds_read_b128 v[194:197], v152 offset:35840
	ds_read_b128 v[202:205], v152 offset:36864
	ds_read_b128 v[206:209], v152 offset:37888
	ds_read_b128 v[210:213], v152 offset:38912
	ds_read_b128 v[214:217], v152 offset:39936
	s_waitcnt vmcnt(8)
	s_waitcnt lgkmcnt(0)
	s_barrier
	s_setprio 1
	s_waitcnt lgkmcnt(0)
	v_mfma_f32_16x16x32_bf16 v[124:127], v[140:143], v[178:181], v[124:127]
	v_mfma_f32_16x16x32_bf16 v[112:115], v[154:157], v[178:181], v[112:115]
	v_mfma_f32_16x16x32_bf16 v[108:111], v[140:143], v[186:189], v[108:111]
	v_mfma_f32_16x16x32_bf16 v[100:103], v[154:157], v[186:189], v[100:103]
	v_mfma_f32_16x16x32_bf16 v[92:95], v[140:143], v[202:205], v[92:95]
	v_mfma_f32_16x16x32_bf16 v[84:87], v[154:157], v[202:205], v[84:87]
	v_mfma_f32_16x16x32_bf16 v[76:79], v[140:143], v[210:213], v[76:79]
	v_mfma_f32_16x16x32_bf16 v[68:71], v[154:157], v[210:213], v[68:71]
	v_mfma_f32_16x16x32_bf16 v[124:127], v[144:147], v[182:185], v[124:127]
	v_mfma_f32_16x16x32_bf16 v[112:115], v[158:161], v[182:185], v[112:115]
	v_mfma_f32_16x16x32_bf16 v[108:111], v[144:147], v[194:197], v[108:111]
	v_mfma_f32_16x16x32_bf16 v[100:103], v[158:161], v[194:197], v[100:103]
	v_mfma_f32_16x16x32_bf16 v[92:95], v[144:147], v[206:209], v[92:95]
	v_mfma_f32_16x16x32_bf16 v[84:87], v[158:161], v[206:209], v[84:87]
	v_mfma_f32_16x16x32_bf16 v[76:79], v[144:147], v[214:217], v[76:79]
	v_mfma_f32_16x16x32_bf16 v[68:71], v[158:161], v[214:217], v[68:71]
	s_setprio 0
	s_setprio 1
	v_mfma_f32_16x16x32_bf16 v[120:123], v[162:165], v[178:181], v[120:123]
	v_mfma_f32_16x16x32_bf16 v[116:119], v[170:173], v[178:181], v[116:119]
	v_mfma_f32_16x16x32_bf16 v[104:107], v[162:165], v[186:189], v[104:107]
	v_mfma_f32_16x16x32_bf16 v[96:99], v[170:173], v[186:189], v[96:99]
	v_mfma_f32_16x16x32_bf16 v[88:91], v[162:165], v[202:205], v[88:91]
	v_mfma_f32_16x16x32_bf16 v[80:83], v[170:173], v[202:205], v[80:83]
	v_mfma_f32_16x16x32_bf16 v[72:75], v[162:165], v[210:213], v[72:75]
	v_mfma_f32_16x16x32_bf16 v[64:67], v[170:173], v[210:213], v[64:67]
	v_mfma_f32_16x16x32_bf16 v[120:123], v[166:169], v[182:185], v[120:123]
	v_mfma_f32_16x16x32_bf16 v[116:119], v[174:177], v[182:185], v[116:119]
	v_mfma_f32_16x16x32_bf16 v[104:107], v[166:169], v[194:197], v[104:107]
	v_mfma_f32_16x16x32_bf16 v[96:99], v[174:177], v[194:197], v[96:99]
	v_mfma_f32_16x16x32_bf16 v[88:91], v[166:169], v[206:209], v[88:91]
	v_mfma_f32_16x16x32_bf16 v[80:83], v[174:177], v[206:209], v[80:83]
	v_mfma_f32_16x16x32_bf16 v[72:75], v[166:169], v[214:217], v[72:75]
	v_mfma_f32_16x16x32_bf16 v[64:67], v[174:177], v[214:217], v[64:67]
	s_setprio 0
	s_barrier
	s_add_i32 s12, s24, s30
	v_lshl_add_u64 v[190:191], v[190:191], 0, s[16:17]
	s_mov_b32 m0, s12
	s_nop 0
	global_load_lds_dwordx4 v[190:191], off
	s_add_i32 m0, s12, 0x2000
	s_add_u32 s10, s10, 0x80080
	v_lshl_add_u64 v[190:191], v[218:219], 0, s[16:17]
	s_addc_u32 s11, s11, 0
	s_add_i32 s12, s25, s30
	global_load_lds_dwordx4 v[190:191], off
	s_mov_b32 m0, s12
	v_lshl_add_u64 v[190:191], s[10:11], 0, v[132:133]
	global_load_lds_dwordx4 v[190:191], off
	s_add_i32 m0, s12, 0x2000
	v_lshl_add_u64 v[190:191], s[10:11], 0, v[128:129]
	global_load_lds_dwordx4 v[190:191], off
	s_mov_b32 m0, s56
	v_lshl_add_u64 v[190:191], v[220:221], 0, s[16:17]
	global_load_lds_dwordx4 v[190:191], off
	s_mov_b32 m0, s57
	v_lshl_add_u64 v[190:191], v[230:231], 0, s[16:17]
	global_load_lds_dwordx4 v[190:191], off
	ds_read_b128 v[178:181], v152 offset:49152
	ds_read_b128 v[182:185], v152 offset:50176
	ds_read_b128 v[186:189], v152 offset:51200
	ds_read_b128 v[194:197], v152 offset:52224
	ds_read_b128 v[202:205], v152 offset:53248
	ds_read_b128 v[206:209], v152 offset:54272
	ds_read_b128 v[210:213], v152 offset:55296
	ds_read_b128 v[214:217], v152 offset:56320
	s_waitcnt vmcnt(8)
	s_waitcnt lgkmcnt(0)
	s_barrier
; #define PG8_STAGE(bufoff, gbase, voff) do { _Pragma("unroll") for (int _i = 0; _i < 2; ++_i) \
;         __builtin_amdgcn_global_load_lds((const unsigned*)((const char*)(gbase) + (voff)[_i]), (PG8_LAS unsigned*)(lds + (bufoff) + ldsw + _i * 8192), 16, 0, 0); } while (0)
; #define PG8_LDA(dst, b, h) do { _Pragma("unroll") for (int m = 0; m < 4; ++m) _Pragma("unroll") for (int k = 0; k < 2; ++k) dst[m][k] = *(const PG8_LAS bf16x8*)(lds + PG8_SA(b, h) + aoff + m * 2048 + k * 1024); } while (0)
; #define PG8_LDB(dst, b, h) do { _Pragma("unroll") for (int n = 0; n < 2; ++n) _Pragma("unroll") for (int k = 0; k < 2; ++k) dst[n][k] = *(const PG8_LAS bf16x8*)(lds + PG8_SB(b, h) + boff + n * 2048 + k * 1024); } while (0)
; #define PG8_MMA(ai, bj, At, Bt) do { __builtin_amdgcn_s_setprio(1); _Pragma("unroll") for (int m = 0; m < 4; ++m) _Pragma("unroll") for (int n = 0; n < 2; ++n) _Pragma("unroll") for (int k = 0; k < 2; ++k) \
;         acc[ai][bj][m][n] = __builtin_amdgcn_mfma_f32_16x16x32_bf16(Bt[n][k], At[m][k], acc[ai][bj][m][n], 0, 0, 0); __builtin_amdgcn_s_setprio(0); } while (0)
; #define PG8_WAIT_V(n) asm volatile("s_waitcnt vmcnt(" #n ")" ::: "memory")
; template <class Epi, class Sched, bool ALIGN_EPI = false, bool SP2 = false>
; __device__ __forceinline__ void gemm_phase(PG8_LAS unsigned char* lds, const Gemm g, const Sched& S, const Epi& E) {
;     ...
;             PG8_LDB(B0, 0, 0); PG8_LDB(B1, 0, 1); PG8_SCHED; PG8_LDA(At, 0, 0); PG8_STAGE(PG8_SA(1, 1), a1 + hstep, voffA);
;             PG8_WAIT_V(8); PG8_WAIT_L(0); PG8_BAR; PG8_MMA(0, 0, At, B0); PG8_MMA(0, 1, At, B1); PG8_BAR; PG8_SCHED;
;             PG8_LDA(At, 0, 1); PG8_STAGE(PG8_SB(0, 0), b2, voffB); PG8_STAGE(PG8_SB(0, 1), b2 + hstep, voffB); PG8_STAGE(PG8_SA(0, 0), a2, voffA);
;             PG8_WAIT_V(8); PG8_WAIT_L(0); PG8_BAR; PG8_MMA(1, 0, At, B0); PG8_MMA(1, 1, At, B1); PG8_BAR; PG8_SCHED;
;             PG8_LDB(B0, 1, 0); PG8_LDB(B1, 1, 1); PG8_SCHED; PG8_LDA(At, 1, 0); PG8_STAGE(PG8_SA(0, 1), a2 + hstep, voffA);
;             PG8_WAIT_V(8); PG8_WAIT_L(0); PG8_BAR; PG8_MMA(0, 0, At, B0); PG8_MMA(0, 1, At, B1); PG8_BAR; PG8_SCHED;
;             PG8_LDA(At, 1, 1); PG8_STAGE(PG8_SB(1, 0), b3, voffB); PG8_STAGE(PG8_SB(1, 1), b3 + hstep, voffB); PG8_STAGE(PG8_SA(1, 0), a3, voffA);
;             PG8_WAIT_V(8); PG8_WAIT_L(0); PG8_BAR; PG8_MMA(1, 0, At, B0); PG8_MMA(1, 1, At, B1); PG8_BAR; PG8_SCHED;
	s_setprio 1
	s_waitcnt lgkmcnt(0)
	v_mfma_f32_16x16x32_bf16 v[60:63], v[140:143], v[178:181], v[60:63]
	v_mfma_f32_16x16x32_bf16 v[52:55], v[154:157], v[178:181], v[52:55]
	v_mfma_f32_16x16x32_bf16 v[44:47], v[140:143], v[186:189], v[44:47]
	v_mfma_f32_16x16x32_bf16 v[36:39], v[154:157], v[186:189], v[36:39]
	v_mfma_f32_16x16x32_bf16 v[28:31], v[140:143], v[202:205], v[28:31]
	v_mfma_f32_16x16x32_bf16 v[20:23], v[154:157], v[202:205], v[20:23]
	v_mfma_f32_16x16x32_bf16 v[12:15], v[140:143], v[210:213], v[12:15]
	v_mfma_f32_16x16x32_bf16 v[4:7], v[154:157], v[210:213], v[4:7]
	v_mfma_f32_16x16x32_bf16 v[60:63], v[144:147], v[182:185], v[60:63]
	v_mfma_f32_16x16x32_bf16 v[52:55], v[158:161], v[182:185], v[52:55]
	v_mfma_f32_16x16x32_bf16 v[44:47], v[144:147], v[194:197], v[44:47]
	v_mfma_f32_16x16x32_bf16 v[36:39], v[158:161], v[194:197], v[36:39]
	v_mfma_f32_16x16x32_bf16 v[28:31], v[144:147], v[206:209], v[28:31]
	v_mfma_f32_16x16x32_bf16 v[20:23], v[158:161], v[206:209], v[20:23]
	v_mfma_f32_16x16x32_bf16 v[12:15], v[144:147], v[214:217], v[12:15]
	v_mfma_f32_16x16x32_bf16 v[4:7], v[158:161], v[214:217], v[4:7]
	s_setprio 0
	s_setprio 1
	v_mfma_f32_16x16x32_bf16 v[56:59], v[162:165], v[178:181], v[56:59]
	v_mfma_f32_16x16x32_bf16 v[48:51], v[170:173], v[178:181], v[48:51]
	v_mfma_f32_16x16x32_bf16 v[40:43], v[162:165], v[186:189], v[40:43]
	v_mfma_f32_16x16x32_bf16 v[32:35], v[170:173], v[186:189], v[32:35]
	v_mfma_f32_16x16x32_bf16 v[24:27], v[162:165], v[202:205], v[24:27]
	v_mfma_f32_16x16x32_bf16 v[16:19], v[170:173], v[202:205], v[16:19]
	v_mfma_f32_16x16x32_bf16 v[8:11], v[162:165], v[210:213], v[8:11]
	v_mfma_f32_16x16x32_bf16 v[0:3], v[170:173], v[210:213], v[0:3]
	v_mfma_f32_16x16x32_bf16 v[56:59], v[166:169], v[182:185], v[56:59]
	v_mfma_f32_16x16x32_bf16 v[48:51], v[174:177], v[182:185], v[48:51]
	v_mfma_f32_16x16x32_bf16 v[40:43], v[166:169], v[194:197], v[40:43]
	v_mfma_f32_16x16x32_bf16 v[32:35], v[174:177], v[194:197], v[32:35]
	v_mfma_f32_16x16x32_bf16 v[24:27], v[166:169], v[206:209], v[24:27]
	v_mfma_f32_16x16x32_bf16 v[16:19], v[174:177], v[206:209], v[16:19]
	v_mfma_f32_16x16x32_bf16 v[8:11], v[166:169], v[214:217], v[8:11]
	v_mfma_f32_16x16x32_bf16 v[0:3], v[174:177], v[214:217], v[0:3]
	s_setprio 0
	s_barrier
	s_add_i32 s64, s64, 2
	s_add_u32 s0, s0, 0x100
	s_addc_u32 s1, s1, 0
	s_add_u32 s62, s62, 0x100
	s_addc_u32 s63, s63, 0
	s_cmp_gt_u32 s64, 29
	s_branch .LBB0_730
.LBB0_730:
	v_lshl_add_u64 v[190:191], s[0:1], 0, v[136:137]
	s_add_i32 m0, s31, 0xc000
	s_nop 0
	global_load_lds_dwordx4 v[190:191], off
	s_add_i32 m0, s31, 0xe000
	v_lshl_add_u64 v[190:191], s[0:1], 0, v[138:139]
	global_load_lds_dwordx4 v[190:191], off
	s_add_u32 s10, s0, 0xfff80080
	s_addc_u32 s11, s1, -1
	s_add_i32 s24, 0, 0x10000
	s_cmp_eq_u32 s64, 28
	s_cselect_b32 s13, s49, s11
	s_cselect_b32 s12, s60, s10
	s_cselect_b32 s11, s47, s63
	s_cselect_b32 s10, s61, s62
	s_add_i32 s25, 0, 0x14000
	v_add_u32_e32 v148, 0x10000, v151
	ds_read_b128 v[140:143], v148
	ds_read_b128 v[144:147], v148 offset:1024
	ds_read_b128 v[154:157], v148 offset:2048
	ds_read_b128 v[158:161], v148 offset:3072
	v_add_u32_e32 v148, 0x14000, v151
	ds_read_b128 v[162:165], v148
	ds_read_b128 v[166:169], v148 offset:1024
	ds_read_b128 v[170:173], v148 offset:2048
	ds_read_b128 v[174:177], v148 offset:3072
	ds_read_b128 v[178:181], v152
	ds_read_b128 v[182:185], v152 offset:1024
	ds_read_b128 v[186:189], v152 offset:2048
	ds_read_b128 v[194:197], v152 offset:3072
	ds_read_b128 v[202:205], v152 offset:4096
	ds_read_b128 v[206:209], v152 offset:5120
	ds_read_b128 v[210:213], v152 offset:6144
	ds_read_b128 v[214:217], v152 offset:7168
	s_waitcnt vmcnt(8)
	s_waitcnt lgkmcnt(0)
	s_barrier
	s_setprio 1
	s_waitcnt lgkmcnt(0)
	v_mfma_f32_16x16x32_bf16 v[124:127], v[140:143], v[178:181], v[124:127]
	v_mfma_f32_16x16x32_bf16 v[112:115], v[154:157], v[178:181], v[112:115]
	v_mfma_f32_16x16x32_bf16 v[108:111], v[140:143], v[186:189], v[108:111]
	v_mfma_f32_16x16x32_bf16 v[100:103], v[154:157], v[186:189], v[100:103]
	v_mfma_f32_16x16x32_bf16 v[92:95], v[140:143], v[202:205], v[92:95]
	v_mfma_f32_16x16x32_bf16 v[84:87], v[154:157], v[202:205], v[84:87]
	v_mfma_f32_16x16x32_bf16 v[76:79], v[140:143], v[210:213], v[76:79]
	v_mfma_f32_16x16x32_bf16 v[68:71], v[154:157], v[210:213], v[68:71]
	v_mfma_f32_16x16x32_bf16 v[124:127], v[144:147], v[182:185], v[124:127]
	v_mfma_f32_16x16x32_bf16 v[112:115], v[158:161], v[182:185], v[112:115]
	v_mfma_f32_16x16x32_bf16 v[108:111], v[144:147], v[194:197], v[108:111]
	v_mfma_f32_16x16x32_bf16 v[100:103], v[158:161], v[194:197], v[100:103]
	v_mfma_f32_16x16x32_bf16 v[92:95], v[144:147], v[206:209], v[92:95]
	v_mfma_f32_16x16x32_bf16 v[84:87], v[158:161], v[206:209], v[84:87]
	v_mfma_f32_16x16x32_bf16 v[76:79], v[144:147], v[214:217], v[76:79]
	v_mfma_f32_16x16x32_bf16 v[68:71], v[158:161], v[214:217], v[68:71]
	s_setprio 0
	s_setprio 1
	v_mfma_f32_16x16x32_bf16 v[120:123], v[162:165], v[178:181], v[120:123]
	v_mfma_f32_16x16x32_bf16 v[116:119], v[170:173], v[178:181], v[116:119]
	v_mfma_f32_16x16x32_bf16 v[104:107], v[162:165], v[186:189], v[104:107]
	v_mfma_f32_16x16x32_bf16 v[96:99], v[170:173], v[186:189], v[96:99]
	v_mfma_f32_16x16x32_bf16 v[88:91], v[162:165], v[202:205], v[88:91]
	v_mfma_f32_16x16x32_bf16 v[80:83], v[170:173], v[202:205], v[80:83]
	v_mfma_f32_16x16x32_bf16 v[72:75], v[162:165], v[210:213], v[72:75]
	v_mfma_f32_16x16x32_bf16 v[64:67], v[170:173], v[210:213], v[64:67]
	v_mfma_f32_16x16x32_bf16 v[120:123], v[166:169], v[182:185], v[120:123]
	v_mfma_f32_16x16x32_bf16 v[116:119], v[174:177], v[182:185], v[116:119]
	v_mfma_f32_16x16x32_bf16 v[104:107], v[166:169], v[194:197], v[104:107]
	v_mfma_f32_16x16x32_bf16 v[96:99], v[174:177], v[194:197], v[96:99]
	v_mfma_f32_16x16x32_bf16 v[88:91], v[166:169], v[206:209], v[88:91]
	v_mfma_f32_16x16x32_bf16 v[80:83], v[174:177], v[206:209], v[80:83]
	v_mfma_f32_16x16x32_bf16 v[72:75], v[166:169], v[214:217], v[72:75]
	v_mfma_f32_16x16x32_bf16 v[64:67], v[174:177], v[214:217], v[64:67]
	s_setprio 0
	s_barrier
; #define PG8_STAGE(bufoff, gbase, voff) do { _Pragma("unroll") for (int _i = 0; _i < 2; ++_i) \
;         __builtin_amdgcn_global_load_lds((const unsigned*)((const char*)(gbase) + (voff)[_i]), (PG8_LAS unsigned*)(lds + (bufoff) + ldsw + _i * 8192), 16, 0, 0); } while (0)
; #define PG8_LDA(dst, b, h) do { _Pragma("unroll") for (int m = 0; m < 4; ++m) _Pragma("unroll") for (int k = 0; k < 2; ++k) dst[m][k] = *(const PG8_LAS bf16x8*)(lds + PG8_SA(b, h) + aoff + m * 2048 + k * 1024); } while (0)
; #define PG8_LDB(dst, b, h) do { _Pragma("unroll") for (int n = 0; n < 2; ++n) _Pragma("unroll") for (int k = 0; k < 2; ++k) dst[n][k] = *(const PG8_LAS bf16x8*)(lds + PG8_SB(b, h) + boff + n * 2048 + k * 1024); } while (0)
; #define PG8_MMA(ai, bj, At, Bt) do { __builtin_amdgcn_s_setprio(1); _Pragma("unroll") for (int m = 0; m < 4; ++m) _Pragma("unroll") for (int n = 0; n < 2; ++n) _Pragma("unroll") for (int k = 0; k < 2; ++k) \
;         acc[ai][bj][m][n] = __builtin_amdgcn_mfma_f32_16x16x32_bf16(Bt[n][k], At[m][k], acc[ai][bj][m][n], 0, 0, 0); __builtin_amdgcn_s_setprio(0); } while (0)
; #define PG8_WAIT_V(n) asm volatile("s_waitcnt vmcnt(" #n ")" ::: "memory")
; #define PG8_WAIT_L(n) asm volatile("s_waitcnt lgkmcnt(" #n ")" ::: "memory")
; #define PG8_BAR __builtin_amdgcn_s_barrier()
; #define PG8_SCHED __builtin_amdgcn_sched_barrier(0)
; template <class Epi, class Sched, bool ALIGN_EPI = false, bool SP2 = false>
; __device__ __forceinline__ void gemm_phase(PG8_LAS unsigned char* lds, const Gemm g, const Sched& S, const Epi& E) {
;     ...
;             PG8_LDA(At, 0, 1); PG8_STAGE(PG8_SB(0, 0), b2, voffB); PG8_STAGE(PG8_SB(0, 1), b2 + hstep, voffB); PG8_STAGE(PG8_SA(0, 0), a2, voffA);
;             PG8_WAIT_V(8); PG8_WAIT_L(0); PG8_BAR; PG8_MMA(1, 0, At, B0); PG8_MMA(1, 1, At, B1); PG8_BAR; PG8_SCHED;
;             PG8_LDB(B0, 1, 0); PG8_LDB(B1, 1, 1); PG8_SCHED; PG8_LDA(At, 1, 0); PG8_STAGE(PG8_SA(0, 1), a2 + hstep, voffA);
;             PG8_WAIT_V(8); PG8_WAIT_L(0); PG8_BAR; PG8_MMA(0, 0, At, B0); PG8_MMA(0, 1, At, B1); PG8_BAR; PG8_SCHED;
	s_add_i32 s24, s24, s30
	v_lshl_add_u64 v[190:191], s[10:11], 0, v[132:133]
	s_mov_b32 m0, s24
	s_nop 0
	global_load_lds_dwordx4 v[190:191], off
	s_add_i32 m0, s24, 0x2000
	s_add_u32 s66, s10, 0x80000
	v_lshl_add_u64 v[218:219], s[10:11], 0, v[128:129]
	s_addc_u32 s67, s11, 0
	s_add_i32 s24, s25, s30
	global_load_lds_dwordx4 v[218:219], off
	v_lshl_add_u64 v[220:221], s[66:67], 0, v[132:133]
	s_mov_b32 m0, s24
	v_lshl_add_u64 v[230:231], s[12:13], 0, v[130:131]
	global_load_lds_dwordx4 v[220:221], off
	s_add_i32 m0, s24, 0x2000
	v_lshl_add_u64 v[220:221], s[66:67], 0, v[128:129]
	global_load_lds_dwordx4 v[220:221], off
	s_mov_b32 m0, s31
	v_lshl_add_u64 v[220:221], s[12:13], 0, v[134:135]
	global_load_lds_dwordx4 v[220:221], off
	s_mov_b32 m0, s34
	s_nop 0
	global_load_lds_dwordx4 v[230:231], off
	ds_read_b128 v[178:181], v152 offset:16384
	ds_read_b128 v[182:185], v152 offset:17408
	ds_read_b128 v[186:189], v152 offset:18432
	ds_read_b128 v[194:197], v152 offset:19456
	ds_read_b128 v[202:205], v152 offset:20480
	ds_read_b128 v[206:209], v152 offset:21504
	ds_read_b128 v[210:213], v152 offset:22528
	ds_read_b128 v[214:217], v152 offset:23552
	s_waitcnt vmcnt(8)
	s_waitcnt lgkmcnt(0)
	s_barrier
	s_setprio 1
	s_waitcnt lgkmcnt(0)
	v_mfma_f32_16x16x32_bf16 v[60:63], v[140:143], v[178:181], v[60:63]
	v_mfma_f32_16x16x32_bf16 v[52:55], v[154:157], v[178:181], v[52:55]
	v_mfma_f32_16x16x32_bf16 v[44:47], v[140:143], v[186:189], v[44:47]
	v_mfma_f32_16x16x32_bf16 v[36:39], v[154:157], v[186:189], v[36:39]
	v_mfma_f32_16x16x32_bf16 v[28:31], v[140:143], v[202:205], v[28:31]
	v_mfma_f32_16x16x32_bf16 v[20:23], v[154:157], v[202:205], v[20:23]
	v_mfma_f32_16x16x32_bf16 v[12:15], v[140:143], v[210:213], v[12:15]
	v_mfma_f32_16x16x32_bf16 v[4:7], v[154:157], v[210:213], v[4:7]
	v_mfma_f32_16x16x32_bf16 v[60:63], v[144:147], v[182:185], v[60:63]
	v_mfma_f32_16x16x32_bf16 v[52:55], v[158:161], v[182:185], v[52:55]
	v_mfma_f32_16x16x32_bf16 v[44:47], v[144:147], v[194:197], v[44:47]
	v_mfma_f32_16x16x32_bf16 v[36:39], v[158:161], v[194:197], v[36:39]
	v_mfma_f32_16x16x32_bf16 v[28:31], v[144:147], v[206:209], v[28:31]
	v_mfma_f32_16x16x32_bf16 v[20:23], v[158:161], v[206:209], v[20:23]
	v_mfma_f32_16x16x32_bf16 v[12:15], v[144:147], v[214:217], v[12:15]
	v_mfma_f32_16x16x32_bf16 v[4:7], v[158:161], v[214:217], v[4:7]
	s_setprio 0
	s_setprio 1
	v_mfma_f32_16x16x32_bf16 v[56:59], v[162:165], v[178:181], v[56:59]
	v_mfma_f32_16x16x32_bf16 v[48:51], v[170:173], v[178:181], v[48:51]
	v_mfma_f32_16x16x32_bf16 v[40:43], v[162:165], v[186:189], v[40:43]
	v_mfma_f32_16x16x32_bf16 v[32:35], v[170:173], v[186:189], v[32:35]
	v_mfma_f32_16x16x32_bf16 v[24:27], v[162:165], v[202:205], v[24:27]
	v_mfma_f32_16x16x32_bf16 v[16:19], v[170:173], v[202:205], v[16:19]
	v_mfma_f32_16x16x32_bf16 v[8:11], v[162:165], v[210:213], v[8:11]
	v_mfma_f32_16x16x32_bf16 v[0:3], v[170:173], v[210:213], v[0:3]
	v_mfma_f32_16x16x32_bf16 v[56:59], v[166:169], v[182:185], v[56:59]
	v_mfma_f32_16x16x32_bf16 v[48:51], v[174:177], v[182:185], v[48:51]
	v_mfma_f32_16x16x32_bf16 v[40:43], v[166:169], v[194:197], v[40:43]
	v_mfma_f32_16x16x32_bf16 v[32:35], v[174:177], v[194:197], v[32:35]
	v_mfma_f32_16x16x32_bf16 v[24:27], v[166:169], v[206:209], v[24:27]
	v_mfma_f32_16x16x32_bf16 v[16:19], v[174:177], v[206:209], v[16:19]
	v_mfma_f32_16x16x32_bf16 v[8:11], v[166:169], v[214:217], v[8:11]
	v_mfma_f32_16x16x32_bf16 v[0:3], v[174:177], v[214:217], v[0:3]
	s_setprio 0
	s_barrier
	s_add_i32 s24, 0, 0x18000
	s_add_i32 s25, 0, 0x1c000
	s_add_u32 s12, s12, 0x80000
	s_addc_u32 s13, s13, 0
	s_mov_b32 m0, s36
	v_lshl_add_u64 v[232:233], s[12:13], 0, v[134:135]
	global_load_lds_dwordx4 v[232:233], off
	s_mov_b32 m0, s37
	v_lshl_add_u64 v[232:233], s[12:13], 0, v[130:131]
	global_load_lds_dwordx4 v[232:233], off
	v_add_u32_e32 v148, 0x18000, v151
	ds_read_b128 v[140:143], v148
	ds_read_b128 v[144:147], v148 offset:1024
	ds_read_b128 v[154:157], v148 offset:2048
	ds_read_b128 v[158:161], v148 offset:3072
	v_add_u32_e32 v148, 0x1c000, v151
	ds_read_b128 v[162:165], v148
	ds_read_b128 v[166:169], v148 offset:1024
	ds_read_b128 v[170:173], v148 offset:2048
	ds_read_b128 v[174:177], v148 offset:3072
	ds_read_b128 v[178:181], v152 offset:32768
	ds_read_b128 v[182:185], v152 offset:33792
	ds_read_b128 v[186:189], v152 offset:34816
	ds_read_b128 v[194:197], v152 offset:35840
	ds_read_b128 v[202:205], v152 offset:36864
	ds_read_b128 v[206:209], v152 offset:37888
	ds_read_b128 v[210:213], v152 offset:38912
	ds_read_b128 v[214:217], v152 offset:39936
	s_waitcnt vmcnt(8)
	s_waitcnt lgkmcnt(0)
	s_barrier
; #define PG8_STAGE(bufoff, gbase, voff) do { _Pragma("unroll") for (int _i = 0; _i < 2; ++_i) \
;         __builtin_amdgcn_global_load_lds((const unsigned*)((const char*)(gbase) + (voff)[_i]), (PG8_LAS unsigned*)(lds + (bufoff) + ldsw + _i * 8192), 16, 0, 0); } while (0)
; #define PG8_LDA(dst, b, h) do { _Pragma("unroll") for (int m = 0; m < 4; ++m) _Pragma("unroll") for (int k = 0; k < 2; ++k) dst[m][k] = *(const PG8_LAS bf16x8*)(lds + PG8_SA(b, h) + aoff + m * 2048 + k * 1024); } while (0)
; #define PG8_LDB(dst, b, h) do { _Pragma("unroll") for (int n = 0; n < 2; ++n) _Pragma("unroll") for (int k = 0; k < 2; ++k) dst[n][k] = *(const PG8_LAS bf16x8*)(lds + PG8_SB(b, h) + boff + n * 2048 + k * 1024); } while (0)
; #define PG8_MMA(ai, bj, At, Bt) do { __builtin_amdgcn_s_setprio(1); _Pragma("unroll") for (int m = 0; m < 4; ++m) _Pragma("unroll") for (int n = 0; n < 2; ++n) _Pragma("unroll") for (int k = 0; k < 2; ++k) \
;         acc[ai][bj][m][n] = __builtin_amdgcn_mfma_f32_16x16x32_bf16(Bt[n][k], At[m][k], acc[ai][bj][m][n], 0, 0, 0); __builtin_amdgcn_s_setprio(0); } while (0)
; #define PG8_WAIT_V(n) asm volatile("s_waitcnt vmcnt(" #n ")" ::: "memory")
; #define PG8_WAIT_L(n) asm volatile("s_waitcnt lgkmcnt(" #n ")" ::: "memory")
; #define PG8_BAR __builtin_amdgcn_s_barrier()
; #define PG8_SCHED __builtin_amdgcn_sched_barrier(0)
; template <class Epi, class Sched, bool ALIGN_EPI = false, bool SP2 = false>
; __device__ __forceinline__ void gemm_phase(PG8_LAS unsigned char* lds, const Gemm g, const Sched& S, const Epi& E) {
;     ...
;             PG8_LDB(B0, 1, 0); PG8_LDB(B1, 1, 1); PG8_SCHED; PG8_LDA(At, 1, 0); PG8_STAGE(PG8_SA(0, 1), a2 + hstep, voffA);
;             PG8_WAIT_V(8); PG8_WAIT_L(0); PG8_BAR; PG8_MMA(0, 0, At, B0); PG8_MMA(0, 1, At, B1); PG8_BAR; PG8_SCHED;
;             PG8_LDA(At, 1, 1); PG8_STAGE(PG8_SB(1, 0), b3, voffB); PG8_STAGE(PG8_SB(1, 1), b3 + hstep, voffB); PG8_STAGE(PG8_SA(1, 0), a3, voffA);
;             PG8_WAIT_V(8); PG8_WAIT_L(0); PG8_BAR; PG8_MMA(1, 0, At, B0); PG8_MMA(1, 1, At, B1); PG8_BAR; PG8_SCHED;
;     ...
;         if constexpr (ALIGN_EPI) { if (wr == 0) PG8_BAR; }
	s_setprio 1
	s_waitcnt lgkmcnt(0)
	v_mfma_f32_16x16x32_bf16 v[124:127], v[140:143], v[178:181], v[124:127]
	v_mfma_f32_16x16x32_bf16 v[112:115], v[154:157], v[178:181], v[112:115]
	v_mfma_f32_16x16x32_bf16 v[108:111], v[140:143], v[186:189], v[108:111]
	v_mfma_f32_16x16x32_bf16 v[100:103], v[154:157], v[186:189], v[100:103]
	v_mfma_f32_16x16x32_bf16 v[92:95], v[140:143], v[202:205], v[92:95]
	v_mfma_f32_16x16x32_bf16 v[84:87], v[154:157], v[202:205], v[84:87]
	v_mfma_f32_16x16x32_bf16 v[76:79], v[140:143], v[210:213], v[76:79]
	v_mfma_f32_16x16x32_bf16 v[68:71], v[154:157], v[210:213], v[68:71]
	v_mfma_f32_16x16x32_bf16 v[124:127], v[144:147], v[182:185], v[124:127]
	v_mfma_f32_16x16x32_bf16 v[112:115], v[158:161], v[182:185], v[112:115]
	v_mfma_f32_16x16x32_bf16 v[108:111], v[144:147], v[194:197], v[108:111]
	v_mfma_f32_16x16x32_bf16 v[100:103], v[158:161], v[194:197], v[100:103]
	v_mfma_f32_16x16x32_bf16 v[92:95], v[144:147], v[206:209], v[92:95]
	v_mfma_f32_16x16x32_bf16 v[84:87], v[158:161], v[206:209], v[84:87]
	v_mfma_f32_16x16x32_bf16 v[76:79], v[144:147], v[214:217], v[76:79]
	v_mfma_f32_16x16x32_bf16 v[68:71], v[158:161], v[214:217], v[68:71]
	s_setprio 0
	s_setprio 1
	v_mfma_f32_16x16x32_bf16 v[120:123], v[162:165], v[178:181], v[120:123]
	v_mfma_f32_16x16x32_bf16 v[116:119], v[170:173], v[178:181], v[116:119]
	v_mfma_f32_16x16x32_bf16 v[104:107], v[162:165], v[186:189], v[104:107]
	v_mfma_f32_16x16x32_bf16 v[96:99], v[170:173], v[186:189], v[96:99]
	v_mfma_f32_16x16x32_bf16 v[88:91], v[162:165], v[202:205], v[88:91]
	v_mfma_f32_16x16x32_bf16 v[80:83], v[170:173], v[202:205], v[80:83]
	v_mfma_f32_16x16x32_bf16 v[72:75], v[162:165], v[210:213], v[72:75]
	v_mfma_f32_16x16x32_bf16 v[64:67], v[170:173], v[210:213], v[64:67]
	v_mfma_f32_16x16x32_bf16 v[120:123], v[166:169], v[182:185], v[120:123]
	v_mfma_f32_16x16x32_bf16 v[116:119], v[174:177], v[182:185], v[116:119]
	v_mfma_f32_16x16x32_bf16 v[104:107], v[166:169], v[194:197], v[104:107]
	v_mfma_f32_16x16x32_bf16 v[96:99], v[174:177], v[194:197], v[96:99]
	v_mfma_f32_16x16x32_bf16 v[88:91], v[166:169], v[206:209], v[88:91]
	v_mfma_f32_16x16x32_bf16 v[80:83], v[174:177], v[206:209], v[80:83]
	v_mfma_f32_16x16x32_bf16 v[72:75], v[166:169], v[214:217], v[72:75]
	v_mfma_f32_16x16x32_bf16 v[64:67], v[174:177], v[214:217], v[64:67]
	s_setprio 0
	s_barrier
	s_add_i32 s12, s24, s30
	v_lshl_add_u64 v[190:191], v[190:191], 0, s[16:17]
	s_mov_b32 m0, s12
	s_nop 0
	global_load_lds_dwordx4 v[190:191], off
	s_add_i32 m0, s12, 0x2000
	s_add_u32 s10, s10, 0x80080
	v_lshl_add_u64 v[190:191], v[218:219], 0, s[16:17]
	s_addc_u32 s11, s11, 0
	s_add_i32 s12, s25, s30
	global_load_lds_dwordx4 v[190:191], off
	s_mov_b32 m0, s12
	v_lshl_add_u64 v[190:191], s[10:11], 0, v[132:133]
	global_load_lds_dwordx4 v[190:191], off
	s_add_i32 m0, s12, 0x2000
	v_lshl_add_u64 v[190:191], s[10:11], 0, v[128:129]
	global_load_lds_dwordx4 v[190:191], off
	s_mov_b32 m0, s56
	v_lshl_add_u64 v[190:191], v[220:221], 0, s[16:17]
	global_load_lds_dwordx4 v[190:191], off
	s_mov_b32 m0, s57
	v_lshl_add_u64 v[190:191], v[230:231], 0, s[16:17]
	global_load_lds_dwordx4 v[190:191], off
	ds_read_b128 v[178:181], v152 offset:49152
	ds_read_b128 v[182:185], v152 offset:50176
	ds_read_b128 v[186:189], v152 offset:51200
	ds_read_b128 v[194:197], v152 offset:52224
	ds_read_b128 v[202:205], v152 offset:53248
	ds_read_b128 v[206:209], v152 offset:54272
	ds_read_b128 v[210:213], v152 offset:55296
	ds_read_b128 v[214:217], v152 offset:56320
	s_waitcnt vmcnt(8)
	s_waitcnt lgkmcnt(0)
	s_barrier
	s_setprio 1
	s_waitcnt lgkmcnt(0)
	v_mfma_f32_16x16x32_bf16 v[60:63], v[140:143], v[178:181], v[60:63]
	v_mfma_f32_16x16x32_bf16 v[52:55], v[154:157], v[178:181], v[52:55]
	v_mfma_f32_16x16x32_bf16 v[44:47], v[140:143], v[186:189], v[44:47]
	v_mfma_f32_16x16x32_bf16 v[36:39], v[154:157], v[186:189], v[36:39]
	v_mfma_f32_16x16x32_bf16 v[28:31], v[140:143], v[202:205], v[28:31]
	v_mfma_f32_16x16x32_bf16 v[20:23], v[154:157], v[202:205], v[20:23]
	v_mfma_f32_16x16x32_bf16 v[12:15], v[140:143], v[210:213], v[12:15]
	v_mfma_f32_16x16x32_bf16 v[4:7], v[154:157], v[210:213], v[4:7]
	v_mfma_f32_16x16x32_bf16 v[60:63], v[144:147], v[182:185], v[60:63]
	v_mfma_f32_16x16x32_bf16 v[52:55], v[158:161], v[182:185], v[52:55]
	v_mfma_f32_16x16x32_bf16 v[44:47], v[144:147], v[194:197], v[44:47]
	v_mfma_f32_16x16x32_bf16 v[36:39], v[158:161], v[194:197], v[36:39]
	v_mfma_f32_16x16x32_bf16 v[28:31], v[144:147], v[206:209], v[28:31]
	v_mfma_f32_16x16x32_bf16 v[20:23], v[158:161], v[206:209], v[20:23]
	v_mfma_f32_16x16x32_bf16 v[12:15], v[144:147], v[214:217], v[12:15]
	v_mfma_f32_16x16x32_bf16 v[4:7], v[158:161], v[214:217], v[4:7]
	s_setprio 0
	s_setprio 1
	v_mfma_f32_16x16x32_bf16 v[56:59], v[162:165], v[178:181], v[56:59]
	v_mfma_f32_16x16x32_bf16 v[48:51], v[170:173], v[178:181], v[48:51]
	v_mfma_f32_16x16x32_bf16 v[40:43], v[162:165], v[186:189], v[40:43]
	v_mfma_f32_16x16x32_bf16 v[32:35], v[170:173], v[186:189], v[32:35]
	v_mfma_f32_16x16x32_bf16 v[24:27], v[162:165], v[202:205], v[24:27]
	v_mfma_f32_16x16x32_bf16 v[16:19], v[170:173], v[202:205], v[16:19]
	v_mfma_f32_16x16x32_bf16 v[8:11], v[162:165], v[210:213], v[8:11]
	v_mfma_f32_16x16x32_bf16 v[0:3], v[170:173], v[210:213], v[0:3]
	v_mfma_f32_16x16x32_bf16 v[56:59], v[166:169], v[182:185], v[56:59]
	v_mfma_f32_16x16x32_bf16 v[48:51], v[174:177], v[182:185], v[48:51]
	v_mfma_f32_16x16x32_bf16 v[40:43], v[166:169], v[194:197], v[40:43]
	v_mfma_f32_16x16x32_bf16 v[32:35], v[174:177], v[194:197], v[32:35]
	v_mfma_f32_16x16x32_bf16 v[24:27], v[166:169], v[206:209], v[24:27]
	v_mfma_f32_16x16x32_bf16 v[16:19], v[174:177], v[206:209], v[16:19]
	v_mfma_f32_16x16x32_bf16 v[8:11], v[166:169], v[214:217], v[8:11]
	v_mfma_f32_16x16x32_bf16 v[0:3], v[174:177], v[214:217], v[0:3]
	s_setprio 0
	s_barrier
	s_add_i32 s64, s64, 2
	s_add_u32 s0, s0, 0x100
	s_addc_u32 s1, s1, 0
	s_add_u32 s62, s62, 0x100
	s_addc_u32 s63, s63, 0
	s_cmp_gt_u32 s64, 29
	s_cbranch_scc0 .LBB0_730
	s_and_b64 vcc, exec, s[44:45]
	s_cbranch_vccz .LBB0_733
	s_barrier

; #define PG8_STAGE(bufoff, gbase, voff) do { _Pragma("unroll") for (int _i = 0; _i < 2; ++_i) \
;         __builtin_amdgcn_global_load_lds((const unsigned*)((const char*)(gbase) + (voff)[_i]), (PG8_LAS unsigned*)(lds + (bufoff) + ldsw + _i * 8192), 16, 0, 0); } while (0)
; #define PG8_LDA(dst, b, h) do { _Pragma("unroll") for (int m = 0; m < 4; ++m) _Pragma("unroll") for (int k = 0; k < 2; ++k) dst[m][k] = *(const PG8_LAS bf16x8*)(lds + PG8_SA(b, h) + aoff + m * 2048 + k * 1024); } while (0)
; #define PG8_LDB(dst, b, h) do { _Pragma("unroll") for (int n = 0; n < 2; ++n) _Pragma("unroll") for (int k = 0; k < 2; ++k) dst[n][k] = *(const PG8_LAS bf16x8*)(lds + PG8_SB(b, h) + boff + n * 2048 + k * 1024); } while (0)
; #define PG8_MMA(ai, bj, At, Bt) do { __builtin_amdgcn_s_setprio(1); _Pragma("unroll") for (int m = 0; m < 4; ++m) _Pragma("unroll") for (int n = 0; n < 2; ++n) _Pragma("unroll") for (int k = 0; k < 2; ++k) \
;         acc[ai][bj][m][n] = __builtin_amdgcn_mfma_f32_16x16x32_bf16(Bt[n][k], At[m][k], acc[ai][bj][m][n], 0, 0, 0); __builtin_amdgcn_s_setprio(0); } while (0)
; #define PG8_WAIT_V(n) asm volatile("s_waitcnt vmcnt(" #n ")" ::: "memory")
; #define PG8_WAIT_L(n) asm volatile("s_waitcnt lgkmcnt(" #n ")" ::: "memory")
; #define PG8_BAR __builtin_amdgcn_s_barrier()
; #define PG8_SCHED __builtin_amdgcn_sched_barrier(0)
; template <class Epi, class Sched, bool ALIGN_EPI = false, bool SP2 = false>
; __device__ __forceinline__ void gemm_phase(PG8_LAS unsigned char* lds, const Gemm g, const Sched& S, const Epi& E) {
;     ...
;             const char* a2 = last ? nA : cA + (size_t)(t + 2) * kstep; const char* b2 = last ? nB : cB + (size_t)(t + 2) * kstep;
;             const char* a3 = a2 + kstep; const char* b3 = b2 + kstep;
;             if (last && has_next) S.a_ready(nxt);
;             if constexpr (SP2) {
;             PG8_LDB(B0, 0, 0); PG8_LDB(B1, 0, 1); PG8_SCHED; PG8_LDA(At, 0, 0); PG8_STAGE(PG8_SA(1, 1), a1 + hstep, voffA);
;             PG8_WAIT_V(8); PG8_WAIT_L(0); PG8_BAR; PG8_MMA(0, 0, At, B0); PG8_MMA(0, 1, At, B1); PG8_BAR; PG8_SCHED;
;             PG8_LDA(At, 0, 1); PG8_STAGE(PG8_SB(0, 0), b2, voffB); PG8_STAGE(PG8_SB(0, 1), b2 + hstep, voffB); PG8_STAGE(PG8_SA(0, 0), a2, voffA);
;             PG8_WAIT_V(8); PG8_WAIT_L(0); PG8_BAR; PG8_MMA(1, 0, At, B0); PG8_MMA(1, 1, At, B1); PG8_BAR; PG8_SCHED;
.LBB0_816:
	s_add_u32 s59, s30, 0x100
	s_addc_u32 s60, s31, 0
	s_mov_b32 s61, -2
	s_waitcnt lgkmcnt(0)
	v_lshl_add_u64 v[168:169], s[18:19], 0, v[160:161]
	s_add_i32 m0, s2, 0xc000
	global_load_lds_dwordx4 v[168:169], off
	s_add_i32 m0, s2, 0xe000
	v_lshl_add_u64 v[168:169], s[18:19], 0, v[162:163]
	global_load_lds_dwordx4 v[168:169], off
	s_add_u32 s30, s18, 0x100
	s_addc_u32 s31, s19, 0
	s_add_i32 s24, 0, 0x10000
	s_cmpk_eq_i32 s61, 0x54
	s_cselect_b32 s39, s5, s31
	s_cselect_b32 s38, s4, s30
	s_cselect_b32 s37, s15, s60
	s_cselect_b32 s36, s14, s59
	s_add_i32 s25, 0, 0x14000
	s_waitcnt vmcnt(8)
	s_waitcnt lgkmcnt(0)
	s_barrier
	s_setprio 1
	s_waitcnt lgkmcnt(0)
	v_mfma_f32_16x16x32_bf16 v[124:127], v[128:131], v[178:181], 0
	v_mfma_f32_16x16x32_bf16 v[120:123], v[136:139], v[178:181], 0
	v_mfma_f32_16x16x32_bf16 v[108:111], v[128:131], v[186:189], 0
	v_mfma_f32_16x16x32_bf16 v[104:107], v[136:139], v[186:189], 0
	v_mfma_f32_16x16x32_bf16 v[92:95], v[128:131], v[202:205], 0
	v_mfma_f32_16x16x32_bf16 v[88:91], v[136:139], v[202:205], 0
	v_mfma_f32_16x16x32_bf16 v[76:79], v[128:131], v[210:213], 0
	v_mfma_f32_16x16x32_bf16 v[72:75], v[136:139], v[210:213], 0
	v_mfma_f32_16x16x32_bf16 v[124:127], v[132:135], v[182:185], v[124:127]
	v_mfma_f32_16x16x32_bf16 v[120:123], v[140:143], v[182:185], v[120:123]
	v_mfma_f32_16x16x32_bf16 v[108:111], v[132:135], v[194:197], v[108:111]
	v_mfma_f32_16x16x32_bf16 v[104:107], v[140:143], v[194:197], v[104:107]
	v_mfma_f32_16x16x32_bf16 v[92:95], v[132:135], v[206:209], v[92:95]
	v_mfma_f32_16x16x32_bf16 v[88:91], v[140:143], v[206:209], v[88:91]
	v_mfma_f32_16x16x32_bf16 v[76:79], v[132:135], v[214:217], v[76:79]
	v_mfma_f32_16x16x32_bf16 v[72:75], v[140:143], v[214:217], v[72:75]
	s_setprio 0
	s_setprio 1
	v_mfma_f32_16x16x32_bf16 v[116:119], v[144:147], v[178:181], 0
	v_mfma_f32_16x16x32_bf16 v[112:115], v[164:167], v[178:181], 0
	v_mfma_f32_16x16x32_bf16 v[100:103], v[144:147], v[186:189], 0
	v_mfma_f32_16x16x32_bf16 v[96:99], v[164:167], v[186:189], 0
	v_mfma_f32_16x16x32_bf16 v[84:87], v[144:147], v[202:205], 0
	v_mfma_f32_16x16x32_bf16 v[80:83], v[164:167], v[202:205], 0
	v_mfma_f32_16x16x32_bf16 v[68:71], v[144:147], v[210:213], 0
	v_mfma_f32_16x16x32_bf16 v[64:67], v[164:167], v[210:213], 0
	v_mfma_f32_16x16x32_bf16 v[116:119], v[148:151], v[182:185], v[116:119]
	v_mfma_f32_16x16x32_bf16 v[112:115], v[174:177], v[182:185], v[112:115]
	v_mfma_f32_16x16x32_bf16 v[100:103], v[148:151], v[194:197], v[100:103]
	v_mfma_f32_16x16x32_bf16 v[96:99], v[174:177], v[194:197], v[96:99]
	v_mfma_f32_16x16x32_bf16 v[84:87], v[148:151], v[206:209], v[84:87]
	v_mfma_f32_16x16x32_bf16 v[80:83], v[174:177], v[206:209], v[80:83]
	v_mfma_f32_16x16x32_bf16 v[68:71], v[148:151], v[214:217], v[68:71]
	v_mfma_f32_16x16x32_bf16 v[64:67], v[174:177], v[214:217], v[64:67]
	s_setprio 0
	s_barrier
	s_add_i32 s18, s24, s43
	v_lshl_add_u64 v[168:169], s[36:37], 0, v[156:157]
	s_mov_b32 m0, s18
	s_nop 0
	global_load_lds_dwordx4 v[168:169], off
	s_add_i32 m0, s18, 0x2000
	s_add_u32 s18, s36, 0x160000
	v_lshl_add_u64 v[190:191], s[36:37], 0, v[152:153]
	s_addc_u32 s19, s37, 0
	s_add_i32 s24, s25, s43
	global_load_lds_dwordx4 v[190:191], off
	v_lshl_add_u64 v[218:219], s[18:19], 0, v[156:157]
	s_mov_b32 m0, s24
	v_lshl_add_u64 v[220:221], s[38:39], 0, v[154:155]
	global_load_lds_dwordx4 v[218:219], off
	s_add_i32 m0, s24, 0x2000
	v_lshl_add_u64 v[218:219], s[18:19], 0, v[152:153]
	global_load_lds_dwordx4 v[218:219], off
	s_mov_b32 m0, s2
	v_lshl_add_u64 v[218:219], s[38:39], 0, v[158:159]
	global_load_lds_dwordx4 v[218:219], off
	s_mov_b32 m0, s44
	s_nop 0
	global_load_lds_dwordx4 v[220:221], off
	ds_read_b128 v[178:181], v173 offset:16384
	ds_read_b128 v[182:185], v173 offset:17408
	ds_read_b128 v[186:189], v173 offset:18432
	ds_read_b128 v[194:197], v173 offset:19456
	ds_read_b128 v[202:205], v173 offset:20480
	ds_read_b128 v[206:209], v173 offset:21504
	ds_read_b128 v[210:213], v173 offset:22528
	ds_read_b128 v[214:217], v173 offset:23552
	s_waitcnt vmcnt(8)
	s_waitcnt lgkmcnt(0)
	s_barrier
	s_setprio 1
	s_waitcnt lgkmcnt(0)
	v_mfma_f32_16x16x32_bf16 v[60:63], v[128:131], v[178:181], 0
	v_mfma_f32_16x16x32_bf16 v[56:59], v[136:139], v[178:181], 0
	v_mfma_f32_16x16x32_bf16 v[44:47], v[128:131], v[186:189], 0
	v_mfma_f32_16x16x32_bf16 v[40:43], v[136:139], v[186:189], 0
	v_mfma_f32_16x16x32_bf16 v[28:31], v[128:131], v[202:205], 0
	v_mfma_f32_16x16x32_bf16 v[24:27], v[136:139], v[202:205], 0
	v_mfma_f32_16x16x32_bf16 v[12:15], v[128:131], v[210:213], 0
	v_mfma_f32_16x16x32_bf16 v[8:11], v[136:139], v[210:213], 0
	v_mfma_f32_16x16x32_bf16 v[60:63], v[132:135], v[182:185], v[60:63]
	v_mfma_f32_16x16x32_bf16 v[56:59], v[140:143], v[182:185], v[56:59]
	v_mfma_f32_16x16x32_bf16 v[44:47], v[132:135], v[194:197], v[44:47]
	v_mfma_f32_16x16x32_bf16 v[40:43], v[140:143], v[194:197], v[40:43]
	v_mfma_f32_16x16x32_bf16 v[28:31], v[132:135], v[206:209], v[28:31]
	v_mfma_f32_16x16x32_bf16 v[24:27], v[140:143], v[206:209], v[24:27]
	v_mfma_f32_16x16x32_bf16 v[12:15], v[132:135], v[214:217], v[12:15]
	v_mfma_f32_16x16x32_bf16 v[8:11], v[140:143], v[214:217], v[8:11]
	s_setprio 0
	s_setprio 1
	v_mfma_f32_16x16x32_bf16 v[52:55], v[144:147], v[178:181], 0
	v_mfma_f32_16x16x32_bf16 v[48:51], v[164:167], v[178:181], 0
	v_mfma_f32_16x16x32_bf16 v[36:39], v[144:147], v[186:189], 0
	v_mfma_f32_16x16x32_bf16 v[32:35], v[164:167], v[186:189], 0
	v_mfma_f32_16x16x32_bf16 v[20:23], v[144:147], v[202:205], 0
	v_mfma_f32_16x16x32_bf16 v[16:19], v[164:167], v[202:205], 0
	v_mfma_f32_16x16x32_bf16 v[4:7], v[144:147], v[210:213], 0
	v_mfma_f32_16x16x32_bf16 v[0:3], v[164:167], v[210:213], 0
	v_mfma_f32_16x16x32_bf16 v[52:55], v[148:151], v[182:185], v[52:55]
	v_mfma_f32_16x16x32_bf16 v[48:51], v[174:177], v[182:185], v[48:51]
	v_mfma_f32_16x16x32_bf16 v[36:39], v[148:151], v[194:197], v[36:39]
	v_mfma_f32_16x16x32_bf16 v[32:35], v[174:177], v[194:197], v[32:35]
	v_mfma_f32_16x16x32_bf16 v[20:23], v[148:151], v[206:209], v[20:23]
	v_mfma_f32_16x16x32_bf16 v[16:19], v[174:177], v[206:209], v[16:19]
	v_mfma_f32_16x16x32_bf16 v[4:7], v[148:151], v[214:217], v[4:7]
	v_mfma_f32_16x16x32_bf16 v[0:3], v[174:177], v[214:217], v[0:3]
	s_setprio 0
	s_barrier
; #define PG8_STAGE(bufoff, gbase, voff) do { _Pragma("unroll") for (int _i = 0; _i < 2; ++_i) \
;         __builtin_amdgcn_global_load_lds((const unsigned*)((const char*)(gbase) + (voff)[_i]), (PG8_LAS unsigned*)(lds + (bufoff) + ldsw + _i * 8192), 16, 0, 0); } while (0)
; #define PG8_LDA(dst, b, h) do { _Pragma("unroll") for (int m = 0; m < 4; ++m) _Pragma("unroll") for (int k = 0; k < 2; ++k) dst[m][k] = *(const PG8_LAS bf16x8*)(lds + PG8_SA(b, h) + aoff + m * 2048 + k * 1024); } while (0)
; #define PG8_LDB(dst, b, h) do { _Pragma("unroll") for (int n = 0; n < 2; ++n) _Pragma("unroll") for (int k = 0; k < 2; ++k) dst[n][k] = *(const PG8_LAS bf16x8*)(lds + PG8_SB(b, h) + boff + n * 2048 + k * 1024); } while (0)
; #define PG8_MMA(ai, bj, At, Bt) do { __builtin_amdgcn_s_setprio(1); _Pragma("unroll") for (int m = 0; m < 4; ++m) _Pragma("unroll") for (int n = 0; n < 2; ++n) _Pragma("unroll") for (int k = 0; k < 2; ++k) \
;         acc[ai][bj][m][n] = __builtin_amdgcn_mfma_f32_16x16x32_bf16(Bt[n][k], At[m][k], acc[ai][bj][m][n], 0, 0, 0); __builtin_amdgcn_s_setprio(0); } while (0)
; #define PG8_WAIT_V(n) asm volatile("s_waitcnt vmcnt(" #n ")" ::: "memory")
; #define PG8_WAIT_L(n) asm volatile("s_waitcnt lgkmcnt(" #n ")" ::: "memory")
; #define PG8_BAR __builtin_amdgcn_s_barrier()
; #define PG8_SCHED __builtin_amdgcn_sched_barrier(0)
; template <class Epi, class Sched, bool ALIGN_EPI = false, bool SP2 = false>
; __device__ __forceinline__ void gemm_phase(PG8_LAS unsigned char* lds, const Gemm g, const Sched& S, const Epi& E) {
;     ...
;             PG8_LDB(B0, 1, 0); PG8_LDB(B1, 1, 1); PG8_SCHED; PG8_LDA(At, 1, 0); PG8_STAGE(PG8_SA(0, 1), a2 + hstep, voffA);
;             PG8_WAIT_V(8); PG8_WAIT_L(0); PG8_BAR; PG8_MMA(0, 0, At, B0); PG8_MMA(0, 1, At, B1); PG8_BAR; PG8_SCHED;
;             PG8_LDA(At, 1, 1); PG8_STAGE(PG8_SB(1, 0), b3, voffB); PG8_STAGE(PG8_SB(1, 1), b3 + hstep, voffB); PG8_STAGE(PG8_SA(1, 0), a3, voffA);
;             PG8_WAIT_V(8); PG8_WAIT_L(0); PG8_BAR; PG8_MMA(1, 0, At, B0); PG8_MMA(1, 1, At, B1); PG8_BAR; PG8_SCHED;
	s_add_i32 s24, 0, 0x18000
	s_add_i32 s25, 0, 0x1c000
	s_add_u32 s18, s38, 0x160000
	s_addc_u32 s19, s39, 0
	s_mov_b32 m0, s45
	v_lshl_add_u64 v[230:231], s[18:19], 0, v[158:159]
	global_load_lds_dwordx4 v[230:231], off
	s_mov_b32 m0, s46
	v_lshl_add_u64 v[230:231], s[18:19], 0, v[154:155]
	global_load_lds_dwordx4 v[230:231], off
	v_add_u32_e32 v140, 0x18000, v172
	v_add_u32_e32 v174, 0x1c000, v172
	ds_read_b128 v[128:131], v140
	ds_read_b128 v[132:135], v140 offset:1024
	ds_read_b128 v[136:139], v140 offset:2048
	ds_read_b128 v[140:143], v140 offset:3072
	ds_read_b128 v[144:147], v174
	ds_read_b128 v[148:151], v174 offset:1024
	ds_read_b128 v[164:167], v174 offset:2048
	ds_read_b128 v[174:177], v174 offset:3072
	ds_read_b128 v[178:181], v173 offset:32768
	ds_read_b128 v[182:185], v173 offset:33792
	ds_read_b128 v[186:189], v173 offset:34816
	ds_read_b128 v[194:197], v173 offset:35840
	ds_read_b128 v[202:205], v173 offset:36864
	ds_read_b128 v[206:209], v173 offset:37888
	ds_read_b128 v[210:213], v173 offset:38912
	ds_read_b128 v[214:217], v173 offset:39936
	s_waitcnt vmcnt(8)
	s_waitcnt lgkmcnt(0)
	s_barrier
	s_setprio 1
	s_waitcnt lgkmcnt(0)
	v_mfma_f32_16x16x32_bf16 v[124:127], v[128:131], v[178:181], v[124:127]
	v_mfma_f32_16x16x32_bf16 v[120:123], v[136:139], v[178:181], v[120:123]
	v_mfma_f32_16x16x32_bf16 v[108:111], v[128:131], v[186:189], v[108:111]
	v_mfma_f32_16x16x32_bf16 v[104:107], v[136:139], v[186:189], v[104:107]
	v_mfma_f32_16x16x32_bf16 v[92:95], v[128:131], v[202:205], v[92:95]
	v_mfma_f32_16x16x32_bf16 v[88:91], v[136:139], v[202:205], v[88:91]
	v_mfma_f32_16x16x32_bf16 v[76:79], v[128:131], v[210:213], v[76:79]
	v_mfma_f32_16x16x32_bf16 v[72:75], v[136:139], v[210:213], v[72:75]
	v_mfma_f32_16x16x32_bf16 v[124:127], v[132:135], v[182:185], v[124:127]
	v_mfma_f32_16x16x32_bf16 v[120:123], v[140:143], v[182:185], v[120:123]
	v_mfma_f32_16x16x32_bf16 v[108:111], v[132:135], v[194:197], v[108:111]
	v_mfma_f32_16x16x32_bf16 v[104:107], v[140:143], v[194:197], v[104:107]
	v_mfma_f32_16x16x32_bf16 v[92:95], v[132:135], v[206:209], v[92:95]
	v_mfma_f32_16x16x32_bf16 v[88:91], v[140:143], v[206:209], v[88:91]
	v_mfma_f32_16x16x32_bf16 v[76:79], v[132:135], v[214:217], v[76:79]
	v_mfma_f32_16x16x32_bf16 v[72:75], v[140:143], v[214:217], v[72:75]
	s_setprio 0
	s_setprio 1
	v_mfma_f32_16x16x32_bf16 v[116:119], v[144:147], v[178:181], v[116:119]
	v_mfma_f32_16x16x32_bf16 v[112:115], v[164:167], v[178:181], v[112:115]
	v_mfma_f32_16x16x32_bf16 v[100:103], v[144:147], v[186:189], v[100:103]
	v_mfma_f32_16x16x32_bf16 v[96:99], v[164:167], v[186:189], v[96:99]
	v_mfma_f32_16x16x32_bf16 v[84:87], v[144:147], v[202:205], v[84:87]
	v_mfma_f32_16x16x32_bf16 v[80:83], v[164:167], v[202:205], v[80:83]
	v_mfma_f32_16x16x32_bf16 v[68:71], v[144:147], v[210:213], v[68:71]
	v_mfma_f32_16x16x32_bf16 v[64:67], v[164:167], v[210:213], v[64:67]
	v_mfma_f32_16x16x32_bf16 v[116:119], v[148:151], v[182:185], v[116:119]
	v_mfma_f32_16x16x32_bf16 v[112:115], v[174:177], v[182:185], v[112:115]
	v_mfma_f32_16x16x32_bf16 v[100:103], v[148:151], v[194:197], v[100:103]
	v_mfma_f32_16x16x32_bf16 v[96:99], v[174:177], v[194:197], v[96:99]
	v_mfma_f32_16x16x32_bf16 v[84:87], v[148:151], v[206:209], v[84:87]
	v_mfma_f32_16x16x32_bf16 v[80:83], v[174:177], v[206:209], v[80:83]
	v_mfma_f32_16x16x32_bf16 v[68:71], v[148:151], v[214:217], v[68:71]
	v_mfma_f32_16x16x32_bf16 v[64:67], v[174:177], v[214:217], v[64:67]
	s_setprio 0
	s_barrier
	s_add_i32 s18, s24, s43
	v_lshl_add_u64 v[168:169], v[168:169], 0, s[16:17]
	s_mov_b32 m0, s18
	s_nop 0
	global_load_lds_dwordx4 v[168:169], off
	s_add_i32 m0, s18, 0x2000
	s_add_u32 s18, s36, 0x160080
	v_lshl_add_u64 v[168:169], v[190:191], 0, s[16:17]
	s_addc_u32 s19, s37, 0
	s_add_i32 s24, s25, s43
	global_load_lds_dwordx4 v[168:169], off
	s_mov_b32 m0, s24
	v_lshl_add_u64 v[168:169], s[18:19], 0, v[156:157]
	global_load_lds_dwordx4 v[168:169], off
	s_add_i32 m0, s24, 0x2000
	v_lshl_add_u64 v[168:169], s[18:19], 0, v[152:153]
	global_load_lds_dwordx4 v[168:169], off
	s_mov_b32 m0, s51
	v_lshl_add_u64 v[168:169], v[218:219], 0, s[16:17]
	global_load_lds_dwordx4 v[168:169], off
	s_mov_b32 m0, s52
	v_lshl_add_u64 v[168:169], v[220:221], 0, s[16:17]
	global_load_lds_dwordx4 v[168:169], off
	ds_read_b128 v[178:181], v173 offset:49152
	ds_read_b128 v[182:185], v173 offset:50176
	ds_read_b128 v[186:189], v173 offset:51200
	ds_read_b128 v[194:197], v173 offset:52224
	ds_read_b128 v[202:205], v173 offset:53248
	ds_read_b128 v[206:209], v173 offset:54272
	ds_read_b128 v[210:213], v173 offset:55296
	ds_read_b128 v[214:217], v173 offset:56320
	s_waitcnt vmcnt(8)
	s_waitcnt lgkmcnt(0)
	s_barrier
; #define PG8_STAGE(bufoff, gbase, voff) do { _Pragma("unroll") for (int _i = 0; _i < 2; ++_i) \
;         __builtin_amdgcn_global_load_lds((const unsigned*)((const char*)(gbase) + (voff)[_i]), (PG8_LAS unsigned*)(lds + (bufoff) + ldsw + _i * 8192), 16, 0, 0); } while (0)
; #define PG8_LDA(dst, b, h) do { _Pragma("unroll") for (int m = 0; m < 4; ++m) _Pragma("unroll") for (int k = 0; k < 2; ++k) dst[m][k] = *(const PG8_LAS bf16x8*)(lds + PG8_SA(b, h) + aoff + m * 2048 + k * 1024); } while (0)
; #define PG8_LDB(dst, b, h) do { _Pragma("unroll") for (int n = 0; n < 2; ++n) _Pragma("unroll") for (int k = 0; k < 2; ++k) dst[n][k] = *(const PG8_LAS bf16x8*)(lds + PG8_SB(b, h) + boff + n * 2048 + k * 1024); } while (0)
; #define PG8_MMA(ai, bj, At, Bt) do { __builtin_amdgcn_s_setprio(1); _Pragma("unroll") for (int m = 0; m < 4; ++m) _Pragma("unroll") for (int n = 0; n < 2; ++n) _Pragma("unroll") for (int k = 0; k < 2; ++k) \
;         acc[ai][bj][m][n] = __builtin_amdgcn_mfma_f32_16x16x32_bf16(Bt[n][k], At[m][k], acc[ai][bj][m][n], 0, 0, 0); __builtin_amdgcn_s_setprio(0); } while (0)
; #define PG8_WAIT_V(n) asm volatile("s_waitcnt vmcnt(" #n ")" ::: "memory")
; template <class Epi, class Sched, bool ALIGN_EPI = false, bool SP2 = false>
; __device__ __forceinline__ void gemm_phase(PG8_LAS unsigned char* lds, const Gemm g, const Sched& S, const Epi& E) {
;     ...
;             PG8_LDB(B0, 0, 0); PG8_LDB(B1, 0, 1); PG8_SCHED; PG8_LDA(At, 0, 0); PG8_STAGE(PG8_SA(1, 1), a1 + hstep, voffA);
;             PG8_WAIT_V(8); PG8_WAIT_L(0); PG8_BAR; PG8_MMA(0, 0, At, B0); PG8_MMA(0, 1, At, B1); PG8_BAR; PG8_SCHED;
;             PG8_LDA(At, 0, 1); PG8_STAGE(PG8_SB(0, 0), b2, voffB); PG8_STAGE(PG8_SB(0, 1), b2 + hstep, voffB); PG8_STAGE(PG8_SA(0, 0), a2, voffA);
;             PG8_WAIT_V(8); PG8_WAIT_L(0); PG8_BAR; PG8_MMA(1, 0, At, B0); PG8_MMA(1, 1, At, B1); PG8_BAR; PG8_SCHED;
;             PG8_LDB(B0, 1, 0); PG8_LDB(B1, 1, 1); PG8_SCHED; PG8_LDA(At, 1, 0); PG8_STAGE(PG8_SA(0, 1), a2 + hstep, voffA);
;             PG8_WAIT_V(8); PG8_WAIT_L(0); PG8_BAR; PG8_MMA(0, 0, At, B0); PG8_MMA(0, 1, At, B1); PG8_BAR; PG8_SCHED;
;             PG8_LDA(At, 1, 1); PG8_STAGE(PG8_SB(1, 0), b3, voffB); PG8_STAGE(PG8_SB(1, 1), b3 + hstep, voffB); PG8_STAGE(PG8_SA(1, 0), a3, voffA);
;             PG8_WAIT_V(8); PG8_WAIT_L(0); PG8_BAR; PG8_MMA(1, 0, At, B0); PG8_MMA(1, 1, At, B1); PG8_BAR; PG8_SCHED;
	s_setprio 1
	s_waitcnt lgkmcnt(0)
	v_mfma_f32_16x16x32_bf16 v[60:63], v[128:131], v[178:181], v[60:63]
	v_mfma_f32_16x16x32_bf16 v[56:59], v[136:139], v[178:181], v[56:59]
	v_mfma_f32_16x16x32_bf16 v[44:47], v[128:131], v[186:189], v[44:47]
	v_mfma_f32_16x16x32_bf16 v[40:43], v[136:139], v[186:189], v[40:43]
	v_mfma_f32_16x16x32_bf16 v[28:31], v[128:131], v[202:205], v[28:31]
	v_mfma_f32_16x16x32_bf16 v[24:27], v[136:139], v[202:205], v[24:27]
	v_mfma_f32_16x16x32_bf16 v[12:15], v[128:131], v[210:213], v[12:15]
	v_mfma_f32_16x16x32_bf16 v[8:11], v[136:139], v[210:213], v[8:11]
	v_mfma_f32_16x16x32_bf16 v[60:63], v[132:135], v[182:185], v[60:63]
	v_mfma_f32_16x16x32_bf16 v[56:59], v[140:143], v[182:185], v[56:59]
	v_mfma_f32_16x16x32_bf16 v[44:47], v[132:135], v[194:197], v[44:47]
	v_mfma_f32_16x16x32_bf16 v[40:43], v[140:143], v[194:197], v[40:43]
	v_mfma_f32_16x16x32_bf16 v[28:31], v[132:135], v[206:209], v[28:31]
	v_mfma_f32_16x16x32_bf16 v[24:27], v[140:143], v[206:209], v[24:27]
	v_mfma_f32_16x16x32_bf16 v[12:15], v[132:135], v[214:217], v[12:15]
	v_mfma_f32_16x16x32_bf16 v[8:11], v[140:143], v[214:217], v[8:11]
	s_setprio 0
	s_setprio 1
	v_mfma_f32_16x16x32_bf16 v[52:55], v[144:147], v[178:181], v[52:55]
	v_mfma_f32_16x16x32_bf16 v[48:51], v[164:167], v[178:181], v[48:51]
	v_mfma_f32_16x16x32_bf16 v[36:39], v[144:147], v[186:189], v[36:39]
	v_mfma_f32_16x16x32_bf16 v[32:35], v[164:167], v[186:189], v[32:35]
	v_mfma_f32_16x16x32_bf16 v[20:23], v[144:147], v[202:205], v[20:23]
	v_mfma_f32_16x16x32_bf16 v[16:19], v[164:167], v[202:205], v[16:19]
	v_mfma_f32_16x16x32_bf16 v[4:7], v[144:147], v[210:213], v[4:7]
	v_mfma_f32_16x16x32_bf16 v[0:3], v[164:167], v[210:213], v[0:3]
	v_mfma_f32_16x16x32_bf16 v[52:55], v[148:151], v[182:185], v[52:55]
	v_mfma_f32_16x16x32_bf16 v[48:51], v[174:177], v[182:185], v[48:51]
	v_mfma_f32_16x16x32_bf16 v[36:39], v[148:151], v[194:197], v[36:39]
	v_mfma_f32_16x16x32_bf16 v[32:35], v[174:177], v[194:197], v[32:35]
	v_mfma_f32_16x16x32_bf16 v[20:23], v[148:151], v[206:209], v[20:23]
	v_mfma_f32_16x16x32_bf16 v[16:19], v[174:177], v[206:209], v[16:19]
	v_mfma_f32_16x16x32_bf16 v[4:7], v[148:151], v[214:217], v[4:7]
	v_mfma_f32_16x16x32_bf16 v[0:3], v[174:177], v[214:217], v[0:3]
	s_setprio 0
	s_barrier
	s_add_i32 s61, s61, 2
	s_add_u32 s59, s59, 0x100
	s_addc_u32 s60, s60, 0
	s_cmpk_gt_u32 s61, 0x55
	s_mov_b64 s[18:19], s[30:31]
	s_branch .LBB0_817
.LBB0_817:
	v_add_u32_e32 v140, 0x10000, v172
	v_add_u32_e32 v168, 0x14000, v172
	ds_read_b128 v[128:131], v140
	ds_read_b128 v[132:135], v140 offset:1024
	ds_read_b128 v[136:139], v140 offset:2048
	ds_read_b128 v[140:143], v140 offset:3072
	ds_read_b128 v[144:147], v168
	ds_read_b128 v[148:151], v168 offset:1024
	ds_read_b128 v[164:167], v168 offset:2048
	ds_read_b128 v[174:177], v168 offset:3072
	v_lshl_add_u64 v[168:169], s[18:19], 0, v[160:161]
	s_add_i32 m0, s2, 0xc000
	ds_read_b128 v[178:181], v173
	ds_read_b128 v[182:185], v173 offset:1024
	ds_read_b128 v[186:189], v173 offset:2048
	ds_read_b128 v[194:197], v173 offset:3072
	ds_read_b128 v[202:205], v173 offset:4096
	ds_read_b128 v[206:209], v173 offset:5120
	ds_read_b128 v[210:213], v173 offset:6144
	ds_read_b128 v[214:217], v173 offset:7168
	global_load_lds_dwordx4 v[168:169], off
	s_add_i32 m0, s2, 0xe000
	v_lshl_add_u64 v[168:169], s[18:19], 0, v[162:163]
	global_load_lds_dwordx4 v[168:169], off
	s_add_u32 s30, s18, 0x100
	s_addc_u32 s31, s19, 0
	s_add_i32 s24, 0, 0x10000
	s_cmpk_eq_i32 s61, 0x54
	s_cselect_b32 s39, s5, s31
	s_cselect_b32 s38, s4, s30
	s_cselect_b32 s37, s15, s60
	s_cselect_b32 s36, s14, s59
	s_add_i32 s25, 0, 0x14000
	s_waitcnt vmcnt(8)
	s_waitcnt lgkmcnt(0)
	s_barrier
	s_setprio 1
	s_waitcnt lgkmcnt(0)
	v_mfma_f32_16x16x32_bf16 v[124:127], v[128:131], v[178:181], v[124:127]
	v_mfma_f32_16x16x32_bf16 v[120:123], v[136:139], v[178:181], v[120:123]
	v_mfma_f32_16x16x32_bf16 v[108:111], v[128:131], v[186:189], v[108:111]
	v_mfma_f32_16x16x32_bf16 v[104:107], v[136:139], v[186:189], v[104:107]
	v_mfma_f32_16x16x32_bf16 v[92:95], v[128:131], v[202:205], v[92:95]
	v_mfma_f32_16x16x32_bf16 v[88:91], v[136:139], v[202:205], v[88:91]
	v_mfma_f32_16x16x32_bf16 v[76:79], v[128:131], v[210:213], v[76:79]
	v_mfma_f32_16x16x32_bf16 v[72:75], v[136:139], v[210:213], v[72:75]
	v_mfma_f32_16x16x32_bf16 v[124:127], v[132:135], v[182:185], v[124:127]
	v_mfma_f32_16x16x32_bf16 v[120:123], v[140:143], v[182:185], v[120:123]
	v_mfma_f32_16x16x32_bf16 v[108:111], v[132:135], v[194:197], v[108:111]
	v_mfma_f32_16x16x32_bf16 v[104:107], v[140:143], v[194:197], v[104:107]
	v_mfma_f32_16x16x32_bf16 v[92:95], v[132:135], v[206:209], v[92:95]
	v_mfma_f32_16x16x32_bf16 v[88:91], v[140:143], v[206:209], v[88:91]
	v_mfma_f32_16x16x32_bf16 v[76:79], v[132:135], v[214:217], v[76:79]
	v_mfma_f32_16x16x32_bf16 v[72:75], v[140:143], v[214:217], v[72:75]
	s_setprio 0
	s_setprio 1
	v_mfma_f32_16x16x32_bf16 v[116:119], v[144:147], v[178:181], v[116:119]
	v_mfma_f32_16x16x32_bf16 v[112:115], v[164:167], v[178:181], v[112:115]
	v_mfma_f32_16x16x32_bf16 v[100:103], v[144:147], v[186:189], v[100:103]
	v_mfma_f32_16x16x32_bf16 v[96:99], v[164:167], v[186:189], v[96:99]
	v_mfma_f32_16x16x32_bf16 v[84:87], v[144:147], v[202:205], v[84:87]
	v_mfma_f32_16x16x32_bf16 v[80:83], v[164:167], v[202:205], v[80:83]
	v_mfma_f32_16x16x32_bf16 v[68:71], v[144:147], v[210:213], v[68:71]
	v_mfma_f32_16x16x32_bf16 v[64:67], v[164:167], v[210:213], v[64:67]
	v_mfma_f32_16x16x32_bf16 v[116:119], v[148:151], v[182:185], v[116:119]
	v_mfma_f32_16x16x32_bf16 v[112:115], v[174:177], v[182:185], v[112:115]
	v_mfma_f32_16x16x32_bf16 v[100:103], v[148:151], v[194:197], v[100:103]
	v_mfma_f32_16x16x32_bf16 v[96:99], v[174:177], v[194:197], v[96:99]
	v_mfma_f32_16x16x32_bf16 v[84:87], v[148:151], v[206:209], v[84:87]
	v_mfma_f32_16x16x32_bf16 v[80:83], v[174:177], v[206:209], v[80:83]
	v_mfma_f32_16x16x32_bf16 v[68:71], v[148:151], v[214:217], v[68:71]
	v_mfma_f32_16x16x32_bf16 v[64:67], v[174:177], v[214:217], v[64:67]
	s_setprio 0
	s_barrier
; #define PG8_STAGE(bufoff, gbase, voff) do { _Pragma("unroll") for (int _i = 0; _i < 2; ++_i) \
;         __builtin_amdgcn_global_load_lds((const unsigned*)((const char*)(gbase) + (voff)[_i]), (PG8_LAS unsigned*)(lds + (bufoff) + ldsw + _i * 8192), 16, 0, 0); } while (0)
; #define PG8_LDA(dst, b, h) do { _Pragma("unroll") for (int m = 0; m < 4; ++m) _Pragma("unroll") for (int k = 0; k < 2; ++k) dst[m][k] = *(const PG8_LAS bf16x8*)(lds + PG8_SA(b, h) + aoff + m * 2048 + k * 1024); } while (0)
; #define PG8_LDB(dst, b, h) do { _Pragma("unroll") for (int n = 0; n < 2; ++n) _Pragma("unroll") for (int k = 0; k < 2; ++k) dst[n][k] = *(const PG8_LAS bf16x8*)(lds + PG8_SB(b, h) + boff + n * 2048 + k * 1024); } while (0)
; #define PG8_MMA(ai, bj, At, Bt) do { __builtin_amdgcn_s_setprio(1); _Pragma("unroll") for (int m = 0; m < 4; ++m) _Pragma("unroll") for (int n = 0; n < 2; ++n) _Pragma("unroll") for (int k = 0; k < 2; ++k) \
;         acc[ai][bj][m][n] = __builtin_amdgcn_mfma_f32_16x16x32_bf16(Bt[n][k], At[m][k], acc[ai][bj][m][n], 0, 0, 0); __builtin_amdgcn_s_setprio(0); } while (0)
; #define PG8_WAIT_V(n) asm volatile("s_waitcnt vmcnt(" #n ")" ::: "memory")
; #define PG8_WAIT_L(n) asm volatile("s_waitcnt lgkmcnt(" #n ")" ::: "memory")
; #define PG8_BAR __builtin_amdgcn_s_barrier()
; #define PG8_SCHED __builtin_amdgcn_sched_barrier(0)
; template <class Epi, class Sched, bool ALIGN_EPI = false, bool SP2 = false>
; __device__ __forceinline__ void gemm_phase(PG8_LAS unsigned char* lds, const Gemm g, const Sched& S, const Epi& E) {
;     ...
;             PG8_WAIT_V(8); PG8_WAIT_L(0); PG8_BAR; PG8_MMA(0, 0, At, B0); PG8_MMA(0, 1, At, B1); PG8_BAR; PG8_SCHED;
;             PG8_LDA(At, 0, 1); PG8_STAGE(PG8_SB(0, 0), b2, voffB); PG8_STAGE(PG8_SB(0, 1), b2 + hstep, voffB); PG8_STAGE(PG8_SA(0, 0), a2, voffA);
;             PG8_WAIT_V(8); PG8_WAIT_L(0); PG8_BAR; PG8_MMA(1, 0, At, B0); PG8_MMA(1, 1, At, B1); PG8_BAR; PG8_SCHED;
;             PG8_LDB(B0, 1, 0); PG8_LDB(B1, 1, 1); PG8_SCHED; PG8_LDA(At, 1, 0); PG8_STAGE(PG8_SA(0, 1), a2 + hstep, voffA);
;             PG8_WAIT_V(8); PG8_WAIT_L(0); PG8_BAR; PG8_MMA(0, 0, At, B0); PG8_MMA(0, 1, At, B1); PG8_BAR; PG8_SCHED;
	s_add_i32 s18, s24, s43
	v_lshl_add_u64 v[168:169], s[36:37], 0, v[156:157]
	s_mov_b32 m0, s18
	s_nop 0
	global_load_lds_dwordx4 v[168:169], off
	s_add_i32 m0, s18, 0x2000
	s_add_u32 s18, s36, 0x160000
	v_lshl_add_u64 v[190:191], s[36:37], 0, v[152:153]
	s_addc_u32 s19, s37, 0
	s_add_i32 s24, s25, s43
	global_load_lds_dwordx4 v[190:191], off
	v_lshl_add_u64 v[218:219], s[18:19], 0, v[156:157]
	s_mov_b32 m0, s24
	v_lshl_add_u64 v[220:221], s[38:39], 0, v[154:155]
	global_load_lds_dwordx4 v[218:219], off
	s_add_i32 m0, s24, 0x2000
	v_lshl_add_u64 v[218:219], s[18:19], 0, v[152:153]
	global_load_lds_dwordx4 v[218:219], off
	s_mov_b32 m0, s2
	v_lshl_add_u64 v[218:219], s[38:39], 0, v[158:159]
	global_load_lds_dwordx4 v[218:219], off
	s_mov_b32 m0, s44
	s_nop 0
	global_load_lds_dwordx4 v[220:221], off
	ds_read_b128 v[178:181], v173 offset:16384
	ds_read_b128 v[182:185], v173 offset:17408
	ds_read_b128 v[186:189], v173 offset:18432
	ds_read_b128 v[194:197], v173 offset:19456
	ds_read_b128 v[202:205], v173 offset:20480
	ds_read_b128 v[206:209], v173 offset:21504
	ds_read_b128 v[210:213], v173 offset:22528
	ds_read_b128 v[214:217], v173 offset:23552
	s_waitcnt vmcnt(8)
	s_waitcnt lgkmcnt(0)
	s_barrier
	s_setprio 1
	s_waitcnt lgkmcnt(0)
	v_mfma_f32_16x16x32_bf16 v[60:63], v[128:131], v[178:181], v[60:63]
	v_mfma_f32_16x16x32_bf16 v[56:59], v[136:139], v[178:181], v[56:59]
	v_mfma_f32_16x16x32_bf16 v[44:47], v[128:131], v[186:189], v[44:47]
	v_mfma_f32_16x16x32_bf16 v[40:43], v[136:139], v[186:189], v[40:43]
	v_mfma_f32_16x16x32_bf16 v[28:31], v[128:131], v[202:205], v[28:31]
	v_mfma_f32_16x16x32_bf16 v[24:27], v[136:139], v[202:205], v[24:27]
	v_mfma_f32_16x16x32_bf16 v[12:15], v[128:131], v[210:213], v[12:15]
	v_mfma_f32_16x16x32_bf16 v[8:11], v[136:139], v[210:213], v[8:11]
	v_mfma_f32_16x16x32_bf16 v[60:63], v[132:135], v[182:185], v[60:63]
	v_mfma_f32_16x16x32_bf16 v[56:59], v[140:143], v[182:185], v[56:59]
	v_mfma_f32_16x16x32_bf16 v[44:47], v[132:135], v[194:197], v[44:47]
	v_mfma_f32_16x16x32_bf16 v[40:43], v[140:143], v[194:197], v[40:43]
	v_mfma_f32_16x16x32_bf16 v[28:31], v[132:135], v[206:209], v[28:31]
	v_mfma_f32_16x16x32_bf16 v[24:27], v[140:143], v[206:209], v[24:27]
	v_mfma_f32_16x16x32_bf16 v[12:15], v[132:135], v[214:217], v[12:15]
	v_mfma_f32_16x16x32_bf16 v[8:11], v[140:143], v[214:217], v[8:11]
	s_setprio 0
	s_setprio 1
	v_mfma_f32_16x16x32_bf16 v[52:55], v[144:147], v[178:181], v[52:55]
	v_mfma_f32_16x16x32_bf16 v[48:51], v[164:167], v[178:181], v[48:51]
	v_mfma_f32_16x16x32_bf16 v[36:39], v[144:147], v[186:189], v[36:39]
	v_mfma_f32_16x16x32_bf16 v[32:35], v[164:167], v[186:189], v[32:35]
	v_mfma_f32_16x16x32_bf16 v[20:23], v[144:147], v[202:205], v[20:23]
	v_mfma_f32_16x16x32_bf16 v[16:19], v[164:167], v[202:205], v[16:19]
	v_mfma_f32_16x16x32_bf16 v[4:7], v[144:147], v[210:213], v[4:7]
	v_mfma_f32_16x16x32_bf16 v[0:3], v[164:167], v[210:213], v[0:3]
	v_mfma_f32_16x16x32_bf16 v[52:55], v[148:151], v[182:185], v[52:55]
	v_mfma_f32_16x16x32_bf16 v[48:51], v[174:177], v[182:185], v[48:51]
	v_mfma_f32_16x16x32_bf16 v[36:39], v[148:151], v[194:197], v[36:39]
	v_mfma_f32_16x16x32_bf16 v[32:35], v[174:177], v[194:197], v[32:35]
	v_mfma_f32_16x16x32_bf16 v[20:23], v[148:151], v[206:209], v[20:23]
	v_mfma_f32_16x16x32_bf16 v[16:19], v[174:177], v[206:209], v[16:19]
	v_mfma_f32_16x16x32_bf16 v[4:7], v[148:151], v[214:217], v[4:7]
	v_mfma_f32_16x16x32_bf16 v[0:3], v[174:177], v[214:217], v[0:3]
	s_setprio 0
	s_barrier
	s_add_i32 s24, 0, 0x18000
	s_add_i32 s25, 0, 0x1c000
	s_add_u32 s18, s38, 0x160000
	s_addc_u32 s19, s39, 0
	s_mov_b32 m0, s45
	v_lshl_add_u64 v[230:231], s[18:19], 0, v[158:159]
	global_load_lds_dwordx4 v[230:231], off
	s_mov_b32 m0, s46
	v_lshl_add_u64 v[230:231], s[18:19], 0, v[154:155]
	global_load_lds_dwordx4 v[230:231], off
	v_add_u32_e32 v140, 0x18000, v172
	v_add_u32_e32 v174, 0x1c000, v172
	ds_read_b128 v[128:131], v140
	ds_read_b128 v[132:135], v140 offset:1024
	ds_read_b128 v[136:139], v140 offset:2048
	ds_read_b128 v[140:143], v140 offset:3072
	ds_read_b128 v[144:147], v174
	ds_read_b128 v[148:151], v174 offset:1024
	ds_read_b128 v[164:167], v174 offset:2048
	ds_read_b128 v[174:177], v174 offset:3072
	ds_read_b128 v[178:181], v173 offset:32768
	ds_read_b128 v[182:185], v173 offset:33792
	ds_read_b128 v[186:189], v173 offset:34816
	ds_read_b128 v[194:197], v173 offset:35840
	ds_read_b128 v[202:205], v173 offset:36864
	ds_read_b128 v[206:209], v173 offset:37888
	ds_read_b128 v[210:213], v173 offset:38912
	ds_read_b128 v[214:217], v173 offset:39936
	s_waitcnt vmcnt(8)
	s_waitcnt lgkmcnt(0)
	s_barrier
; #define PG8_STAGE(bufoff, gbase, voff) do { _Pragma("unroll") for (int _i = 0; _i < 2; ++_i) \
;         __builtin_amdgcn_global_load_lds((const unsigned*)((const char*)(gbase) + (voff)[_i]), (PG8_LAS unsigned*)(lds + (bufoff) + ldsw + _i * 8192), 16, 0, 0); } while (0)
; #define PG8_LDA(dst, b, h) do { _Pragma("unroll") for (int m = 0; m < 4; ++m) _Pragma("unroll") for (int k = 0; k < 2; ++k) dst[m][k] = *(const PG8_LAS bf16x8*)(lds + PG8_SA(b, h) + aoff + m * 2048 + k * 1024); } while (0)
; #define PG8_MMA(ai, bj, At, Bt) do { __builtin_amdgcn_s_setprio(1); _Pragma("unroll") for (int m = 0; m < 4; ++m) _Pragma("unroll") for (int n = 0; n < 2; ++n) _Pragma("unroll") for (int k = 0; k < 2; ++k) \
;         acc[ai][bj][m][n] = __builtin_amdgcn_mfma_f32_16x16x32_bf16(Bt[n][k], At[m][k], acc[ai][bj][m][n], 0, 0, 0); __builtin_amdgcn_s_setprio(0); } while (0)
; #define PG8_WAIT_V(n) asm volatile("s_waitcnt vmcnt(" #n ")" ::: "memory")
; #define PG8_WAIT_L(n) asm volatile("s_waitcnt lgkmcnt(" #n ")" ::: "memory")
; #define PG8_BAR __builtin_amdgcn_s_barrier()
; #define PG8_SCHED __builtin_amdgcn_sched_barrier(0)
; template <class Epi, class Sched, bool ALIGN_EPI = false, bool SP2 = false>
; __device__ __forceinline__ void gemm_phase(PG8_LAS unsigned char* lds, const Gemm g, const Sched& S, const Epi& E) {
;     ...
;         for (int t = 0; t < nt; t += 2) {
;     ...
;             PG8_WAIT_V(8); PG8_WAIT_L(0); PG8_BAR; PG8_MMA(0, 0, At, B0); PG8_MMA(0, 1, At, B1); PG8_BAR; PG8_SCHED;
;             PG8_LDA(At, 1, 1); PG8_STAGE(PG8_SB(1, 0), b3, voffB); PG8_STAGE(PG8_SB(1, 1), b3 + hstep, voffB); PG8_STAGE(PG8_SA(1, 0), a3, voffA);
;             PG8_WAIT_V(8); PG8_WAIT_L(0); PG8_BAR; PG8_MMA(1, 0, At, B0); PG8_MMA(1, 1, At, B1); PG8_BAR; PG8_SCHED;
	s_setprio 1
	s_waitcnt lgkmcnt(0)
	v_mfma_f32_16x16x32_bf16 v[124:127], v[128:131], v[178:181], v[124:127]
	v_mfma_f32_16x16x32_bf16 v[120:123], v[136:139], v[178:181], v[120:123]
	v_mfma_f32_16x16x32_bf16 v[108:111], v[128:131], v[186:189], v[108:111]
	v_mfma_f32_16x16x32_bf16 v[104:107], v[136:139], v[186:189], v[104:107]
	v_mfma_f32_16x16x32_bf16 v[92:95], v[128:131], v[202:205], v[92:95]
	v_mfma_f32_16x16x32_bf16 v[88:91], v[136:139], v[202:205], v[88:91]
	v_mfma_f32_16x16x32_bf16 v[76:79], v[128:131], v[210:213], v[76:79]
	v_mfma_f32_16x16x32_bf16 v[72:75], v[136:139], v[210:213], v[72:75]
	v_mfma_f32_16x16x32_bf16 v[124:127], v[132:135], v[182:185], v[124:127]
	v_mfma_f32_16x16x32_bf16 v[120:123], v[140:143], v[182:185], v[120:123]
	v_mfma_f32_16x16x32_bf16 v[108:111], v[132:135], v[194:197], v[108:111]
	v_mfma_f32_16x16x32_bf16 v[104:107], v[140:143], v[194:197], v[104:107]
	v_mfma_f32_16x16x32_bf16 v[92:95], v[132:135], v[206:209], v[92:95]
	v_mfma_f32_16x16x32_bf16 v[88:91], v[140:143], v[206:209], v[88:91]
	v_mfma_f32_16x16x32_bf16 v[76:79], v[132:135], v[214:217], v[76:79]
	v_mfma_f32_16x16x32_bf16 v[72:75], v[140:143], v[214:217], v[72:75]
	s_setprio 0
	s_setprio 1
	v_mfma_f32_16x16x32_bf16 v[116:119], v[144:147], v[178:181], v[116:119]
	v_mfma_f32_16x16x32_bf16 v[112:115], v[164:167], v[178:181], v[112:115]
	v_mfma_f32_16x16x32_bf16 v[100:103], v[144:147], v[186:189], v[100:103]
	v_mfma_f32_16x16x32_bf16 v[96:99], v[164:167], v[186:189], v[96:99]
	v_mfma_f32_16x16x32_bf16 v[84:87], v[144:147], v[202:205], v[84:87]
	v_mfma_f32_16x16x32_bf16 v[80:83], v[164:167], v[202:205], v[80:83]
	v_mfma_f32_16x16x32_bf16 v[68:71], v[144:147], v[210:213], v[68:71]
	v_mfma_f32_16x16x32_bf16 v[64:67], v[164:167], v[210:213], v[64:67]
	v_mfma_f32_16x16x32_bf16 v[116:119], v[148:151], v[182:185], v[116:119]
	v_mfma_f32_16x16x32_bf16 v[112:115], v[174:177], v[182:185], v[112:115]
	v_mfma_f32_16x16x32_bf16 v[100:103], v[148:151], v[194:197], v[100:103]
	v_mfma_f32_16x16x32_bf16 v[96:99], v[174:177], v[194:197], v[96:99]
	v_mfma_f32_16x16x32_bf16 v[84:87], v[148:151], v[206:209], v[84:87]
	v_mfma_f32_16x16x32_bf16 v[80:83], v[174:177], v[206:209], v[80:83]
	v_mfma_f32_16x16x32_bf16 v[68:71], v[148:151], v[214:217], v[68:71]
	v_mfma_f32_16x16x32_bf16 v[64:67], v[174:177], v[214:217], v[64:67]
	s_setprio 0
	s_barrier
	s_add_i32 s18, s24, s43
	v_lshl_add_u64 v[168:169], v[168:169], 0, s[16:17]
	s_mov_b32 m0, s18
	s_nop 0
	global_load_lds_dwordx4 v[168:169], off
	s_add_i32 m0, s18, 0x2000
	s_add_u32 s18, s36, 0x160080
	v_lshl_add_u64 v[168:169], v[190:191], 0, s[16:17]
	s_addc_u32 s19, s37, 0
	s_add_i32 s24, s25, s43
	global_load_lds_dwordx4 v[168:169], off
	s_mov_b32 m0, s24
	v_lshl_add_u64 v[168:169], s[18:19], 0, v[156:157]
	global_load_lds_dwordx4 v[168:169], off
	s_add_i32 m0, s24, 0x2000
	v_lshl_add_u64 v[168:169], s[18:19], 0, v[152:153]
	global_load_lds_dwordx4 v[168:169], off
	s_mov_b32 m0, s51
	v_lshl_add_u64 v[168:169], v[218:219], 0, s[16:17]
	global_load_lds_dwordx4 v[168:169], off
	s_mov_b32 m0, s52
	v_lshl_add_u64 v[168:169], v[220:221], 0, s[16:17]
	global_load_lds_dwordx4 v[168:169], off
	ds_read_b128 v[178:181], v173 offset:49152
	ds_read_b128 v[182:185], v173 offset:50176
	ds_read_b128 v[186:189], v173 offset:51200
	ds_read_b128 v[194:197], v173 offset:52224
	ds_read_b128 v[202:205], v173 offset:53248
	ds_read_b128 v[206:209], v173 offset:54272
	ds_read_b128 v[210:213], v173 offset:55296
	ds_read_b128 v[214:217], v173 offset:56320
	s_waitcnt vmcnt(8)
	s_waitcnt lgkmcnt(0)
	s_barrier
	s_setprio 1
	s_waitcnt lgkmcnt(0)
	v_mfma_f32_16x16x32_bf16 v[60:63], v[128:131], v[178:181], v[60:63]
	v_mfma_f32_16x16x32_bf16 v[56:59], v[136:139], v[178:181], v[56:59]
	v_mfma_f32_16x16x32_bf16 v[44:47], v[128:131], v[186:189], v[44:47]
	v_mfma_f32_16x16x32_bf16 v[40:43], v[136:139], v[186:189], v[40:43]
	v_mfma_f32_16x16x32_bf16 v[28:31], v[128:131], v[202:205], v[28:31]
	v_mfma_f32_16x16x32_bf16 v[24:27], v[136:139], v[202:205], v[24:27]
	v_mfma_f32_16x16x32_bf16 v[12:15], v[128:131], v[210:213], v[12:15]
	v_mfma_f32_16x16x32_bf16 v[8:11], v[136:139], v[210:213], v[8:11]
	v_mfma_f32_16x16x32_bf16 v[60:63], v[132:135], v[182:185], v[60:63]
	v_mfma_f32_16x16x32_bf16 v[56:59], v[140:143], v[182:185], v[56:59]
	v_mfma_f32_16x16x32_bf16 v[44:47], v[132:135], v[194:197], v[44:47]
	v_mfma_f32_16x16x32_bf16 v[40:43], v[140:143], v[194:197], v[40:43]
	v_mfma_f32_16x16x32_bf16 v[28:31], v[132:135], v[206:209], v[28:31]
	v_mfma_f32_16x16x32_bf16 v[24:27], v[140:143], v[206:209], v[24:27]
	v_mfma_f32_16x16x32_bf16 v[12:15], v[132:135], v[214:217], v[12:15]
	v_mfma_f32_16x16x32_bf16 v[8:11], v[140:143], v[214:217], v[8:11]
	s_setprio 0
	s_setprio 1
	v_mfma_f32_16x16x32_bf16 v[52:55], v[144:147], v[178:181], v[52:55]
	v_mfma_f32_16x16x32_bf16 v[48:51], v[164:167], v[178:181], v[48:51]
	v_mfma_f32_16x16x32_bf16 v[36:39], v[144:147], v[186:189], v[36:39]
	v_mfma_f32_16x16x32_bf16 v[32:35], v[164:167], v[186:189], v[32:35]
	v_mfma_f32_16x16x32_bf16 v[20:23], v[144:147], v[202:205], v[20:23]
	v_mfma_f32_16x16x32_bf16 v[16:19], v[164:167], v[202:205], v[16:19]
	v_mfma_f32_16x16x32_bf16 v[4:7], v[144:147], v[210:213], v[4:7]
	v_mfma_f32_16x16x32_bf16 v[0:3], v[164:167], v[210:213], v[0:3]
	v_mfma_f32_16x16x32_bf16 v[52:55], v[148:151], v[182:185], v[52:55]
	v_mfma_f32_16x16x32_bf16 v[48:51], v[174:177], v[182:185], v[48:51]
	v_mfma_f32_16x16x32_bf16 v[36:39], v[148:151], v[194:197], v[36:39]
	v_mfma_f32_16x16x32_bf16 v[32:35], v[174:177], v[194:197], v[32:35]
	v_mfma_f32_16x16x32_bf16 v[20:23], v[148:151], v[206:209], v[20:23]
	v_mfma_f32_16x16x32_bf16 v[16:19], v[174:177], v[206:209], v[16:19]
	v_mfma_f32_16x16x32_bf16 v[4:7], v[148:151], v[214:217], v[4:7]
	v_mfma_f32_16x16x32_bf16 v[0:3], v[174:177], v[214:217], v[0:3]
	s_setprio 0
	s_barrier
	s_add_i32 s61, s61, 2
	s_add_u32 s59, s59, 0x100
	s_addc_u32 s60, s60, 0
	s_cmpk_gt_u32 s61, 0x55
	s_mov_b64 s[18:19], s[30:31]
	s_cbranch_scc0 .LBB0_817
	s_and_b64 vcc, exec, s[12:13]
	s_cbranch_vccz .LBB0_820
	s_barrier
